# row-sum add chains split three ways (ACC, RES, RES+1) where a second temp register is free; else two-way; adds GQA second-half chain
# speedup vs baseline: 1.0079x; 1.0012x over previous
; __device__ __forceinline__ void finishSM(f32x16& p0, f32x16& p1, float& l_reg, bf16x8& pa0, bf16x8& pa1, bf16x8& pa2, bf16x8& pa3) {
; #pragma unroll
;   for (int r = 0; r < 16; ++r) p1[r] = __builtin_amdgcn_exp2f(p1[r]);
;   float ps = 0;
; #pragma unroll
;   for (int r = 0; r < 16; ++r) ps += p0[r];
; #pragma unroll
;   for (int r = 0; r < 16; ++r) ps += p1[r];
;   { auto rr = __builtin_amdgcn_permlane32_swap(__float_as_uint(ps), __float_as_uint(ps), false, false);
;     ps = __uint_as_float(rr[0]) + __uint_as_float(rr[1]); }
;   l_reg += ps;
;     ...
;   PK4(p0, 0, pa0); PK4(p0, 8, pa1); PK4(p1, 0, pa2); PK4(p1, 8, pa3);
;     ...
; }
; template <int DQK, int QL>
; __device__ __forceinline__ void qkt(f32x16& p0, f32x16& p1, const char* Ks, const bf16x8 (&qr)[DQK / 16 - QL], const char* qlds, const int (&kofs)[4], float negM) {
;   constexpr int QR = DQK / 16 - QL;
; #pragma unroll
;   for (int r = 0; r < 16; ++r) { p0[r] = negM; p1[r] = negM; }
; #pragma unroll
;   for (int d0 = 0; d0 < DQK / 16; ++d0) {
;     const char* kp = Ks + kofs[d0 & 3] + (d0 >> 2) * 128;
;     bf16x8 b0 = *reinterpret_cast<const bf16x8*>(kp);
;     bf16x8 b1 = *reinterpret_cast<const bf16x8*>(kp + 32 * DQK * 2);
;     bf16x8 qf;
;     if constexpr (QL > 0) { if (d0 < QR) qf = qr[d0 < QR ? d0 : 0]; else qf = *reinterpret_cast<const bf16x8*>(qlds + (d0 - QR) * 1024); }
;     else qf = qr[d0];
;     p0 = __builtin_amdgcn_mfma_f32_32x32x16_bf16(b0, qf, p0, 0, 0, 0);
;     p1 = __builtin_amdgcn_mfma_f32_32x32x16_bf16(b1, qf, p1, 0, 0, 0);
;   }
; }
; template <int NCB> __device__ __forceinline__ int v_st(int k, int c) {
;   const int kk = (k & ~0xC) | ((k & 4) << 1) | ((k & 8) >> 1);
;   return ((kk >> 3) * NCB + (c >> 5)) * 512 + ((kk & 7) * 32 + (c & 31)) * 2;
; }
; __device__ __forceinline__ int v_rd_base(int lane) { return ((lane & 3) << 3) | (((lane >> 2) & 3) << 6) | (((lane >> 4) & 1) << 5) | (((lane >> 5) & 1) << 8); }
; template <int OFF> __device__ __forceinline__ s16x4 tr_read(int vb) {
;   s16x4 r; asm volatile("ds_read_b64_tr_b16 %0, %1 offset:%2" : "=&v"(r) : "v"(vb), "i"(OFF) : "memory"); return r;
; }
; template <int NCB, int D0> __device__ __forceinline__ void pv_one(f32x16& od, int vb, bf16x8 pa0, bf16x8 pa1, bf16x8 pa2, bf16x8 pa3) {
;   constexpr int KSTEP = NCB * 1024, HALF = NCB * 512, B0 = D0 * 512;
.LBB0_323:
	ds_read_b128 v[96:99], v174 offset:40960
	ds_read_b128 v[182:185], v174 offset:45056
	v_exp_f32_e32 v100, v68
	v_exp_f32_e32 v101, v69
	s_waitcnt lgkmcnt(1)
	v_mfma_f32_32x32x16_bf16 v[80:95], v[96:99], v[142:145], v[238:253]
	ds_read_b128 v[96:99], v175 offset:40960
	ds_read_b128 v[186:189], v175 offset:45056
	v_exp_f32_e32 v102, v70
	v_exp_f32_e32 v103, v71
	v_exp_f32_e32 v104, v72
	v_exp_f32_e32 v105, v73
	v_exp_f32_e32 v106, v74
	v_exp_f32_e32 v107, v75
	s_waitcnt lgkmcnt(1)
	v_mfma_f32_32x32x16_bf16 v[80:95], v[96:99], v[138:141], v[80:95]
	ds_read_b128 v[96:99], v173 offset:40960
	ds_read_b128 v[190:193], v173 offset:45056
	v_exp_f32_e32 v108, v76
	v_exp_f32_e32 v109, v77
	v_exp_f32_e32 v110, v78
	v_exp_f32_e32 v79, v79
	s_waitcnt lgkmcnt(1)
	v_mfma_f32_32x32x16_bf16 v[80:95], v[96:99], v[134:137], v[80:95]
	ds_read_b128 v[96:99], v176 offset:40960
	ds_read_b128 v[194:197], v176 offset:45056
	s_waitcnt lgkmcnt(1)
	v_mfma_f32_32x32x16_bf16 v[80:95], v[96:99], v[130:133], v[80:95]
	v_exp_f32_e32 v96, v64
	v_add_f32_e32 v64, 0, v165
	v_add_f32_e32 v64, v166, v64
	v_add_f32_e32 v180, v167, v155
	v_add_f32_e32 v181, v157, v164
	v_add_f32_e32 v64, v154, v64
	v_add_f32_e32 v180, v156, v180
	v_add_f32_e32 v181, v151, v181
	v_add_f32_e32 v64, v153, v64
	v_add_f32_e32 v180, v149, v180
	v_add_f32_e32 v181, v152, v181
	v_add_f32_e32 v64, v147, v64
	v_exp_f32_e32 v97, v65
	v_add_f32_e32 v180, v150, v180
	v_exp_f32_e32 v98, v66
	v_add_f32_e32 v181, v146, v181
	v_exp_f32_e32 v99, v67
	v_add_f32_e32 v64, v148, v64
	v_add_f32_e32 v180, v96, v180
	v_add_f32_e32 v181, v97, v181
	v_add_f32_e32 v64, v98, v64
	v_add_f32_e32 v180, v99, v180
	v_add_f32_e32 v181, v100, v181
	v_add_f32_e32 v64, v101, v64
	v_add_f32_e32 v180, v102, v180
	v_add_f32_e32 v181, v103, v181
	v_add_f32_e32 v64, v104, v64
	v_add_f32_e32 v180, v105, v180
	v_add_f32_e32 v181, v106, v181
	v_add_f32_e32 v64, v107, v64
	v_add_f32_e32 v180, v108, v180
	v_add_f32_e32 v181, v109, v181
	v_add_f32_e32 v64, v110, v64
	v_add_f32_e32 v180, v79, v180
	v_add_f32_e32 v180, v64, v180
	v_add_f32_e32 v180, v181, v180
	v_mov_b32_e32 v181, v180
	s_nop 1
	v_permlane32_swap_b32_e32 v180, v181
	v_cvt_pk_bf16_f32 v64, v165, v167
	v_cvt_pk_bf16_f32 v65, v157, v166
	v_cvt_pk_bf16_f32 v66, v155, v164
	v_cvt_pk_bf16_f32 v67, v154, v156
	v_cvt_pk_bf16_f32 v68, v151, v153
	v_cvt_pk_bf16_f32 v69, v149, v152
	v_cvt_pk_bf16_f32 v70, v147, v150
	v_cvt_pk_bf16_f32 v71, v146, v148
	v_cvt_pk_bf16_f32 v72, v96, v97
	v_cvt_pk_bf16_f32 v73, v98, v99
	v_cvt_pk_bf16_f32 v74, v100, v101
	v_cvt_pk_bf16_f32 v75, v102, v103
	v_cvt_pk_bf16_f32 v76, v104, v105
	v_cvt_pk_bf16_f32 v77, v106, v107
	v_cvt_pk_bf16_f32 v78, v108, v109
	v_cvt_pk_bf16_f32 v79, v110, v79
	s_nop 0
	v_permlane32_swap_b32_e32 v64, v66
	v_permlane32_swap_b32_e32 v65, v67
	v_permlane32_swap_b32_e32 v68, v70
	v_permlane32_swap_b32_e32 v69, v71
	v_permlane32_swap_b32_e32 v72, v74
	v_permlane32_swap_b32_e32 v73, v75
	v_permlane32_swap_b32_e32 v76, v78
	v_permlane32_swap_b32_e32 v77, v79
	v_mfma_f32_32x32x16_bf16 v[96:111], v[182:185], v[142:145], v[238:253]
	v_mfma_f32_32x32x16_bf16 v[96:111], v[186:189], v[138:141], v[96:111]
	s_add_u32 s100, s80, 0x590c000
	s_addc_u32 s101, s81, 0
	global_load_dwordx4 v[146:149], v158, s[100:101] offset:1280
	global_load_dwordx4 v[150:153], v160, s[100:101] offset:2304
	v_mfma_f32_32x32x16_bf16 v[96:111], v[190:193], v[134:137], v[96:111]
	global_load_dwordx4 v[154:157], v162, s[100:101] offset:2304
	s_waitcnt lgkmcnt(0)
	v_mfma_f32_32x32x16_bf16 v[96:111], v[194:197], v[130:133], v[96:111]
	ds_read_b64_tr_b16 v[112:113], v172 offset:0
	ds_read_b64_tr_b16 v[114:115], v172 offset:0x800
	ds_read_b64_tr_b16 v[116:117], v172 offset:0x1000
	ds_read_b64_tr_b16 v[118:119], v172 offset:0x1800
	ds_read_b64_tr_b16 v[120:121], v172 offset:0x2000
	ds_read_b64_tr_b16 v[122:123], v172 offset:0x2800
	ds_read_b64_tr_b16 v[124:125], v172 offset:0x3000
	ds_read_b64_tr_b16 v[126:127], v172 offset:0x3800
	s_nop 0
	s_waitcnt lgkmcnt(6)
	v_mfma_f32_32x32x16_bf16 v[0:15], v[64:67], v[112:115], v[0:15]
	ds_read_b64_tr_b16 v[112:113], v172 offset:0x200
	ds_read_b64_tr_b16 v[114:115], v172 offset:0xa00
	s_waitcnt lgkmcnt(6)
	v_mfma_f32_32x32x16_bf16 v[0:15], v[68:71], v[116:119], v[0:15]
	ds_read_b64_tr_b16 v[116:117], v172 offset:0x1200
	ds_read_b64_tr_b16 v[118:119], v172 offset:0x1a00
	s_waitcnt lgkmcnt(6)
	v_mfma_f32_32x32x16_bf16 v[0:15], v[72:75], v[120:123], v[0:15]
	ds_read_b64_tr_b16 v[120:121], v172 offset:0x2200
	ds_read_b64_tr_b16 v[122:123], v172 offset:0x2a00
	s_waitcnt lgkmcnt(6)
	v_mfma_f32_32x32x16_bf16 v[0:15], v[76:79], v[124:127], v[0:15]
	ds_read_b64_tr_b16 v[124:125], v172 offset:0x3200
	ds_read_b64_tr_b16 v[126:127], v172 offset:0x3a00
	s_waitcnt lgkmcnt(6)
	v_mfma_f32_32x32x16_bf16 v[16:31], v[64:67], v[112:115], v[16:31]
	ds_read_b64_tr_b16 v[112:113], v172 offset:0x400
	ds_read_b64_tr_b16 v[114:115], v172 offset:0xc00
	s_waitcnt lgkmcnt(6)
	v_mfma_f32_32x32x16_bf16 v[16:31], v[68:71], v[116:119], v[16:31]
	ds_read_b64_tr_b16 v[116:117], v172 offset:0x1400
	ds_read_b64_tr_b16 v[118:119], v172 offset:0x1c00
	s_waitcnt lgkmcnt(6)
	v_mfma_f32_32x32x16_bf16 v[16:31], v[72:75], v[120:123], v[16:31]
	ds_read_b64_tr_b16 v[120:121], v172 offset:0x2400
	ds_read_b64_tr_b16 v[122:123], v172 offset:0x2c00
	s_waitcnt lgkmcnt(6)
	v_mfma_f32_32x32x16_bf16 v[16:31], v[76:79], v[124:127], v[16:31]
	ds_read_b64_tr_b16 v[124:125], v172 offset:0x3400
	ds_read_b64_tr_b16 v[126:127], v172 offset:0x3c00
	s_waitcnt lgkmcnt(6)
	v_mfma_f32_32x32x16_bf16 v[32:47], v[64:67], v[112:115], v[32:47]
	ds_read_b64_tr_b16 v[112:113], v172 offset:0x600
	ds_read_b64_tr_b16 v[114:115], v172 offset:0xe00
	s_waitcnt lgkmcnt(6)
	v_mfma_f32_32x32x16_bf16 v[32:47], v[68:71], v[116:119], v[32:47]
	ds_read_b64_tr_b16 v[116:117], v172 offset:0x1600
	ds_read_b64_tr_b16 v[118:119], v172 offset:0x1e00
	s_waitcnt lgkmcnt(6)
	v_mfma_f32_32x32x16_bf16 v[32:47], v[72:75], v[120:123], v[32:47]
	ds_read_b64_tr_b16 v[120:121], v172 offset:0x2600
	ds_read_b64_tr_b16 v[122:123], v172 offset:0x2e00
	s_waitcnt lgkmcnt(6)
	v_mfma_f32_32x32x16_bf16 v[32:47], v[76:79], v[124:127], v[32:47]
	ds_read_b64_tr_b16 v[124:125], v172 offset:0x3600
	ds_read_b64_tr_b16 v[126:127], v172 offset:0x3e00
	s_waitcnt lgkmcnt(6)
	v_mfma_f32_32x32x16_bf16 v[48:63], v[64:67], v[112:115], v[48:63]
	s_add_i32 s20, s36, 64
	s_cmp_le_i32 s20, s59
	v_add_u32_e32 v182, s36, v171
	s_waitcnt lgkmcnt(4)
	v_mfma_f32_32x32x16_bf16 v[48:63], v[68:71], v[116:119], v[48:63]
	s_waitcnt lgkmcnt(2)
	v_mfma_f32_32x32x16_bf16 v[48:63], v[72:75], v[120:123], v[48:63]
	s_waitcnt lgkmcnt(0)
	v_mfma_f32_32x32x16_bf16 v[48:63], v[76:79], v[124:127], v[48:63]
	s_cbranch_scc1 .LBB0_325
; __device__ __forceinline__ int crow(int r, int hi) { return (r & 3) + 8 * (r >> 2) + 4 * hi; }
; template <bool GM>
; __device__ __forceinline__ void partialSM(f32x16& p0, f32x16& p1, bool mask, int kbase, int L, int qpos, int hi) {
;   if (mask) {
; #pragma unroll
;     for (int r = 0; r < 16; ++r) {
;       int k = kbase + crow(r, hi);
;       asm volatile("" : "+v"(k) : "v"(p0[r]));
;       bool ok = k < L;
;       if (GM) ok = ok && (k < 16 || abs(qpos - k) <= 128);
;       p0[r] = ok ? p0[r] : -1e30f;
;       int k2 = k + 32;
;       asm volatile("" : "+v"(k2) : "v"(p1[r]));
;       bool ok2 = k2 < L;
;       if (GM) ok2 = ok2 && (k2 < 16 || abs(qpos - k2) <= 128);
;       p1[r] = ok2 ? p1[r] : -1e30f;
;     }
;   }
	v_add_u32_e32 v64, 64, v182
	s_nop 0
	v_cmp_gt_i32_e32 vcc, s94, v64
	v_add_u32_e32 v64, 32, v64
	s_nop 0
	v_cndmask_b32_e32 v80, v233, v80, vcc
	v_cmp_gt_i32_e32 vcc, s94, v64
	v_add_u32_e32 v64, 0x41, v182
	s_nop 0
	v_cndmask_b32_e32 v96, v233, v96, vcc
	v_cmp_gt_i32_e32 vcc, s94, v64
	v_add_u32_e32 v64, 32, v64
	s_nop 0
	v_cndmask_b32_e32 v81, v233, v81, vcc
	v_cmp_gt_i32_e32 vcc, s94, v64
	v_add_u32_e32 v64, 0x42, v182
	s_nop 0
	v_cndmask_b32_e32 v97, v233, v97, vcc
	v_cmp_gt_i32_e32 vcc, s94, v64
	v_add_u32_e32 v64, 32, v64
	s_nop 0
	v_cndmask_b32_e32 v82, v233, v82, vcc
	v_cmp_gt_i32_e32 vcc, s94, v64
	v_add_u32_e32 v64, 0x43, v182
	s_nop 0
	v_cndmask_b32_e32 v98, v233, v98, vcc
	v_cmp_gt_i32_e32 vcc, s94, v64
	v_add_u32_e32 v64, 32, v64
	s_nop 0
	v_cndmask_b32_e32 v83, v233, v83, vcc
	v_cmp_gt_i32_e32 vcc, s94, v64
	v_add_u32_e32 v64, 0x48, v182
	s_nop 0
	v_cndmask_b32_e32 v99, v233, v99, vcc
	v_cmp_gt_i32_e32 vcc, s94, v64
	v_add_u32_e32 v64, 32, v64
	s_nop 0
	v_cndmask_b32_e32 v84, v233, v84, vcc
	v_cmp_gt_i32_e32 vcc, s94, v64
	v_add_u32_e32 v64, 0x49, v182
	s_nop 0
	v_cndmask_b32_e32 v100, v233, v100, vcc
	v_cmp_gt_i32_e32 vcc, s94, v64
	v_add_u32_e32 v64, 32, v64
	s_nop 0
	v_cndmask_b32_e32 v85, v233, v85, vcc
	v_cmp_gt_i32_e32 vcc, s94, v64
	v_add_u32_e32 v64, 0x4a, v182
	s_nop 0
	v_cndmask_b32_e32 v101, v233, v101, vcc
	v_cmp_gt_i32_e32 vcc, s94, v64
	v_add_u32_e32 v64, 32, v64
	s_nop 0
	v_cndmask_b32_e32 v86, v233, v86, vcc
	v_cmp_gt_i32_e32 vcc, s94, v64
	v_add_u32_e32 v64, 0x4b, v182
	s_nop 0
	v_cndmask_b32_e32 v102, v233, v102, vcc
	v_cmp_gt_i32_e32 vcc, s94, v64
	v_add_u32_e32 v64, 32, v64
	s_nop 0
	v_cndmask_b32_e32 v87, v233, v87, vcc
	v_cmp_gt_i32_e32 vcc, s94, v64
	v_add_u32_e32 v64, 0x50, v182
	s_nop 0
	v_cndmask_b32_e32 v103, v233, v103, vcc
	v_cmp_gt_i32_e32 vcc, s94, v64
	v_add_u32_e32 v64, 32, v64
	s_nop 0
	v_cndmask_b32_e32 v88, v233, v88, vcc
	v_cmp_gt_i32_e32 vcc, s94, v64
	v_add_u32_e32 v64, 0x51, v182
	s_nop 0
	v_cndmask_b32_e32 v104, v233, v104, vcc
	v_cmp_gt_i32_e32 vcc, s94, v64
	v_add_u32_e32 v64, 32, v64
	s_nop 0
	v_cndmask_b32_e32 v89, v233, v89, vcc
	v_cmp_gt_i32_e32 vcc, s94, v64
	v_add_u32_e32 v64, 0x52, v182
	s_nop 0
	v_cndmask_b32_e32 v105, v233, v105, vcc
	v_cmp_gt_i32_e32 vcc, s94, v64
	v_add_u32_e32 v64, 32, v64
	s_nop 0
	v_cndmask_b32_e32 v90, v233, v90, vcc
	v_cmp_gt_i32_e32 vcc, s94, v64
	v_add_u32_e32 v64, 0x53, v182
	s_nop 0
	v_cndmask_b32_e32 v106, v233, v106, vcc
	v_cmp_gt_i32_e32 vcc, s94, v64
	v_add_u32_e32 v64, 32, v64
	s_nop 0
	v_cndmask_b32_e32 v91, v233, v91, vcc
	v_cmp_gt_i32_e32 vcc, s94, v64
	v_add_u32_e32 v64, 0x58, v182
	s_nop 0
	v_cndmask_b32_e32 v107, v233, v107, vcc
	v_cmp_gt_i32_e32 vcc, s94, v64
	v_add_u32_e32 v64, 32, v64
	s_nop 0
	v_cndmask_b32_e32 v92, v233, v92, vcc
	v_cmp_gt_i32_e32 vcc, s94, v64
	v_add_u32_e32 v64, 0x59, v182
	s_nop 0
	v_cndmask_b32_e32 v108, v233, v108, vcc
	v_cmp_gt_i32_e32 vcc, s94, v64
	v_add_u32_e32 v64, 32, v64
	s_nop 0
	v_cndmask_b32_e32 v93, v233, v93, vcc
	v_cmp_gt_i32_e32 vcc, s94, v64
	v_add_u32_e32 v64, 0x5a, v182
	s_nop 0
	v_cndmask_b32_e32 v109, v233, v109, vcc
	v_cmp_gt_i32_e32 vcc, s94, v64
	v_add_u32_e32 v64, 32, v64
	s_nop 0
	v_cndmask_b32_e32 v94, v233, v94, vcc
	v_cmp_gt_i32_e32 vcc, s94, v64
	v_add_u32_e32 v64, 0x5b, v182
	s_nop 0
	v_cndmask_b32_e32 v110, v233, v110, vcc
	v_cmp_gt_i32_e32 vcc, s94, v64
	v_add_u32_e32 v64, 32, v64
	s_nop 0
	v_cndmask_b32_e32 v95, v233, v95, vcc
	v_cmp_gt_i32_e32 vcc, s94, v64
	s_nop 1
	v_cndmask_b32_e32 v111, v233, v111, vcc
; #define WAIT_V0() asm volatile("s_waitcnt vmcnt(0)" ::: "memory")
; #define SBAR() __builtin_amdgcn_sched_barrier(0)
; #define SWRITE(b) do { FRESH_COORDS(); \
;     if constexpr (!KDMA) { _Pragma("unroll") for (int i = 0; i < KC; ++i) *reinterpret_cast<bf16x8*>(shm + (b) * SHM_K + klo[i]) = ks[i]; } \
;     _Pragma("unroll") for (int i = 0; i < VC; ++i) *reinterpret_cast<bf16x8*>(shm + (b) * SHM_V + vlo[i]) = vs[i]; } while (0)
; #define QKT(P0, P1, BUF) qkt<DQK, QL>(P0, P1, shm + K_OFF + (BUF) * SHM_K, qr, qlds, kofs, negM)
; __device__ __forceinline__ void finishSM(f32x16& p0, f32x16& p1, float& l_reg, bf16x8& pa0, bf16x8& pa1, bf16x8& pa2, bf16x8& pa3) {
; #pragma unroll
;   for (int r = 0; r < 16; ++r) p1[r] = __builtin_amdgcn_exp2f(p1[r]);
;   float ps = 0;
; #pragma unroll
;   for (int r = 0; r < 16; ++r) ps += p0[r];
; #pragma unroll
;   for (int r = 0; r < 16; ++r) ps += p1[r];
;   { auto rr = __builtin_amdgcn_permlane32_swap(__float_as_uint(ps), __float_as_uint(ps), false, false);
;     ps = __uint_as_float(rr[0]) + __uint_as_float(rr[1]); }
;   l_reg += ps;
;     ...
;   PK4(p0, 0, pa0); PK4(p0, 8, pa1); PK4(p1, 0, pa2); PK4(p1, 8, pa3);
;     ...
; }
;     ...
;     __syncthreads(); WAIT_V0(); SWRITE(0);
;     __syncthreads();
;     SBAR();
;     if constexpr (ONEP) { finishSM(pB0, pB1, l_reg, pa0, pa1, pa2, pa3); SBAR(); QKT(pA0, pA1, 0); }
;     else { QKT(pA0, pA1, 0); finishSM(pB0, pB1, l_reg, pa0, pa1, pa2, pa3); }
;     SBAR();
;     if (j + 2 < NT) SLOAD(TKEY(j + 2), 1);
.LBB0_325:
	s_barrier
	s_waitcnt vmcnt(0)
	s_waitcnt vmcnt(2)
	ds_write_b128 v179, v[146:149] offset:32768
	s_waitcnt vmcnt(1)
	ds_write_b128 v177, v[150:153]
	s_waitcnt vmcnt(0)
	ds_write_b128 v178, v[154:157]
	v_exp_f32_e32 v183, v80
	v_exp_f32_e32 v188, v81
	v_exp_f32_e32 v189, v82
	v_exp_f32_e32 v190, v83
	v_exp_f32_e32 v191, v84
	v_exp_f32_e32 v192, v85
	v_exp_f32_e32 v193, v86
	v_exp_f32_e32 v194, v87
	v_exp_f32_e32 v195, v88
	v_exp_f32_e32 v196, v89
	v_exp_f32_e32 v197, v90
	v_exp_f32_e32 v198, v91
	v_exp_f32_e32 v199, v92
	v_exp_f32_e32 v200, v93
	v_exp_f32_e32 v201, v94
	v_exp_f32_e32 v202, v95
	s_waitcnt lgkmcnt(0)
	s_barrier
	ds_read_b128 v[64:67], v174 offset:32768
	ds_read_b128 v[184:187], v174 offset:36864
	v_exp_f32_e32 v111, v111
	s_waitcnt lgkmcnt(1)
	v_mfma_f32_32x32x16_bf16 v[80:95], v[64:67], v[142:145], v[238:253]
	s_waitcnt lgkmcnt(0)
	v_mfma_f32_32x32x16_bf16 v[64:79], v[184:187], v[142:145], v[238:253]
	ds_read_b128 v[112:115], v175 offset:32768
	ds_read_b128 v[116:119], v175 offset:36864
	v_exp_f32_e32 v120, v102
	v_exp_f32_e32 v121, v103
	v_exp_f32_e32 v122, v104
	v_exp_f32_e32 v123, v105
	v_exp_f32_e32 v124, v106
	v_exp_f32_e32 v125, v107
	s_waitcnt lgkmcnt(1)
	v_mfma_f32_32x32x16_bf16 v[80:95], v[112:115], v[138:141], v[80:95]
	v_exp_f32_e32 v126, v108
	v_exp_f32_e32 v127, v109
	v_exp_f32_e32 v184, v110
	s_waitcnt lgkmcnt(0)
	v_mfma_f32_32x32x16_bf16 v[64:79], v[116:119], v[138:141], v[64:79]
	ds_read_b128 v[112:115], v173 offset:32768
	ds_read_b128 v[116:119], v173 offset:36864
	s_waitcnt lgkmcnt(1)
	v_mfma_f32_32x32x16_bf16 v[80:95], v[112:115], v[134:137], v[80:95]
	s_waitcnt lgkmcnt(0)
	v_mfma_f32_32x32x16_bf16 v[64:79], v[116:119], v[134:137], v[64:79]
	ds_read_b128 v[112:115], v176 offset:32768
	ds_read_b128 v[116:119], v176 offset:36864
	s_waitcnt lgkmcnt(1)
	v_mfma_f32_32x32x16_bf16 v[80:95], v[112:115], v[130:133], v[80:95]
	v_exp_f32_e32 v114, v96
	v_add_f32_e32 v96, 0, v183
	v_add_f32_e32 v96, v190, v96
	v_add_f32_e32 v112, v188, v191
	v_add_f32_e32 v113, v189, v192
	v_add_f32_e32 v96, v193, v96
	v_add_f32_e32 v112, v194, v112
	v_add_f32_e32 v113, v195, v113
	v_add_f32_e32 v96, v196, v96
	v_add_f32_e32 v112, v197, v112
	v_add_f32_e32 v113, v198, v113
	v_add_f32_e32 v96, v199, v96
	v_exp_f32_e32 v115, v97
	v_add_f32_e32 v112, v200, v112
	s_waitcnt lgkmcnt(0)
	v_mfma_f32_32x32x16_bf16 v[64:79], v[116:119], v[130:133], v[64:79]
	v_exp_f32_e32 v116, v98
	v_add_f32_e32 v113, v201, v113
	v_exp_f32_e32 v117, v99
	v_add_f32_e32 v96, v202, v96
	v_exp_f32_e32 v118, v100
	v_add_f32_e32 v112, v114, v112
	v_exp_f32_e32 v119, v101
	v_add_f32_e32 v113, v115, v113
	v_add_f32_e32 v96, v116, v96
	v_add_f32_e32 v112, v117, v112
	v_add_f32_e32 v113, v118, v113
	v_add_f32_e32 v96, v119, v96
	v_add_f32_e32 v112, v120, v112
	v_add_f32_e32 v113, v121, v113
	v_add_f32_e32 v96, v122, v96
	v_add_f32_e32 v112, v123, v112
	v_add_f32_e32 v113, v124, v113
	v_add_f32_e32 v96, v125, v96
	v_add_f32_e32 v112, v126, v112
	v_add_f32_e32 v113, v127, v113
	v_add_f32_e32 v96, v184, v96
	v_add_f32_e32 v112, v111, v112
	v_add_f32_e32 v112, v96, v112
	v_add_f32_e32 v112, v113, v112
	v_mov_b32_e32 v113, v112
	v_cvt_pk_bf16_f32 v96, v183, v188
	v_cvt_pk_bf16_f32 v97, v189, v190
	v_cvt_pk_bf16_f32 v98, v191, v192
	v_cvt_pk_bf16_f32 v99, v193, v194
	v_cvt_pk_bf16_f32 v100, v195, v196
	v_cvt_pk_bf16_f32 v101, v197, v198
	v_cvt_pk_bf16_f32 v102, v199, v200
	v_cvt_pk_bf16_f32 v103, v201, v202
	v_cvt_pk_bf16_f32 v104, v114, v115
	v_cvt_pk_bf16_f32 v105, v116, v117
	v_cvt_pk_bf16_f32 v106, v118, v119
	v_cvt_pk_bf16_f32 v107, v120, v121
	v_cvt_pk_bf16_f32 v108, v122, v123
	v_cvt_pk_bf16_f32 v109, v124, v125
	v_cvt_pk_bf16_f32 v110, v126, v127
	v_cvt_pk_bf16_f32 v111, v184, v111
	s_nop 1
	v_permlane32_swap_b32_e32 v112, v113
	v_permlane32_swap_b32_e32 v96, v98
	v_permlane32_swap_b32_e32 v97, v99
	v_permlane32_swap_b32_e32 v100, v102
	v_permlane32_swap_b32_e32 v101, v103
	v_permlane32_swap_b32_e32 v104, v106
	v_permlane32_swap_b32_e32 v105, v107
	v_permlane32_swap_b32_e32 v108, v110
	v_permlane32_swap_b32_e32 v109, v111
	s_cmp_lt_u32 s26, s58
	s_cselect_b64 s[22:23], -1, 0
	s_cmp_ge_u32 s26, s58
	s_cselect_b64 s[20:21], -1, 0
	s_and_b64 vcc, exec, s[20:21]
	s_cbranch_vccnz .LBB0_327
	s_add_u32 s100, s80, 0x593c000
	s_addc_u32 s101, s81, 0
	global_load_dwordx4 v[146:149], v158, s[100:101] offset:1280
	global_load_dwordx4 v[150:153], v160, s[100:101] offset:2304
	global_load_dwordx4 v[154:157], v162, s[100:101] offset:2304

; __device__ __forceinline__ void finishSM(f32x16& p0, f32x16& p1, float& l_reg, bf16x8& pa0, bf16x8& pa1, bf16x8& pa2, bf16x8& pa3) {
; #pragma unroll
;   for (int r = 0; r < 16; ++r) p1[r] = __builtin_amdgcn_exp2f(p1[r]);
;   float ps = 0;
; #pragma unroll
;   for (int r = 0; r < 16; ++r) ps += p0[r];
; #pragma unroll
;   for (int r = 0; r < 16; ++r) ps += p1[r];
;   { auto rr = __builtin_amdgcn_permlane32_swap(__float_as_uint(ps), __float_as_uint(ps), false, false);
;     ps = __uint_as_float(rr[0]) + __uint_as_float(rr[1]); }
;   l_reg += ps;
;     ...
;   PK4(p0, 0, pa0); PK4(p0, 8, pa1); PK4(p1, 0, pa2); PK4(p1, 8, pa3);
;     ...
; }
; template <int DQK, int QL>
; __device__ __forceinline__ void qkt(f32x16& p0, f32x16& p1, const char* Ks, const bf16x8 (&qr)[DQK / 16 - QL], const char* qlds, const int (&kofs)[4], float negM) {
;   constexpr int QR = DQK / 16 - QL;
; #pragma unroll
;   for (int r = 0; r < 16; ++r) { p0[r] = negM; p1[r] = negM; }
; #pragma unroll
;   for (int d0 = 0; d0 < DQK / 16; ++d0) {
;     const char* kp = Ks + kofs[d0 & 3] + (d0 >> 2) * 128;
;     bf16x8 b0 = *reinterpret_cast<const bf16x8*>(kp);
;     bf16x8 b1 = *reinterpret_cast<const bf16x8*>(kp + 32 * DQK * 2);
;     bf16x8 qf;
;     if constexpr (QL > 0) { if (d0 < QR) qf = qr[d0 < QR ? d0 : 0]; else qf = *reinterpret_cast<const bf16x8*>(qlds + (d0 - QR) * 1024); }
;     else qf = qr[d0];
;     p0 = __builtin_amdgcn_mfma_f32_32x32x16_bf16(b0, qf, p0, 0, 0, 0);
;     p1 = __builtin_amdgcn_mfma_f32_32x32x16_bf16(b1, qf, p1, 0, 0, 0);
;   }
; }
; template <int NCB> __device__ __forceinline__ int v_st(int k, int c) {
;   const int kk = (k & ~0xC) | ((k & 4) << 1) | ((k & 8) >> 1);
;   return ((kk >> 3) * NCB + (c >> 5)) * 512 + ((kk & 7) * 32 + (c & 31)) * 2;
; }
; __device__ __forceinline__ int v_rd_base(int lane) { return ((lane & 3) << 3) | (((lane >> 2) & 3) << 6) | (((lane >> 4) & 1) << 5) | (((lane >> 5) & 1) << 8); }
; template <int OFF> __device__ __forceinline__ s16x4 tr_read(int vb) {
;   s16x4 r; asm volatile("ds_read_b64_tr_b16 %0, %1 offset:%2" : "=&v"(r) : "v"(vb), "i"(OFF) : "memory"); return r;
; }
; template <int NCB, int D0> __device__ __forceinline__ void pv_one(f32x16& od, int vb, bf16x8 pa0, bf16x8 pa1, bf16x8 pa2, bf16x8 pa3) {
;   constexpr int KSTEP = NCB * 1024, HALF = NCB * 512, B0 = D0 * 512;
.LBB0_342:
	ds_read_b128 v[96:99], v174 offset:40960
	ds_read_b128 v[182:185], v174 offset:45056
	v_exp_f32_e32 v100, v68
	v_exp_f32_e32 v101, v69
	s_waitcnt lgkmcnt(1)
	v_mfma_f32_32x32x16_bf16 v[80:95], v[96:99], v[142:145], v[238:253]
	ds_read_b128 v[96:99], v175 offset:40960
	ds_read_b128 v[186:189], v175 offset:45056
	v_exp_f32_e32 v102, v70
	v_exp_f32_e32 v103, v71
	v_exp_f32_e32 v104, v72
	v_exp_f32_e32 v105, v73
	v_exp_f32_e32 v106, v74
	v_exp_f32_e32 v107, v75
	s_waitcnt lgkmcnt(1)
	v_mfma_f32_32x32x16_bf16 v[80:95], v[96:99], v[138:141], v[80:95]
	ds_read_b128 v[96:99], v173 offset:40960
	ds_read_b128 v[190:193], v173 offset:45056
	v_exp_f32_e32 v108, v76
	v_exp_f32_e32 v109, v77
	v_exp_f32_e32 v110, v78
	v_exp_f32_e32 v79, v79
	s_waitcnt lgkmcnt(1)
	v_mfma_f32_32x32x16_bf16 v[80:95], v[96:99], v[134:137], v[80:95]
	ds_read_b128 v[96:99], v176 offset:40960
	ds_read_b128 v[194:197], v176 offset:45056
	s_waitcnt lgkmcnt(1)
	v_mfma_f32_32x32x16_bf16 v[80:95], v[96:99], v[130:133], v[80:95]
	v_exp_f32_e32 v96, v64
	v_add_f32_e32 v64, 0, v165
	v_add_f32_e32 v64, v166, v64
	v_add_f32_e32 v180, v167, v155
	v_add_f32_e32 v181, v157, v164
	v_add_f32_e32 v64, v154, v64
	v_add_f32_e32 v180, v156, v180
	v_add_f32_e32 v181, v151, v181
	v_add_f32_e32 v64, v153, v64
	v_add_f32_e32 v180, v149, v180
	v_add_f32_e32 v181, v152, v181
	v_add_f32_e32 v64, v147, v64
	v_exp_f32_e32 v97, v65
	v_add_f32_e32 v180, v150, v180
	v_exp_f32_e32 v98, v66
	v_add_f32_e32 v181, v146, v181
	v_exp_f32_e32 v99, v67
	v_add_f32_e32 v64, v148, v64
	v_add_f32_e32 v180, v96, v180
	v_add_f32_e32 v181, v97, v181
	v_add_f32_e32 v64, v98, v64
	v_add_f32_e32 v180, v99, v180
	v_add_f32_e32 v181, v100, v181
	v_add_f32_e32 v64, v101, v64
	v_add_f32_e32 v180, v102, v180
	v_add_f32_e32 v181, v103, v181
	v_add_f32_e32 v64, v104, v64
	v_add_f32_e32 v180, v105, v180
	v_add_f32_e32 v181, v106, v181
	v_add_f32_e32 v64, v107, v64
	v_add_f32_e32 v180, v108, v180
	v_add_f32_e32 v181, v109, v181
	v_add_f32_e32 v64, v110, v64
	v_add_f32_e32 v180, v79, v180
	v_add_f32_e32 v180, v64, v180
	v_add_f32_e32 v180, v181, v180
	v_mov_b32_e32 v181, v180
	s_nop 1
	v_permlane32_swap_b32_e32 v180, v181
	v_cvt_pk_bf16_f32 v64, v165, v167
	v_cvt_pk_bf16_f32 v65, v157, v166
	v_cvt_pk_bf16_f32 v66, v155, v164
	v_cvt_pk_bf16_f32 v67, v154, v156
	v_cvt_pk_bf16_f32 v68, v151, v153
	v_cvt_pk_bf16_f32 v69, v149, v152
	v_cvt_pk_bf16_f32 v70, v147, v150
	v_cvt_pk_bf16_f32 v71, v146, v148
	v_cvt_pk_bf16_f32 v72, v96, v97
	v_cvt_pk_bf16_f32 v73, v98, v99
	v_cvt_pk_bf16_f32 v74, v100, v101
	v_cvt_pk_bf16_f32 v75, v102, v103
	v_cvt_pk_bf16_f32 v76, v104, v105
	v_cvt_pk_bf16_f32 v77, v106, v107
	v_cvt_pk_bf16_f32 v78, v108, v109
	v_cvt_pk_bf16_f32 v79, v110, v79
	s_nop 0
	v_permlane32_swap_b32_e32 v64, v66
	v_permlane32_swap_b32_e32 v65, v67
	v_permlane32_swap_b32_e32 v68, v70
	v_permlane32_swap_b32_e32 v69, v71
	v_permlane32_swap_b32_e32 v72, v74
	v_permlane32_swap_b32_e32 v73, v75
	v_permlane32_swap_b32_e32 v76, v78
	v_permlane32_swap_b32_e32 v77, v79
	v_mfma_f32_32x32x16_bf16 v[96:111], v[182:185], v[142:145], v[238:253]
	v_mfma_f32_32x32x16_bf16 v[96:111], v[186:189], v[138:141], v[96:111]
	s_add_u32 s100, s0, 0x590c000
	s_addc_u32 s101, s1, 0
	global_load_dwordx4 v[146:149], v158, s[100:101] offset:1408
	global_load_dwordx4 v[150:153], v160, s[100:101] offset:2304
	v_mfma_f32_32x32x16_bf16 v[96:111], v[190:193], v[134:137], v[96:111]
	global_load_dwordx4 v[154:157], v162, s[100:101] offset:2304
	s_waitcnt lgkmcnt(0)
	v_mfma_f32_32x32x16_bf16 v[96:111], v[194:197], v[130:133], v[96:111]
	ds_read_b64_tr_b16 v[112:113], v172 offset:0
	ds_read_b64_tr_b16 v[114:115], v172 offset:0x800
	ds_read_b64_tr_b16 v[116:117], v172 offset:0x1000
	ds_read_b64_tr_b16 v[118:119], v172 offset:0x1800
	ds_read_b64_tr_b16 v[120:121], v172 offset:0x2000
	ds_read_b64_tr_b16 v[122:123], v172 offset:0x2800
	ds_read_b64_tr_b16 v[124:125], v172 offset:0x3000
	ds_read_b64_tr_b16 v[126:127], v172 offset:0x3800
	s_nop 0
	s_waitcnt lgkmcnt(6)
	v_mfma_f32_32x32x16_bf16 v[0:15], v[64:67], v[112:115], v[0:15]
	ds_read_b64_tr_b16 v[112:113], v172 offset:0x200
	ds_read_b64_tr_b16 v[114:115], v172 offset:0xa00
	s_waitcnt lgkmcnt(6)
	v_mfma_f32_32x32x16_bf16 v[0:15], v[68:71], v[116:119], v[0:15]
	ds_read_b64_tr_b16 v[116:117], v172 offset:0x1200
	ds_read_b64_tr_b16 v[118:119], v172 offset:0x1a00
	s_waitcnt lgkmcnt(6)
	v_mfma_f32_32x32x16_bf16 v[0:15], v[72:75], v[120:123], v[0:15]
	ds_read_b64_tr_b16 v[120:121], v172 offset:0x2200
	ds_read_b64_tr_b16 v[122:123], v172 offset:0x2a00
	s_waitcnt lgkmcnt(6)
	v_mfma_f32_32x32x16_bf16 v[0:15], v[76:79], v[124:127], v[0:15]
	ds_read_b64_tr_b16 v[124:125], v172 offset:0x3200
	ds_read_b64_tr_b16 v[126:127], v172 offset:0x3a00
	s_waitcnt lgkmcnt(6)
	v_mfma_f32_32x32x16_bf16 v[16:31], v[64:67], v[112:115], v[16:31]
	ds_read_b64_tr_b16 v[112:113], v172 offset:0x400
	ds_read_b64_tr_b16 v[114:115], v172 offset:0xc00
	s_waitcnt lgkmcnt(6)
	v_mfma_f32_32x32x16_bf16 v[16:31], v[68:71], v[116:119], v[16:31]
	ds_read_b64_tr_b16 v[116:117], v172 offset:0x1400
	ds_read_b64_tr_b16 v[118:119], v172 offset:0x1c00
	s_waitcnt lgkmcnt(6)
	v_mfma_f32_32x32x16_bf16 v[16:31], v[72:75], v[120:123], v[16:31]
	ds_read_b64_tr_b16 v[120:121], v172 offset:0x2400
	ds_read_b64_tr_b16 v[122:123], v172 offset:0x2c00
	s_waitcnt lgkmcnt(6)
	v_mfma_f32_32x32x16_bf16 v[16:31], v[76:79], v[124:127], v[16:31]
	ds_read_b64_tr_b16 v[124:125], v172 offset:0x3400
	ds_read_b64_tr_b16 v[126:127], v172 offset:0x3c00
	s_waitcnt lgkmcnt(6)
	v_mfma_f32_32x32x16_bf16 v[32:47], v[64:67], v[112:115], v[32:47]
	ds_read_b64_tr_b16 v[112:113], v172 offset:0x600
	ds_read_b64_tr_b16 v[114:115], v172 offset:0xe00
	s_waitcnt lgkmcnt(6)
	v_mfma_f32_32x32x16_bf16 v[32:47], v[68:71], v[116:119], v[32:47]
	ds_read_b64_tr_b16 v[116:117], v172 offset:0x1600
	ds_read_b64_tr_b16 v[118:119], v172 offset:0x1e00
	s_waitcnt lgkmcnt(6)
	v_mfma_f32_32x32x16_bf16 v[32:47], v[72:75], v[120:123], v[32:47]
	ds_read_b64_tr_b16 v[120:121], v172 offset:0x2600
	ds_read_b64_tr_b16 v[122:123], v172 offset:0x2e00
	s_waitcnt lgkmcnt(6)
	v_mfma_f32_32x32x16_bf16 v[32:47], v[76:79], v[124:127], v[32:47]
	ds_read_b64_tr_b16 v[124:125], v172 offset:0x3600
	ds_read_b64_tr_b16 v[126:127], v172 offset:0x3e00
	s_waitcnt lgkmcnt(6)
	v_mfma_f32_32x32x16_bf16 v[48:63], v[64:67], v[112:115], v[48:63]
	s_add_i32 s20, s36, 64
	s_cmp_le_i32 s20, s59
	v_add_u32_e32 v182, s36, v171
	s_waitcnt lgkmcnt(4)
	v_mfma_f32_32x32x16_bf16 v[48:63], v[68:71], v[116:119], v[48:63]
	s_waitcnt lgkmcnt(2)
	v_mfma_f32_32x32x16_bf16 v[48:63], v[72:75], v[120:123], v[48:63]
	s_waitcnt lgkmcnt(0)
	v_mfma_f32_32x32x16_bf16 v[48:63], v[76:79], v[124:127], v[48:63]
	s_cbranch_scc1 .LBB0_344
; __device__ __forceinline__ int crow(int r, int hi) { return (r & 3) + 8 * (r >> 2) + 4 * hi; }
; template <bool GM>
; __device__ __forceinline__ void partialSM(f32x16& p0, f32x16& p1, bool mask, int kbase, int L, int qpos, int hi) {
;   if (mask) {
; #pragma unroll
;     for (int r = 0; r < 16; ++r) {
;       int k = kbase + crow(r, hi);
;       asm volatile("" : "+v"(k) : "v"(p0[r]));
;       bool ok = k < L;
;       if (GM) ok = ok && (k < 16 || abs(qpos - k) <= 128);
;       p0[r] = ok ? p0[r] : -1e30f;
;       int k2 = k + 32;
;       asm volatile("" : "+v"(k2) : "v"(p1[r]));
;       bool ok2 = k2 < L;
;       if (GM) ok2 = ok2 && (k2 < 16 || abs(qpos - k2) <= 128);
;       p1[r] = ok2 ? p1[r] : -1e30f;
;     }
;   }
	v_add_u32_e32 v64, 64, v182
	s_nop 0
	v_cmp_gt_i32_e32 vcc, s94, v64
	v_add_u32_e32 v64, 32, v64
	s_nop 0
	v_cndmask_b32_e32 v80, v233, v80, vcc
	v_cmp_gt_i32_e32 vcc, s94, v64
	v_add_u32_e32 v64, 0x41, v182
	s_nop 0
	v_cndmask_b32_e32 v96, v233, v96, vcc
	v_cmp_gt_i32_e32 vcc, s94, v64
	v_add_u32_e32 v64, 32, v64
	s_nop 0
	v_cndmask_b32_e32 v81, v233, v81, vcc
	v_cmp_gt_i32_e32 vcc, s94, v64
	v_add_u32_e32 v64, 0x42, v182
	s_nop 0
	v_cndmask_b32_e32 v97, v233, v97, vcc
	v_cmp_gt_i32_e32 vcc, s94, v64
	v_add_u32_e32 v64, 32, v64
	s_nop 0
	v_cndmask_b32_e32 v82, v233, v82, vcc
	v_cmp_gt_i32_e32 vcc, s94, v64
	v_add_u32_e32 v64, 0x43, v182
	s_nop 0
	v_cndmask_b32_e32 v98, v233, v98, vcc
	v_cmp_gt_i32_e32 vcc, s94, v64
	v_add_u32_e32 v64, 32, v64
	s_nop 0
	v_cndmask_b32_e32 v83, v233, v83, vcc
	v_cmp_gt_i32_e32 vcc, s94, v64
	v_add_u32_e32 v64, 0x48, v182
	s_nop 0
	v_cndmask_b32_e32 v99, v233, v99, vcc
	v_cmp_gt_i32_e32 vcc, s94, v64
	v_add_u32_e32 v64, 32, v64
	s_nop 0
	v_cndmask_b32_e32 v84, v233, v84, vcc
	v_cmp_gt_i32_e32 vcc, s94, v64
	v_add_u32_e32 v64, 0x49, v182
	s_nop 0
	v_cndmask_b32_e32 v100, v233, v100, vcc
	v_cmp_gt_i32_e32 vcc, s94, v64
	v_add_u32_e32 v64, 32, v64
	s_nop 0
	v_cndmask_b32_e32 v85, v233, v85, vcc
	v_cmp_gt_i32_e32 vcc, s94, v64
	v_add_u32_e32 v64, 0x4a, v182
	s_nop 0
	v_cndmask_b32_e32 v101, v233, v101, vcc
	v_cmp_gt_i32_e32 vcc, s94, v64
	v_add_u32_e32 v64, 32, v64
	s_nop 0
	v_cndmask_b32_e32 v86, v233, v86, vcc
	v_cmp_gt_i32_e32 vcc, s94, v64
	v_add_u32_e32 v64, 0x4b, v182
	s_nop 0
	v_cndmask_b32_e32 v102, v233, v102, vcc
	v_cmp_gt_i32_e32 vcc, s94, v64
	v_add_u32_e32 v64, 32, v64
	s_nop 0
	v_cndmask_b32_e32 v87, v233, v87, vcc
	v_cmp_gt_i32_e32 vcc, s94, v64
	v_add_u32_e32 v64, 0x50, v182
	s_nop 0
	v_cndmask_b32_e32 v103, v233, v103, vcc
	v_cmp_gt_i32_e32 vcc, s94, v64
	v_add_u32_e32 v64, 32, v64
	s_nop 0
	v_cndmask_b32_e32 v88, v233, v88, vcc
	v_cmp_gt_i32_e32 vcc, s94, v64
	v_add_u32_e32 v64, 0x51, v182
	s_nop 0
	v_cndmask_b32_e32 v104, v233, v104, vcc
	v_cmp_gt_i32_e32 vcc, s94, v64
	v_add_u32_e32 v64, 32, v64
	s_nop 0
	v_cndmask_b32_e32 v89, v233, v89, vcc
	v_cmp_gt_i32_e32 vcc, s94, v64
	v_add_u32_e32 v64, 0x52, v182
	s_nop 0
	v_cndmask_b32_e32 v105, v233, v105, vcc
	v_cmp_gt_i32_e32 vcc, s94, v64
	v_add_u32_e32 v64, 32, v64
	s_nop 0
	v_cndmask_b32_e32 v90, v233, v90, vcc
	v_cmp_gt_i32_e32 vcc, s94, v64
	v_add_u32_e32 v64, 0x53, v182
	s_nop 0
	v_cndmask_b32_e32 v106, v233, v106, vcc
	v_cmp_gt_i32_e32 vcc, s94, v64
	v_add_u32_e32 v64, 32, v64
	s_nop 0
	v_cndmask_b32_e32 v91, v233, v91, vcc
	v_cmp_gt_i32_e32 vcc, s94, v64
	v_add_u32_e32 v64, 0x58, v182
	s_nop 0
	v_cndmask_b32_e32 v107, v233, v107, vcc
	v_cmp_gt_i32_e32 vcc, s94, v64
	v_add_u32_e32 v64, 32, v64
	s_nop 0
	v_cndmask_b32_e32 v92, v233, v92, vcc
	v_cmp_gt_i32_e32 vcc, s94, v64
	v_add_u32_e32 v64, 0x59, v182
	s_nop 0
	v_cndmask_b32_e32 v108, v233, v108, vcc
	v_cmp_gt_i32_e32 vcc, s94, v64
	v_add_u32_e32 v64, 32, v64
	s_nop 0
	v_cndmask_b32_e32 v93, v233, v93, vcc
	v_cmp_gt_i32_e32 vcc, s94, v64
	v_add_u32_e32 v64, 0x5a, v182
	s_nop 0
	v_cndmask_b32_e32 v109, v233, v109, vcc
	v_cmp_gt_i32_e32 vcc, s94, v64
	v_add_u32_e32 v64, 32, v64
	s_nop 0
	v_cndmask_b32_e32 v94, v233, v94, vcc
	v_cmp_gt_i32_e32 vcc, s94, v64
	v_add_u32_e32 v64, 0x5b, v182
	s_nop 0
	v_cndmask_b32_e32 v110, v233, v110, vcc
	v_cmp_gt_i32_e32 vcc, s94, v64
	v_add_u32_e32 v64, 32, v64
	s_nop 0
	v_cndmask_b32_e32 v95, v233, v95, vcc
	v_cmp_gt_i32_e32 vcc, s94, v64
	s_nop 1
	v_cndmask_b32_e32 v111, v233, v111, vcc
; #define WAIT_V0() asm volatile("s_waitcnt vmcnt(0)" ::: "memory")
; #define SBAR() __builtin_amdgcn_sched_barrier(0)
; #define SWRITE(b) do { FRESH_COORDS(); \
;     if constexpr (!KDMA) { _Pragma("unroll") for (int i = 0; i < KC; ++i) *reinterpret_cast<bf16x8*>(shm + (b) * SHM_K + klo[i]) = ks[i]; } \
;     _Pragma("unroll") for (int i = 0; i < VC; ++i) *reinterpret_cast<bf16x8*>(shm + (b) * SHM_V + vlo[i]) = vs[i]; } while (0)
; #define QKT(P0, P1, BUF) qkt<DQK, QL>(P0, P1, shm + K_OFF + (BUF) * SHM_K, qr, qlds, kofs, negM)
; __device__ __forceinline__ void finishSM(f32x16& p0, f32x16& p1, float& l_reg, bf16x8& pa0, bf16x8& pa1, bf16x8& pa2, bf16x8& pa3) {
; #pragma unroll
;   for (int r = 0; r < 16; ++r) p1[r] = __builtin_amdgcn_exp2f(p1[r]);
;   float ps = 0;
; #pragma unroll
;   for (int r = 0; r < 16; ++r) ps += p0[r];
; #pragma unroll
;   for (int r = 0; r < 16; ++r) ps += p1[r];
;   { auto rr = __builtin_amdgcn_permlane32_swap(__float_as_uint(ps), __float_as_uint(ps), false, false);
;     ps = __uint_as_float(rr[0]) + __uint_as_float(rr[1]); }
;   l_reg += ps;
;     ...
;   PK4(p0, 0, pa0); PK4(p0, 8, pa1); PK4(p1, 0, pa2); PK4(p1, 8, pa3);
;     ...
; }
;     ...
;     __syncthreads(); WAIT_V0(); SWRITE(0);
;     __syncthreads();
;     SBAR();
;     if constexpr (ONEP) { finishSM(pB0, pB1, l_reg, pa0, pa1, pa2, pa3); SBAR(); QKT(pA0, pA1, 0); }
;     else { QKT(pA0, pA1, 0); finishSM(pB0, pB1, l_reg, pa0, pa1, pa2, pa3); }
;     SBAR();
;     if (j + 2 < NT) SLOAD(TKEY(j + 2), 1);
.LBB0_344:
	s_barrier
	s_waitcnt vmcnt(0)
	s_waitcnt vmcnt(2)
	ds_write_b128 v179, v[146:149] offset:32768
	s_waitcnt vmcnt(1)
	ds_write_b128 v177, v[150:153]
	s_waitcnt vmcnt(0)
	ds_write_b128 v178, v[154:157]
	v_exp_f32_e32 v183, v80
	v_exp_f32_e32 v188, v81
	v_exp_f32_e32 v189, v82
	v_exp_f32_e32 v190, v83
	v_exp_f32_e32 v191, v84
	v_exp_f32_e32 v192, v85
	v_exp_f32_e32 v193, v86
	v_exp_f32_e32 v194, v87
	v_exp_f32_e32 v195, v88
	v_exp_f32_e32 v196, v89
	v_exp_f32_e32 v197, v90
	v_exp_f32_e32 v198, v91
	v_exp_f32_e32 v199, v92
	v_exp_f32_e32 v200, v93
	v_exp_f32_e32 v201, v94
	v_exp_f32_e32 v202, v95
	s_waitcnt lgkmcnt(0)
	s_barrier
	ds_read_b128 v[64:67], v174 offset:32768
	ds_read_b128 v[184:187], v174 offset:36864
	v_exp_f32_e32 v111, v111
	s_waitcnt lgkmcnt(1)
	v_mfma_f32_32x32x16_bf16 v[80:95], v[64:67], v[142:145], v[238:253]
	s_waitcnt lgkmcnt(0)
	v_mfma_f32_32x32x16_bf16 v[64:79], v[184:187], v[142:145], v[238:253]
	ds_read_b128 v[112:115], v175 offset:32768
	ds_read_b128 v[116:119], v175 offset:36864
	v_exp_f32_e32 v120, v102
	v_exp_f32_e32 v121, v103
	v_exp_f32_e32 v122, v104
	v_exp_f32_e32 v123, v105
	v_exp_f32_e32 v124, v106
	v_exp_f32_e32 v125, v107
	s_waitcnt lgkmcnt(1)
	v_mfma_f32_32x32x16_bf16 v[80:95], v[112:115], v[138:141], v[80:95]
	v_exp_f32_e32 v126, v108
	v_exp_f32_e32 v127, v109
	v_exp_f32_e32 v184, v110
	s_waitcnt lgkmcnt(0)
	v_mfma_f32_32x32x16_bf16 v[64:79], v[116:119], v[138:141], v[64:79]
	ds_read_b128 v[112:115], v173 offset:32768
	ds_read_b128 v[116:119], v173 offset:36864
	s_waitcnt lgkmcnt(1)
	v_mfma_f32_32x32x16_bf16 v[80:95], v[112:115], v[134:137], v[80:95]
	s_waitcnt lgkmcnt(0)
	v_mfma_f32_32x32x16_bf16 v[64:79], v[116:119], v[134:137], v[64:79]
	ds_read_b128 v[112:115], v176 offset:32768
	ds_read_b128 v[116:119], v176 offset:36864
	s_waitcnt lgkmcnt(1)
	v_mfma_f32_32x32x16_bf16 v[80:95], v[112:115], v[130:133], v[80:95]
	v_exp_f32_e32 v114, v96
	v_add_f32_e32 v96, 0, v183
	v_add_f32_e32 v96, v190, v96
	v_add_f32_e32 v112, v188, v191
	v_add_f32_e32 v113, v189, v192
	v_add_f32_e32 v96, v193, v96
	v_add_f32_e32 v112, v194, v112
	v_add_f32_e32 v113, v195, v113
	v_add_f32_e32 v96, v196, v96
	v_add_f32_e32 v112, v197, v112
	v_add_f32_e32 v113, v198, v113
	v_add_f32_e32 v96, v199, v96
	v_exp_f32_e32 v115, v97
	v_add_f32_e32 v112, v200, v112
	s_waitcnt lgkmcnt(0)
	v_mfma_f32_32x32x16_bf16 v[64:79], v[116:119], v[130:133], v[64:79]
	v_exp_f32_e32 v116, v98
	v_add_f32_e32 v113, v201, v113
	v_exp_f32_e32 v117, v99
	v_add_f32_e32 v96, v202, v96
	v_exp_f32_e32 v118, v100
	v_add_f32_e32 v112, v114, v112
	v_exp_f32_e32 v119, v101
	v_add_f32_e32 v113, v115, v113
	v_add_f32_e32 v96, v116, v96
	v_add_f32_e32 v112, v117, v112
	v_add_f32_e32 v113, v118, v113
	v_add_f32_e32 v96, v119, v96
	v_add_f32_e32 v112, v120, v112
	v_add_f32_e32 v113, v121, v113
	v_add_f32_e32 v96, v122, v96
	v_add_f32_e32 v112, v123, v112
	v_add_f32_e32 v113, v124, v113
	v_add_f32_e32 v96, v125, v96
	v_add_f32_e32 v112, v126, v112
	v_add_f32_e32 v113, v127, v113
	v_add_f32_e32 v96, v184, v96
	v_add_f32_e32 v112, v111, v112
	v_add_f32_e32 v112, v96, v112
	v_add_f32_e32 v112, v113, v112
	v_mov_b32_e32 v113, v112
	v_cvt_pk_bf16_f32 v96, v183, v188
	v_cvt_pk_bf16_f32 v97, v189, v190
	v_cvt_pk_bf16_f32 v98, v191, v192
	v_cvt_pk_bf16_f32 v99, v193, v194
	v_cvt_pk_bf16_f32 v100, v195, v196
	v_cvt_pk_bf16_f32 v101, v197, v198
	v_cvt_pk_bf16_f32 v102, v199, v200
	v_cvt_pk_bf16_f32 v103, v201, v202
	v_cvt_pk_bf16_f32 v104, v114, v115
	v_cvt_pk_bf16_f32 v105, v116, v117
	v_cvt_pk_bf16_f32 v106, v118, v119
	v_cvt_pk_bf16_f32 v107, v120, v121
	v_cvt_pk_bf16_f32 v108, v122, v123
	v_cvt_pk_bf16_f32 v109, v124, v125
	v_cvt_pk_bf16_f32 v110, v126, v127
	v_cvt_pk_bf16_f32 v111, v184, v111
	s_nop 1
	v_permlane32_swap_b32_e32 v112, v113
	v_permlane32_swap_b32_e32 v96, v98
	v_permlane32_swap_b32_e32 v97, v99
	v_permlane32_swap_b32_e32 v100, v102
	v_permlane32_swap_b32_e32 v101, v103
	v_permlane32_swap_b32_e32 v104, v106
	v_permlane32_swap_b32_e32 v105, v107
	v_permlane32_swap_b32_e32 v108, v110
	v_permlane32_swap_b32_e32 v109, v111
	s_cmp_lt_u32 s3, s58
	s_cselect_b64 s[22:23], -1, 0
	s_cmp_ge_u32 s3, s58
	s_cselect_b64 s[20:21], -1, 0
	s_and_b64 vcc, exec, s[20:21]
	s_cbranch_vccnz .LBB0_346
	s_add_u32 s100, s0, 0x593c000
	s_addc_u32 s101, s1, 0
	global_load_dwordx4 v[146:149], v158, s[100:101] offset:1408
	global_load_dwordx4 v[150:153], v160, s[100:101] offset:2304
	global_load_dwordx4 v[154:157], v162, s[100:101] offset:2304

; __device__ __forceinline__ void finishSM(f32x16& p0, f32x16& p1, float& l_reg, bf16x8& pa0, bf16x8& pa1, bf16x8& pa2, bf16x8& pa3) {
; #pragma unroll
;   for (int r = 0; r < 16; ++r) p1[r] = __builtin_amdgcn_exp2f(p1[r]);
;   float ps = 0;
; #pragma unroll
;   for (int r = 0; r < 16; ++r) ps += p0[r];
; #pragma unroll
;   for (int r = 0; r < 16; ++r) ps += p1[r];
;   { auto rr = __builtin_amdgcn_permlane32_swap(__float_as_uint(ps), __float_as_uint(ps), false, false);
;     ps = __uint_as_float(rr[0]) + __uint_as_float(rr[1]); }
;   l_reg += ps;
;     ...
;   PK4(p0, 0, pa0); PK4(p0, 8, pa1); PK4(p1, 0, pa2); PK4(p1, 8, pa3);
;     ...
; }
; template <int DQK, int QL>
; __device__ __forceinline__ void qkt(f32x16& p0, f32x16& p1, const char* Ks, const bf16x8 (&qr)[DQK / 16 - QL], const char* qlds, const int (&kofs)[4], float negM) {
;   constexpr int QR = DQK / 16 - QL;
; #pragma unroll
;   for (int r = 0; r < 16; ++r) { p0[r] = negM; p1[r] = negM; }
; #pragma unroll
;   for (int d0 = 0; d0 < DQK / 16; ++d0) {
;     const char* kp = Ks + kofs[d0 & 3] + (d0 >> 2) * 128;
;     bf16x8 b0 = *reinterpret_cast<const bf16x8*>(kp);
;     bf16x8 b1 = *reinterpret_cast<const bf16x8*>(kp + 32 * DQK * 2);
;     bf16x8 qf;
;     if constexpr (QL > 0) { if (d0 < QR) qf = qr[d0 < QR ? d0 : 0]; else qf = *reinterpret_cast<const bf16x8*>(qlds + (d0 - QR) * 1024); }
;     else qf = qr[d0];
;     p0 = __builtin_amdgcn_mfma_f32_32x32x16_bf16(b0, qf, p0, 0, 0, 0);
;     p1 = __builtin_amdgcn_mfma_f32_32x32x16_bf16(b1, qf, p1, 0, 0, 0);
;   }
; }
.LBB0_369:
	v_add_f32_e32 v80, 0, v176
	v_add_f32_e32 v80, v177, v80
	v_add_f32_e32 v169, v178, v172
	v_add_f32_e32 v170, v174, v175
	v_add_f32_e32 v80, v171, v80
	v_add_f32_e32 v169, v173, v169
	v_add_f32_e32 v170, v147, v170
	v_add_f32_e32 v80, v149, v80
	v_add_f32_e32 v169, v145, v169
	v_add_f32_e32 v170, v148, v170
	v_exp_f32_e32 v64, v64
	v_add_f32_e32 v80, v143, v80
	v_exp_f32_e32 v65, v65
	v_add_f32_e32 v169, v146, v169
	v_exp_f32_e32 v66, v66
	v_add_f32_e32 v170, v142, v170
	v_exp_f32_e32 v67, v67
	v_add_f32_e32 v80, v144, v80
	v_exp_f32_e32 v68, v68
	v_add_f32_e32 v169, v64, v169
	v_exp_f32_e32 v69, v69
	v_add_f32_e32 v170, v65, v170
	v_exp_f32_e32 v70, v70
	v_add_f32_e32 v80, v66, v80
	v_exp_f32_e32 v71, v71
	v_add_f32_e32 v169, v67, v169
	v_exp_f32_e32 v72, v72
	v_add_f32_e32 v170, v68, v170
	v_exp_f32_e32 v73, v73
	v_add_f32_e32 v80, v69, v80
	v_exp_f32_e32 v74, v74
	v_add_f32_e32 v169, v70, v169
	v_exp_f32_e32 v75, v75
	v_add_f32_e32 v170, v71, v170
	v_exp_f32_e32 v76, v76
	v_add_f32_e32 v80, v72, v80
	v_exp_f32_e32 v77, v77
	v_add_f32_e32 v169, v73, v169
	v_exp_f32_e32 v78, v78
	v_add_f32_e32 v170, v74, v170
	v_exp_f32_e32 v79, v79
	v_add_f32_e32 v80, v75, v80
	v_add_f32_e32 v169, v76, v169
	v_add_f32_e32 v170, v77, v170
	v_add_f32_e32 v80, v78, v80
	v_add_f32_e32 v169, v79, v169
	v_add_f32_e32 v169, v80, v169
	v_add_f32_e32 v169, v170, v169
	v_mov_b32_e32 v170, v169
	s_nop 1
	v_permlane32_swap_b32_e32 v169, v170
	v_cvt_pk_bf16_f32 v120, v176, v178
	v_cvt_pk_bf16_f32 v121, v174, v177
	v_cvt_pk_bf16_f32 v122, v172, v175
	v_cvt_pk_bf16_f32 v123, v171, v173
	v_cvt_pk_bf16_f32 v124, v147, v149
	v_cvt_pk_bf16_f32 v125, v145, v148
	v_cvt_pk_bf16_f32 v126, v143, v146
	v_cvt_pk_bf16_f32 v127, v142, v144
	v_cvt_pk_bf16_f32 v142, v64, v65
	v_cvt_pk_bf16_f32 v143, v66, v67
	v_cvt_pk_bf16_f32 v144, v68, v69
	v_cvt_pk_bf16_f32 v145, v70, v71
	v_cvt_pk_bf16_f32 v146, v72, v73
	v_cvt_pk_bf16_f32 v147, v74, v75
	v_cvt_pk_bf16_f32 v148, v76, v77
	v_cvt_pk_bf16_f32 v149, v78, v79
	s_nop 0
	v_permlane32_swap_b32_e32 v120, v122
	v_permlane32_swap_b32_e32 v121, v123
	v_permlane32_swap_b32_e32 v124, v126
	v_permlane32_swap_b32_e32 v125, v127
	v_permlane32_swap_b32_e32 v142, v144
	v_permlane32_swap_b32_e32 v143, v145
	v_permlane32_swap_b32_e32 v146, v148
	v_permlane32_swap_b32_e32 v147, v149
	ds_read_b128 v[80:83], v152 offset:57344
	ds_read_b128 v[84:87], v152 offset:57472
	v_mov_b64_e32 v[110:111], s[18:19]
	v_mov_b64_e32 v[108:109], s[16:17]
	v_mov_b64_e32 v[106:107], s[14:15]
	v_mov_b64_e32 v[104:105], s[12:13]
	v_mov_b64_e32 v[102:103], s[10:11]
	v_mov_b64_e32 v[100:101], s[8:9]
	v_mov_b64_e32 v[98:99], s[6:7]
	v_mov_b64_e32 v[96:97], s[4:5]
	v_add_u32_e32 v167, v163, v162
	s_waitcnt lgkmcnt(1)
	v_mfma_f32_32x32x16_bf16 v[64:79], v[80:83], v[138:141], v[96:111]
	ds_read_b128 v[80:83], v156 offset:57344
	ds_read_b128 v[88:91], v152 offset:57600
	s_waitcnt lgkmcnt(1)
	v_mfma_f32_32x32x16_bf16 v[64:79], v[80:83], v[134:137], v[64:79]
	ds_read_b128 v[80:83], v155 offset:57344
	ds_read_b128 v[92:95], v155 offset:57472
	s_waitcnt lgkmcnt(1)
	v_mfma_f32_32x32x16_bf16 v[64:79], v[80:83], v[130:133], v[64:79]
	ds_read_b128 v[80:83], v153 offset:57344
	ds_read_b128 v[112:115], v167
	ds_read_b128 v[116:119], v155 offset:57600
	ds_read_b128 v[172:175], v167 offset:1024
	s_waitcnt lgkmcnt(2)
	v_mfma_f32_32x32x16_bf16 v[64:79], v[80:83], v[112:115], v[64:79]
	s_waitcnt lgkmcnt(0)
	v_mfma_f32_32x32x16_bf16 v[64:79], v[84:87], v[172:175], v[64:79]
	ds_read_b128 v[80:83], v156 offset:57472
	ds_read_b128 v[176:179], v167 offset:2048
	ds_read_b128 v[84:87], v156 offset:57600
	ds_read_b128 v[180:183], v167 offset:3072
	s_waitcnt lgkmcnt(2)
	v_mfma_f32_32x32x16_bf16 v[64:79], v[80:83], v[176:179], v[64:79]
	s_waitcnt lgkmcnt(0)
	v_mfma_f32_32x32x16_bf16 v[64:79], v[92:95], v[180:183], v[64:79]
	ds_read_b128 v[80:83], v153 offset:57472
	ds_read_b128 v[184:187], v167 offset:4096
	ds_read_b128 v[188:191], v167 offset:5120
	ds_read_b128 v[92:95], v153 offset:57600
	ds_read_b128 v[192:195], v167 offset:6144
	ds_read_b128 v[196:199], v167 offset:7168
	ds_read_b128 v[200:203], v160 offset:12288
	ds_read_b128 v[204:207], v160 offset:12416
	ds_read_b128 v[208:211], v158 offset:12288
	ds_read_b128 v[212:215], v158 offset:12416
	ds_read_b128 v[216:219], v159 offset:12288
	ds_read_b128 v[220:223], v160 offset:12544
	s_waitcnt lgkmcnt(10)
	v_mfma_f32_32x32x16_bf16 v[64:79], v[80:83], v[184:187], v[64:79]
	s_waitcnt lgkmcnt(9)
	v_mfma_f32_32x32x16_bf16 v[64:79], v[88:91], v[188:191], v[64:79]
	s_waitcnt lgkmcnt(7)
	v_mfma_f32_32x32x16_bf16 v[64:79], v[84:87], v[192:195], v[64:79]
	s_waitcnt lgkmcnt(6)
	v_mfma_f32_32x32x16_bf16 v[64:79], v[116:119], v[196:199], v[64:79]
	ds_read_b128 v[116:119], v159 offset:12416
	ds_read_b128 v[238:241], v159 offset:12544
	ds_read_b128 v[242:245], v167 offset:8192
	ds_read_b128 v[246:249], v157 offset:12288
	ds_read_b128 v[250:253], v158 offset:12544
	ds_read_b128 v[228:231], v157 offset:12416
	ds_read_b128 v[224:227], v157 offset:12544
	s_waitcnt lgkmcnt(4)
	v_mfma_f32_32x32x16_bf16 v[64:79], v[92:95], v[242:245], v[64:79]
	v_mfma_f32_32x32x16_bf16 v[80:95], v[200:203], v[138:141], v[96:111]
	v_mov_b32_e32 v171, v161
	s_add_u32 s72, s55, s0
	s_addc_u32 s73, s83, s1
	v_mfma_f32_32x32x16_bf16 v[80:95], v[216:219], v[134:137], v[80:95]
	v_mfma_f32_32x32x16_bf16 v[80:95], v[208:211], v[130:133], v[80:95]
	s_waitcnt lgkmcnt(3)
; #define WAIT_L0() asm volatile("s_waitcnt lgkmcnt(0)" ::: "memory")
; #define SBAR() __builtin_amdgcn_sched_barrier(0)
; template <int NCB, int D0> __device__ __forceinline__ void pv_one(f32x16& od, int vb, bf16x8 pa0, bf16x8 pa1, bf16x8 pa2, bf16x8 pa3) {
;   constexpr int KSTEP = NCB * 1024, HALF = NCB * 512, B0 = D0 * 512;
;   const s16x4 l0 = tr_read<B0>(vb), h0 = tr_read<B0 + HALF>(vb), l1 = tr_read<B0 + KSTEP>(vb), h1 = tr_read<B0 + KSTEP + HALF>(vb);
;   const s16x4 l2 = tr_read<B0 + 2 * KSTEP>(vb), h2 = tr_read<B0 + 2 * KSTEP + HALF>(vb), l3 = tr_read<B0 + 3 * KSTEP>(vb), h3 = tr_read<B0 + 3 * KSTEP + HALF>(vb);
;   WAIT_L0(); SBAR();
;     ...
;   od = __builtin_amdgcn_mfma_f32_32x32x16_bf16(pa0, PK(l0, h0), od, 0, 0, 0);
;   od = __builtin_amdgcn_mfma_f32_32x32x16_bf16(pa1, PK(l1, h1), od, 0, 0, 0);
;   od = __builtin_amdgcn_mfma_f32_32x32x16_bf16(pa2, PK(l2, h2), od, 0, 0, 0);
;   od = __builtin_amdgcn_mfma_f32_32x32x16_bf16(pa3, PK(l3, h3), od, 0, 0, 0);
;     ...
; }
; template <int NCB> __device__ __forceinline__ void pv_all(f32x16 (&o)[NCB], int vb, bf16x8 pa0, bf16x8 pa1, bf16x8 pa2, bf16x8 pa3) {
;   pv_one<NCB, 0>(o[0], vb, pa0, pa1, pa2, pa3); pv_one<NCB, 1>(o[1], vb, pa0, pa1, pa2, pa3);
;   if constexpr (NCB == 4) { pv_one<NCB, 2>(o[2], vb, pa0, pa1, pa2, pa3); pv_one<NCB, 3>(o[3], vb, pa0, pa1, pa2, pa3); }
; }
	v_mfma_f32_32x32x16_bf16 v[80:95], v[246:249], v[112:115], v[80:95]
	v_mfma_f32_32x32x16_bf16 v[80:95], v[204:207], v[172:175], v[80:95]
	s_add_u32 s74, s36, s0
	s_addc_u32 s75, s54, s1
	s_add_u32 s100, s72, s46
	s_addc_u32 s101, s73, s47
	v_readfirstlane_b32 s20, v164
	s_mov_b32 m0, s20
	s_nop 0
	global_load_lds_dwordx4 v235, s[100:101]
	v_readfirstlane_b32 s20, v165
	s_mov_b32 m0, s20
	s_nop 0
	global_load_lds_dwordx4 v236, s[100:101]
	v_readfirstlane_b32 s20, v166
	s_mov_b32 m0, s20
	s_nop 0
	global_load_lds_dwordx4 v237, s[100:101]
	v_mfma_f32_32x32x16_bf16 v[80:95], v[116:119], v[176:179], v[80:95]
	s_add_u32 s100, s74, s25
	s_addc_u32 s101, s75, 0
	global_load_dwordx4 v[112:115], v232, s[100:101] offset:256
	s_add_u32 s100, s100, 0x8000
	s_addc_u32 s101, s101, 0
	global_load_dwordx4 v[116:119], v232, s[100:101] offset:256
	v_mfma_f32_32x32x16_bf16 v[80:95], v[212:215], v[180:183], v[80:95]
	s_waitcnt lgkmcnt(0)
	v_mfma_f32_32x32x16_bf16 v[80:95], v[228:231], v[184:187], v[80:95]
	v_mfma_f32_32x32x16_bf16 v[80:95], v[220:223], v[188:191], v[80:95]
	v_mfma_f32_32x32x16_bf16 v[80:95], v[238:241], v[192:195], v[80:95]
	v_mfma_f32_32x32x16_bf16 v[80:95], v[250:253], v[196:199], v[80:95]
	v_mfma_f32_32x32x16_bf16 v[80:95], v[224:227], v[242:245], v[80:95]
	ds_read_b64_tr_b16 v[96:97], v151 offset:0
	ds_read_b64_tr_b16 v[98:99], v151 offset:0x800
	ds_read_b64_tr_b16 v[100:101], v151 offset:0x1000
	ds_read_b64_tr_b16 v[102:103], v151 offset:0x1800
	ds_read_b64_tr_b16 v[104:105], v151 offset:0x2000
	ds_read_b64_tr_b16 v[106:107], v151 offset:0x2800
	ds_read_b64_tr_b16 v[108:109], v151 offset:0x3000
	ds_read_b64_tr_b16 v[110:111], v151 offset:0x3800
	s_nop 0
	s_waitcnt lgkmcnt(6)
	v_mfma_f32_32x32x16_bf16 v[0:15], v[120:123], v[96:99], v[0:15]
	ds_read_b64_tr_b16 v[96:97], v151 offset:0x200
	ds_read_b64_tr_b16 v[98:99], v151 offset:0xa00
	s_waitcnt lgkmcnt(6)
	v_mfma_f32_32x32x16_bf16 v[0:15], v[124:127], v[100:103], v[0:15]
	ds_read_b64_tr_b16 v[100:101], v151 offset:0x1200
	ds_read_b64_tr_b16 v[102:103], v151 offset:0x1a00
	s_waitcnt lgkmcnt(6)
	v_mfma_f32_32x32x16_bf16 v[0:15], v[142:145], v[104:107], v[0:15]
	ds_read_b64_tr_b16 v[104:105], v151 offset:0x2200
	ds_read_b64_tr_b16 v[106:107], v151 offset:0x2a00
	s_waitcnt lgkmcnt(6)
	v_mfma_f32_32x32x16_bf16 v[0:15], v[146:149], v[108:111], v[0:15]
	ds_read_b64_tr_b16 v[108:109], v151 offset:0x3200
	ds_read_b64_tr_b16 v[110:111], v151 offset:0x3a00
	s_waitcnt lgkmcnt(6)
	v_mfma_f32_32x32x16_bf16 v[16:31], v[120:123], v[96:99], v[16:31]
	ds_read_b64_tr_b16 v[96:97], v151 offset:0x400
	ds_read_b64_tr_b16 v[98:99], v151 offset:0xc00
	s_waitcnt lgkmcnt(6)
	v_mfma_f32_32x32x16_bf16 v[16:31], v[124:127], v[100:103], v[16:31]
	ds_read_b64_tr_b16 v[100:101], v151 offset:0x1400
	ds_read_b64_tr_b16 v[102:103], v151 offset:0x1c00
	s_waitcnt lgkmcnt(6)
	v_mfma_f32_32x32x16_bf16 v[16:31], v[142:145], v[104:107], v[16:31]
	ds_read_b64_tr_b16 v[104:105], v151 offset:0x2400
	ds_read_b64_tr_b16 v[106:107], v151 offset:0x2c00
	s_waitcnt lgkmcnt(6)
	v_mfma_f32_32x32x16_bf16 v[16:31], v[146:149], v[108:111], v[16:31]
	ds_read_b64_tr_b16 v[108:109], v151 offset:0x3400
	ds_read_b64_tr_b16 v[110:111], v151 offset:0x3c00
	s_waitcnt lgkmcnt(6)
	v_mfma_f32_32x32x16_bf16 v[32:47], v[120:123], v[96:99], v[32:47]
	ds_read_b64_tr_b16 v[96:97], v151 offset:0x600
	ds_read_b64_tr_b16 v[98:99], v151 offset:0xe00
	s_waitcnt lgkmcnt(6)
	v_mfma_f32_32x32x16_bf16 v[32:47], v[124:127], v[100:103], v[32:47]
	ds_read_b64_tr_b16 v[100:101], v151 offset:0x1600
	ds_read_b64_tr_b16 v[102:103], v151 offset:0x1e00
	s_waitcnt lgkmcnt(6)
	v_mfma_f32_32x32x16_bf16 v[32:47], v[142:145], v[104:107], v[32:47]
	ds_read_b64_tr_b16 v[104:105], v151 offset:0x2600
	ds_read_b64_tr_b16 v[106:107], v151 offset:0x2e00
	s_waitcnt lgkmcnt(6)
	v_mfma_f32_32x32x16_bf16 v[32:47], v[146:149], v[108:111], v[32:47]
	ds_read_b64_tr_b16 v[108:109], v151 offset:0x3600
	ds_read_b64_tr_b16 v[110:111], v151 offset:0x3e00
	s_waitcnt lgkmcnt(6)
	v_mfma_f32_32x32x16_bf16 v[48:63], v[120:123], v[96:99], v[48:63]
	s_add_i32 s20, s87, 64
	s_cmp_le_i32 s20, s59
	v_add_u32_e32 v171, s87, v154
	s_waitcnt lgkmcnt(4)
	v_mfma_f32_32x32x16_bf16 v[48:63], v[124:127], v[100:103], v[48:63]
	s_waitcnt lgkmcnt(2)
	v_mfma_f32_32x32x16_bf16 v[48:63], v[142:145], v[104:107], v[48:63]
	s_waitcnt lgkmcnt(0)
	v_mfma_f32_32x32x16_bf16 v[48:63], v[146:149], v[108:111], v[48:63]
	s_cbranch_scc1 .LBB0_371
; __device__ __forceinline__ int crow(int r, int hi) { return (r & 3) + 8 * (r >> 2) + 4 * hi; }
; template <bool GM>
; __device__ __forceinline__ void partialSM(f32x16& p0, f32x16& p1, bool mask, int kbase, int L, int qpos, int hi) {
;   if (mask) {
; #pragma unroll
;     for (int r = 0; r < 16; ++r) {
;       int k = kbase + crow(r, hi);
;       asm volatile("" : "+v"(k) : "v"(p0[r]));
;       bool ok = k < L;
;       if (GM) ok = ok && (k < 16 || abs(qpos - k) <= 128);
;       p0[r] = ok ? p0[r] : -1e30f;
;       int k2 = k + 32;
;       asm volatile("" : "+v"(k2) : "v"(p1[r]));
;       bool ok2 = k2 < L;
;       if (GM) ok2 = ok2 && (k2 < 16 || abs(qpos - k2) <= 128);
;       p1[r] = ok2 ? p1[r] : -1e30f;
;     }
;   }
; #pragma unroll
;   for (int r = 0; r < 16; ++r) p0[r] = __builtin_amdgcn_exp2f(p0[r]);
	v_add_u32_e32 v96, 64, v171
	s_nop 0
	v_cmp_gt_i32_e32 vcc, s94, v96
	v_add_u32_e32 v96, 32, v96
	s_nop 0
	v_cndmask_b32_e32 v64, v233, v64, vcc
	v_cmp_gt_i32_e32 vcc, s94, v96
	v_add_u32_e32 v96, 0x41, v171
	s_nop 0
	v_cndmask_b32_e32 v80, v233, v80, vcc
	v_cmp_gt_i32_e32 vcc, s94, v96
	v_add_u32_e32 v96, 32, v96
	s_nop 0
	v_cndmask_b32_e32 v65, v233, v65, vcc
	v_cmp_gt_i32_e32 vcc, s94, v96
	v_add_u32_e32 v96, 0x42, v171
	s_nop 0
	v_cndmask_b32_e32 v81, v233, v81, vcc
	v_cmp_gt_i32_e32 vcc, s94, v96
	v_add_u32_e32 v96, 32, v96
	s_nop 0
	v_cndmask_b32_e32 v66, v233, v66, vcc
	v_cmp_gt_i32_e32 vcc, s94, v96
	v_add_u32_e32 v96, 0x43, v171
	s_nop 0
	v_cndmask_b32_e32 v82, v233, v82, vcc
	v_cmp_gt_i32_e32 vcc, s94, v96
	v_add_u32_e32 v96, 32, v96
	s_nop 0
	v_cndmask_b32_e32 v67, v233, v67, vcc
	v_cmp_gt_i32_e32 vcc, s94, v96
	v_add_u32_e32 v96, 0x48, v171
	s_nop 0
	v_cndmask_b32_e32 v83, v233, v83, vcc
	v_cmp_gt_i32_e32 vcc, s94, v96
	v_add_u32_e32 v96, 32, v96
	s_nop 0
	v_cndmask_b32_e32 v68, v233, v68, vcc
	v_cmp_gt_i32_e32 vcc, s94, v96
	v_add_u32_e32 v96, 0x49, v171
	s_nop 0
	v_cndmask_b32_e32 v84, v233, v84, vcc
	v_cmp_gt_i32_e32 vcc, s94, v96
	v_add_u32_e32 v96, 32, v96
	s_nop 0
	v_cndmask_b32_e32 v69, v233, v69, vcc
	v_cmp_gt_i32_e32 vcc, s94, v96
	v_add_u32_e32 v96, 0x4a, v171
	s_nop 0
	v_cndmask_b32_e32 v85, v233, v85, vcc
	v_cmp_gt_i32_e32 vcc, s94, v96
	v_add_u32_e32 v96, 32, v96
	s_nop 0
	v_cndmask_b32_e32 v70, v233, v70, vcc
	v_cmp_gt_i32_e32 vcc, s94, v96
	v_add_u32_e32 v96, 0x4b, v171
	s_nop 0
	v_cndmask_b32_e32 v86, v233, v86, vcc
	v_cmp_gt_i32_e32 vcc, s94, v96
	v_add_u32_e32 v96, 32, v96
	s_nop 0
	v_cndmask_b32_e32 v71, v233, v71, vcc
	v_cmp_gt_i32_e32 vcc, s94, v96
	v_add_u32_e32 v96, 0x50, v171
	s_nop 0
	v_cndmask_b32_e32 v87, v233, v87, vcc
	v_cmp_gt_i32_e32 vcc, s94, v96
	v_add_u32_e32 v96, 32, v96
	s_nop 0
	v_cndmask_b32_e32 v72, v233, v72, vcc
	v_cmp_gt_i32_e32 vcc, s94, v96
	v_add_u32_e32 v96, 0x51, v171
	s_nop 0
	v_cndmask_b32_e32 v88, v233, v88, vcc
	v_cmp_gt_i32_e32 vcc, s94, v96
	v_add_u32_e32 v96, 32, v96
	s_nop 0
	v_cndmask_b32_e32 v73, v233, v73, vcc
	v_cmp_gt_i32_e32 vcc, s94, v96
	v_add_u32_e32 v96, 0x52, v171
	s_nop 0
	v_cndmask_b32_e32 v89, v233, v89, vcc
	v_cmp_gt_i32_e32 vcc, s94, v96
	v_add_u32_e32 v96, 32, v96
	s_nop 0
	v_cndmask_b32_e32 v74, v233, v74, vcc
	v_cmp_gt_i32_e32 vcc, s94, v96
	v_add_u32_e32 v96, 0x53, v171
	s_nop 0
	v_cndmask_b32_e32 v90, v233, v90, vcc
	v_cmp_gt_i32_e32 vcc, s94, v96
	v_add_u32_e32 v96, 32, v96
	s_nop 0
	v_cndmask_b32_e32 v75, v233, v75, vcc
	v_cmp_gt_i32_e32 vcc, s94, v96
	v_add_u32_e32 v96, 0x58, v171
	s_nop 0
	v_cndmask_b32_e32 v91, v233, v91, vcc
	v_cmp_gt_i32_e32 vcc, s94, v96
	v_add_u32_e32 v96, 32, v96
	s_nop 0
	v_cndmask_b32_e32 v76, v233, v76, vcc
	v_cmp_gt_i32_e32 vcc, s94, v96
	v_add_u32_e32 v96, 0x59, v171
	s_nop 0
	v_cndmask_b32_e32 v92, v233, v92, vcc
	v_cmp_gt_i32_e32 vcc, s94, v96
	v_add_u32_e32 v96, 32, v96
	s_nop 0
	v_cndmask_b32_e32 v77, v233, v77, vcc
	v_cmp_gt_i32_e32 vcc, s94, v96
	v_add_u32_e32 v96, 0x5a, v171
	s_nop 0
	v_cndmask_b32_e32 v93, v233, v93, vcc
	v_cmp_gt_i32_e32 vcc, s94, v96
	v_add_u32_e32 v96, 32, v96
	s_nop 0
	v_cndmask_b32_e32 v78, v233, v78, vcc
	v_cmp_gt_i32_e32 vcc, s94, v96
	v_add_u32_e32 v96, 0x5b, v171
	s_nop 0
	v_cndmask_b32_e32 v94, v233, v94, vcc
	v_cmp_gt_i32_e32 vcc, s94, v96
	v_add_u32_e32 v96, 32, v96
	s_nop 0
	v_cndmask_b32_e32 v79, v233, v79, vcc
	v_cmp_gt_i32_e32 vcc, s94, v96
	s_nop 1
	v_cndmask_b32_e32 v95, v233, v95, vcc
.LBB0_371:
	v_mov_b32_e32 v96, v161
	v_ashrrev_i32_e32 v97, 4, v96
	v_and_b32_e32 v99, 0xfffff0, v97
	v_lshlrev_b32_e32 v100, 1, v97
	v_add_u32_e32 v98, 32, v97
	v_and_or_b32 v99, v100, 8, v99
	v_lshrrev_b32_e32 v100, 1, v97
	v_and_b32_e32 v97, 3, v97
	v_and_or_b32 v97, v100, 4, v97
	v_and_b32_e32 v100, 0xfffff0, v98
	v_lshlrev_b32_e32 v98, 1, v98
	v_and_or_b32 v98, v98, 8, v100
	v_lshrrev_b32_e32 v99, 1, v99
	v_bfe_u32 v101, v96, 2, 2
	v_lshrrev_b32_e32 v98, 1, v98
	v_or_b32_e32 v99, v99, v101
	v_lshlrev_b32_e32 v96, 4, v96
	v_or_b32_e32 v98, v98, v101
	v_lshlrev_b32_e32 v99, 9, v99
	v_lshlrev_b32_e32 v97, 6, v97
	v_and_b32_e32 v96, 48, v96
	v_lshlrev_b32_e32 v98, 9, v98
	v_or3_b32 v99, v99, v97, v96
	v_or3_b32 v96, v98, v97, v96
	s_waitcnt vmcnt(0)
	s_barrier
	s_waitcnt vmcnt(0)
	ds_write_b128 v99, v[112:115]
	ds_write_b128 v96, v[116:119]
	v_exp_f32_e32 v64, v64
	v_exp_f32_e32 v66, v66
	v_exp_f32_e32 v68, v68
	v_exp_f32_e32 v70, v70
	v_exp_f32_e32 v72, v72
	v_exp_f32_e32 v74, v74
	v_exp_f32_e32 v76, v76
	v_exp_f32_e32 v78, v78
	v_exp_f32_e32 v65, v65
	v_exp_f32_e32 v67, v67
	v_exp_f32_e32 v69, v69
	v_exp_f32_e32 v71, v71
	v_exp_f32_e32 v73, v73
	v_exp_f32_e32 v75, v75
	v_exp_f32_e32 v77, v77
	v_exp_f32_e32 v79, v79
	s_waitcnt lgkmcnt(0)
	s_barrier
; __device__ __forceinline__ void finishSM(f32x16& p0, f32x16& p1, float& l_reg, bf16x8& pa0, bf16x8& pa1, bf16x8& pa2, bf16x8& pa3) {
; #pragma unroll
;   for (int r = 0; r < 16; ++r) p1[r] = __builtin_amdgcn_exp2f(p1[r]);
;   float ps = 0;
; #pragma unroll
;   for (int r = 0; r < 16; ++r) ps += p0[r];
; #pragma unroll
;   for (int r = 0; r < 16; ++r) ps += p1[r];
;   { auto rr = __builtin_amdgcn_permlane32_swap(__float_as_uint(ps), __float_as_uint(ps), false, false);
;     ps = __uint_as_float(rr[0]) + __uint_as_float(rr[1]); }
;   l_reg += ps;
;     ...
;   PK4(p0, 0, pa0); PK4(p0, 8, pa1); PK4(p1, 0, pa2); PK4(p1, 8, pa3);
;     ...
; }
; template <int DQK, int QL>
; __device__ __forceinline__ void qkt(f32x16& p0, f32x16& p1, const char* Ks, const bf16x8 (&qr)[DQK / 16 - QL], const char* qlds, const int (&kofs)[4], float negM) {
;   constexpr int QR = DQK / 16 - QL;
; #pragma unroll
;   for (int r = 0; r < 16; ++r) { p0[r] = negM; p1[r] = negM; }
; #pragma unroll
;   for (int d0 = 0; d0 < DQK / 16; ++d0) {
;     const char* kp = Ks + kofs[d0 & 3] + (d0 >> 2) * 128;
;     bf16x8 b0 = *reinterpret_cast<const bf16x8*>(kp);
;     bf16x8 b1 = *reinterpret_cast<const bf16x8*>(kp + 32 * DQK * 2);
;     bf16x8 qf;
;     if constexpr (QL > 0) { if (d0 < QR) qf = qr[d0 < QR ? d0 : 0]; else qf = *reinterpret_cast<const bf16x8*>(qlds + (d0 - QR) * 1024); }
;     else qf = qr[d0];
;     p0 = __builtin_amdgcn_mfma_f32_32x32x16_bf16(b0, qf, p0, 0, 0, 0);
;     p1 = __builtin_amdgcn_mfma_f32_32x32x16_bf16(b1, qf, p1, 0, 0, 0);
;   }
; }
	v_add_f32_e32 v96, 0, v64
	v_add_f32_e32 v96, v67, v96
	v_add_f32_e32 v179, v65, v68
	v_add_f32_e32 v180, v66, v69
	v_add_f32_e32 v96, v70, v96
	v_add_f32_e32 v179, v71, v179
	v_add_f32_e32 v180, v72, v180
	v_add_f32_e32 v96, v73, v96
	v_add_f32_e32 v179, v74, v179
	v_add_f32_e32 v180, v75, v180
	v_exp_f32_e32 v80, v80
	v_add_f32_e32 v96, v76, v96
	v_exp_f32_e32 v81, v81
	v_add_f32_e32 v179, v77, v179
	v_exp_f32_e32 v82, v82
	v_add_f32_e32 v180, v78, v180
	v_exp_f32_e32 v83, v83
	v_add_f32_e32 v96, v79, v96
	v_exp_f32_e32 v84, v84
	v_add_f32_e32 v179, v80, v179
	v_exp_f32_e32 v85, v85
	v_add_f32_e32 v180, v81, v180
	v_exp_f32_e32 v86, v86
	v_add_f32_e32 v96, v82, v96
	v_exp_f32_e32 v87, v87
	v_add_f32_e32 v179, v83, v179
	v_exp_f32_e32 v88, v88
	v_add_f32_e32 v180, v84, v180
	v_exp_f32_e32 v89, v89
	v_add_f32_e32 v96, v85, v96
	v_exp_f32_e32 v90, v90
	v_add_f32_e32 v179, v86, v179
	v_exp_f32_e32 v91, v91
	v_add_f32_e32 v180, v87, v180
	v_exp_f32_e32 v92, v92
	v_add_f32_e32 v96, v88, v96
	v_exp_f32_e32 v93, v93
	v_add_f32_e32 v179, v89, v179
	v_exp_f32_e32 v94, v94
	v_add_f32_e32 v180, v90, v180
	v_exp_f32_e32 v95, v95
	v_add_f32_e32 v96, v91, v96
	v_add_f32_e32 v179, v92, v179
	v_add_f32_e32 v180, v93, v180
	v_add_f32_e32 v96, v94, v96
	v_add_f32_e32 v179, v95, v179
	v_add_f32_e32 v179, v96, v179
	v_add_f32_e32 v179, v180, v179
	v_mov_b32_e32 v180, v179
	v_cvt_pk_bf16_f32 v120, v64, v65
	v_cvt_pk_bf16_f32 v121, v66, v67
	v_cvt_pk_bf16_f32 v122, v68, v69
	v_cvt_pk_bf16_f32 v123, v70, v71
	v_cvt_pk_bf16_f32 v124, v72, v73
	v_cvt_pk_bf16_f32 v125, v74, v75
	v_cvt_pk_bf16_f32 v126, v76, v77
	v_cvt_pk_bf16_f32 v127, v78, v79
	v_cvt_pk_bf16_f32 v142, v80, v81
	v_cvt_pk_bf16_f32 v143, v82, v83
	v_cvt_pk_bf16_f32 v144, v84, v85
	v_cvt_pk_bf16_f32 v145, v86, v87
	v_cvt_pk_bf16_f32 v146, v88, v89
	v_cvt_pk_bf16_f32 v147, v90, v91
	v_cvt_pk_bf16_f32 v148, v92, v93
	v_cvt_pk_bf16_f32 v149, v94, v95
	s_nop 1
	v_permlane32_swap_b32_e32 v179, v180
	v_permlane32_swap_b32_e32 v120, v122
	v_permlane32_swap_b32_e32 v121, v123
	v_permlane32_swap_b32_e32 v124, v126
	v_permlane32_swap_b32_e32 v125, v127
	v_permlane32_swap_b32_e32 v142, v144
	v_permlane32_swap_b32_e32 v143, v145
	v_permlane32_swap_b32_e32 v146, v148
	v_permlane32_swap_b32_e32 v147, v149
	ds_read_b128 v[64:67], v152 offset:32768
	ds_read_b128 v[172:175], v152 offset:45056
	v_mov_b64_e32 v[110:111], s[18:19]
	v_mov_b64_e32 v[108:109], s[16:17]
	v_mov_b64_e32 v[106:107], s[14:15]
	v_mov_b64_e32 v[104:105], s[12:13]
	v_mov_b64_e32 v[102:103], s[10:11]
	v_mov_b64_e32 v[100:101], s[8:9]
	v_mov_b64_e32 v[98:99], s[6:7]
	v_mov_b64_e32 v[96:97], s[4:5]
	s_waitcnt lgkmcnt(1)
	s_nop 0
	v_mfma_f32_32x32x16_bf16 v[80:95], v[64:67], v[138:141], v[96:111]
	s_waitcnt lgkmcnt(0)
	v_mfma_f32_32x32x16_bf16 v[64:79], v[172:175], v[138:141], v[96:111]
	s_nop 6
	ds_read_b128 v[96:99], v156 offset:32768
	ds_read_b128 v[100:103], v156 offset:45056
	s_waitcnt lgkmcnt(1)
	v_mfma_f32_32x32x16_bf16 v[80:95], v[96:99], v[134:137], v[80:95]
	s_waitcnt lgkmcnt(0)
	v_mfma_f32_32x32x16_bf16 v[64:79], v[100:103], v[134:137], v[64:79]
	ds_read_b128 v[96:99], v155 offset:32768
	ds_read_b128 v[100:103], v155 offset:45056
	s_waitcnt lgkmcnt(1)
	v_mfma_f32_32x32x16_bf16 v[80:95], v[96:99], v[130:133], v[80:95]
	s_waitcnt lgkmcnt(0)
	v_mfma_f32_32x32x16_bf16 v[64:79], v[100:103], v[130:133], v[64:79]
	ds_read_b128 v[96:99], v153 offset:32768
	ds_read_b128 v[100:103], v153 offset:45056
	ds_read_b128 v[104:107], v167
	s_waitcnt lgkmcnt(0)
	v_mfma_f32_32x32x16_bf16 v[80:95], v[96:99], v[104:107], v[80:95]
	v_mfma_f32_32x32x16_bf16 v[64:79], v[100:103], v[104:107], v[64:79]
	ds_read_b128 v[96:99], v152 offset:32896
	ds_read_b128 v[100:103], v152 offset:45184
	ds_read_b128 v[104:107], v167 offset:1024
	s_waitcnt lgkmcnt(0)
	v_mfma_f32_32x32x16_bf16 v[80:95], v[96:99], v[104:107], v[80:95]
	v_mfma_f32_32x32x16_bf16 v[64:79], v[100:103], v[104:107], v[64:79]
	ds_read_b128 v[96:99], v156 offset:32896
	ds_read_b128 v[100:103], v156 offset:45184
	ds_read_b128 v[104:107], v167 offset:2048
	s_waitcnt lgkmcnt(0)
	v_mfma_f32_32x32x16_bf16 v[80:95], v[96:99], v[104:107], v[80:95]
	v_mfma_f32_32x32x16_bf16 v[64:79], v[100:103], v[104:107], v[64:79]
	ds_read_b128 v[96:99], v155 offset:32896
	ds_read_b128 v[100:103], v155 offset:45184
	ds_read_b128 v[104:107], v167 offset:3072
	s_waitcnt lgkmcnt(0)
	v_mfma_f32_32x32x16_bf16 v[80:95], v[96:99], v[104:107], v[80:95]
	v_mfma_f32_32x32x16_bf16 v[64:79], v[100:103], v[104:107], v[64:79]
	ds_read_b128 v[96:99], v153 offset:32896
	ds_read_b128 v[100:103], v153 offset:45184
	ds_read_b128 v[104:107], v167 offset:4096
	s_waitcnt lgkmcnt(0)
	v_mfma_f32_32x32x16_bf16 v[80:95], v[96:99], v[104:107], v[80:95]
	v_mfma_f32_32x32x16_bf16 v[64:79], v[100:103], v[104:107], v[64:79]
	ds_read_b128 v[96:99], v152 offset:33024
	ds_read_b128 v[100:103], v152 offset:45312
	ds_read_b128 v[104:107], v167 offset:5120
	s_waitcnt lgkmcnt(0)
	v_mfma_f32_32x32x16_bf16 v[80:95], v[96:99], v[104:107], v[80:95]
	v_mfma_f32_32x32x16_bf16 v[64:79], v[100:103], v[104:107], v[64:79]
	ds_read_b128 v[96:99], v156 offset:33024
	ds_read_b128 v[100:103], v156 offset:45312
	ds_read_b128 v[104:107], v167 offset:6144
	s_waitcnt lgkmcnt(0)
	v_mfma_f32_32x32x16_bf16 v[80:95], v[96:99], v[104:107], v[80:95]
	v_mfma_f32_32x32x16_bf16 v[64:79], v[100:103], v[104:107], v[64:79]
	ds_read_b128 v[96:99], v155 offset:33024
	ds_read_b128 v[100:103], v155 offset:45312
	ds_read_b128 v[104:107], v167 offset:7168
	s_waitcnt lgkmcnt(0)
	v_mfma_f32_32x32x16_bf16 v[80:95], v[96:99], v[104:107], v[80:95]
	v_mfma_f32_32x32x16_bf16 v[64:79], v[100:103], v[104:107], v[64:79]
	ds_read_b128 v[96:99], v153 offset:33024
	ds_read_b128 v[100:103], v153 offset:45312
	ds_read_b128 v[104:107], v167 offset:8192
	s_waitcnt lgkmcnt(0)
	v_mfma_f32_32x32x16_bf16 v[80:95], v[96:99], v[104:107], v[80:95]
	v_mfma_f32_32x32x16_bf16 v[64:79], v[100:103], v[104:107], v[64:79]
	s_cmp_lt_u32 s3, s58
	s_cselect_b64 s[22:23], -1, 0
	s_cmp_ge_u32 s3, s58
	s_cselect_b64 s[20:21], -1, 0
	s_and_b64 vcc, exec, s[20:21]
	s_cbranch_vccnz .LBB0_373
	s_add_u32 s100, s72, s48
	s_addc_u32 s101, s73, s49
	v_readfirstlane_b32 s38, v168
	s_mov_b32 m0, s38
	s_nop 0
	global_load_lds_dwordx4 v235, s[100:101]
	s_add_i32 m0, s38, 0x2000
	s_nop 0
	global_load_lds_dwordx4 v236, s[100:101]
	s_add_i32 m0, s38, 0x4000
	s_nop 0
	global_load_lds_dwordx4 v237, s[100:101]
	s_add_u32 s100, s74, 0xd2bc000
	s_addc_u32 s101, s75, 0
	global_load_dwordx4 v[112:115], v232, s[100:101] offset:256
	s_add_u32 s100, s100, 0x8000
	s_addc_u32 s101, s101, 0
	global_load_dwordx4 v[116:119], v232, s[100:101] offset:256

; __device__ __forceinline__ void finishSM(f32x16& p0, f32x16& p1, float& l_reg, bf16x8& pa0, bf16x8& pa1, bf16x8& pa2, bf16x8& pa3) {
; #pragma unroll
;   for (int r = 0; r < 16; ++r) p1[r] = __builtin_amdgcn_exp2f(p1[r]);
;   float ps = 0;
; #pragma unroll
;   for (int r = 0; r < 16; ++r) ps += p0[r];
; #pragma unroll
;   for (int r = 0; r < 16; ++r) ps += p1[r];
;   { auto rr = __builtin_amdgcn_permlane32_swap(__float_as_uint(ps), __float_as_uint(ps), false, false);
;     ps = __uint_as_float(rr[0]) + __uint_as_float(rr[1]); }
;   l_reg += ps;
;     ...
;   PK4(p0, 0, pa0); PK4(p0, 8, pa1); PK4(p1, 0, pa2); PK4(p1, 8, pa3);
;     ...
; }
; template <int DQK, int QL>
; __device__ __forceinline__ void qkt(f32x16& p0, f32x16& p1, const char* Ks, const bf16x8 (&qr)[DQK / 16 - QL], const char* qlds, const int (&kofs)[4], float negM) {
;   constexpr int QR = DQK / 16 - QL;
; #pragma unroll
;   for (int r = 0; r < 16; ++r) { p0[r] = negM; p1[r] = negM; }
; #pragma unroll
;   for (int d0 = 0; d0 < DQK / 16; ++d0) {
;     const char* kp = Ks + kofs[d0 & 3] + (d0 >> 2) * 128;
;     bf16x8 b0 = *reinterpret_cast<const bf16x8*>(kp);
;     bf16x8 b1 = *reinterpret_cast<const bf16x8*>(kp + 32 * DQK * 2);
;     bf16x8 qf;
;     if constexpr (QL > 0) { if (d0 < QR) qf = qr[d0 < QR ? d0 : 0]; else qf = *reinterpret_cast<const bf16x8*>(qlds + (d0 - QR) * 1024); }
;     else qf = qr[d0];
;     p0 = __builtin_amdgcn_mfma_f32_32x32x16_bf16(b0, qf, p0, 0, 0, 0);
;     p1 = __builtin_amdgcn_mfma_f32_32x32x16_bf16(b1, qf, p1, 0, 0, 0);
;   }
; }
; template <int NCB> __device__ __forceinline__ int v_st(int k, int c) {
;   const int kk = (k & ~0xC) | ((k & 4) << 1) | ((k & 8) >> 1);
;   return ((kk >> 3) * NCB + (c >> 5)) * 512 + ((kk & 7) * 32 + (c & 31)) * 2;
; }
; __device__ __forceinline__ int v_rd_base(int lane) { return ((lane & 3) << 3) | (((lane >> 2) & 3) << 6) | (((lane >> 4) & 1) << 5) | (((lane >> 5) & 1) << 8); }
; template <int OFF> __device__ __forceinline__ s16x4 tr_read(int vb) {
;   s16x4 r; asm volatile("ds_read_b64_tr_b16 %0, %1 offset:%2" : "=&v"(r) : "v"(vb), "i"(OFF) : "memory"); return r;
; }
; template <int NCB, int D0> __device__ __forceinline__ void pv_one(f32x16& od, int vb, bf16x8 pa0, bf16x8 pa1, bf16x8 pa2, bf16x8 pa3) {
;   constexpr int KSTEP = NCB * 1024, HALF = NCB * 512, B0 = D0 * 512;
.LBB0_398:
	ds_read_b128 v[96:99], v169 offset:40960
	s_waitcnt vmcnt(0)
	ds_read_b128 v[154:157], v169 offset:45056
	v_mov_b64_e32 v[126:127], s[18:19]
	v_mov_b64_e32 v[124:125], s[16:17]
	v_mov_b64_e32 v[122:123], s[14:15]
	v_mov_b64_e32 v[120:121], s[12:13]
	v_mov_b64_e32 v[118:119], s[10:11]
	v_mov_b64_e32 v[116:117], s[8:9]
	v_mov_b64_e32 v[114:115], s[6:7]
	v_mov_b64_e32 v[112:113], s[4:5]
	v_exp_f32_e32 v100, v68
	v_exp_f32_e32 v101, v69
	s_waitcnt lgkmcnt(1)
	v_mfma_f32_32x32x16_bf16 v[80:95], v[96:99], v[142:145], v[112:127]
	ds_read_b128 v[96:99], v168 offset:40960
	ds_read_b128 v[178:181], v168 offset:45056
	v_exp_f32_e32 v102, v70
	v_exp_f32_e32 v103, v71
	v_exp_f32_e32 v190, v72
	v_exp_f32_e32 v191, v73
	v_exp_f32_e32 v192, v74
	v_exp_f32_e32 v193, v75
	s_waitcnt lgkmcnt(1)
	v_mfma_f32_32x32x16_bf16 v[80:95], v[96:99], v[138:141], v[80:95]
	ds_read_b128 v[96:99], v167 offset:40960
	ds_read_b128 v[182:185], v167 offset:45056
	v_exp_f32_e32 v194, v76
	v_exp_f32_e32 v195, v77
	v_exp_f32_e32 v196, v78
	v_exp_f32_e32 v79, v79
	s_waitcnt lgkmcnt(1)
	v_mfma_f32_32x32x16_bf16 v[80:95], v[96:99], v[134:137], v[80:95]
	ds_read_b128 v[96:99], v166 offset:40960
	ds_read_b128 v[186:189], v166 offset:45056
	s_waitcnt lgkmcnt(1)
	v_mfma_f32_32x32x16_bf16 v[80:95], v[96:99], v[130:133], v[80:95]
	v_exp_f32_e32 v96, v64
	v_add_f32_e32 v64, 0, v152
	v_add_f32_e32 v64, v151, v64
	v_add_f32_e32 v176, v153, v148
	v_add_f32_e32 v177, v150, v149
	v_add_f32_e32 v64, v146, v64
	v_add_f32_e32 v176, v147, v176
	v_add_f32_e32 v177, v110, v177
	v_add_f32_e32 v64, v111, v64
	v_add_f32_e32 v176, v108, v176
	v_add_f32_e32 v177, v109, v177
	v_add_f32_e32 v64, v106, v64
	v_exp_f32_e32 v97, v65
	v_add_f32_e32 v176, v107, v176
	v_exp_f32_e32 v98, v66
	v_add_f32_e32 v177, v104, v177
	v_exp_f32_e32 v99, v67
	v_add_f32_e32 v64, v105, v64
	v_add_f32_e32 v176, v96, v176
	v_add_f32_e32 v177, v97, v177
	v_add_f32_e32 v64, v98, v64
	v_add_f32_e32 v176, v99, v176
	v_add_f32_e32 v177, v100, v177
	v_add_f32_e32 v64, v101, v64
	v_add_f32_e32 v176, v102, v176
	v_add_f32_e32 v177, v103, v177
	v_add_f32_e32 v64, v190, v64
	v_add_f32_e32 v176, v191, v176
	v_add_f32_e32 v177, v192, v177
	v_add_f32_e32 v64, v193, v64
	v_add_f32_e32 v176, v194, v176
	v_add_f32_e32 v177, v195, v177
	v_add_f32_e32 v64, v196, v64
	v_add_f32_e32 v176, v79, v176
	v_add_f32_e32 v176, v64, v176
	v_add_f32_e32 v176, v177, v176
	v_mov_b32_e32 v177, v176
	s_nop 1
	v_permlane32_swap_b32_e32 v176, v177
	v_cvt_pk_bf16_f32 v64, v152, v153
	v_cvt_pk_bf16_f32 v65, v150, v151
	v_cvt_pk_bf16_f32 v66, v148, v149
	v_cvt_pk_bf16_f32 v67, v146, v147
	v_cvt_pk_bf16_f32 v68, v110, v111
	v_cvt_pk_bf16_f32 v69, v108, v109
	v_cvt_pk_bf16_f32 v70, v106, v107
	v_cvt_pk_bf16_f32 v71, v104, v105
	v_cvt_pk_bf16_f32 v72, v96, v97
	v_cvt_pk_bf16_f32 v73, v98, v99
	v_cvt_pk_bf16_f32 v74, v100, v101
	v_cvt_pk_bf16_f32 v75, v102, v103
	v_cvt_pk_bf16_f32 v76, v190, v191
	v_cvt_pk_bf16_f32 v77, v192, v193
	v_cvt_pk_bf16_f32 v78, v194, v195
	v_cvt_pk_bf16_f32 v79, v196, v79
	s_nop 0
	v_permlane32_swap_b32_e32 v64, v66
	v_permlane32_swap_b32_e32 v65, v67
	v_permlane32_swap_b32_e32 v68, v70
	v_permlane32_swap_b32_e32 v69, v71
	v_permlane32_swap_b32_e32 v72, v74
	v_permlane32_swap_b32_e32 v73, v75
	v_permlane32_swap_b32_e32 v76, v78
	v_permlane32_swap_b32_e32 v77, v79
	s_add_i32 s68, s69, 0x80
	v_mfma_f32_32x32x16_bf16 v[96:111], v[154:157], v[142:145], v[112:127]
	s_mul_i32 s39, s68, 0xc00
	s_mul_hi_i32 s38, s68, 0xc00
	s_nop 4
	v_mad_i64_i32 v[112:113], s[20:21], s68, v236, v[162:163]
	s_add_u32 s20, s3, s39
	s_addc_u32 s21, s36, s38
	v_lshl_add_u64 v[116:117], v[160:161], 1, s[20:21]
	v_lshl_add_u64 v[114:115], v[158:159], 1, s[20:21]
	global_load_dwordx4 v[146:149], v[112:113], off offset:1024
	global_load_dwordx4 v[150:153], v[114:115], off offset:2048
	global_load_dwordx4 v[154:157], v[116:117], off offset:2048
	v_mfma_f32_32x32x16_bf16 v[96:111], v[178:181], v[138:141], v[96:111]
	v_mfma_f32_32x32x16_bf16 v[96:111], v[182:185], v[134:137], v[96:111]
	s_waitcnt lgkmcnt(0)
	v_mfma_f32_32x32x16_bf16 v[96:111], v[186:189], v[130:133], v[96:111]
	ds_read_b64_tr_b16 v[112:113], v171 offset:0
	ds_read_b64_tr_b16 v[114:115], v171 offset:0x800
	ds_read_b64_tr_b16 v[116:117], v171 offset:0x1000
	ds_read_b64_tr_b16 v[118:119], v171 offset:0x1800
	ds_read_b64_tr_b16 v[120:121], v171 offset:0x2000
	ds_read_b64_tr_b16 v[122:123], v171 offset:0x2800
	ds_read_b64_tr_b16 v[124:125], v171 offset:0x3000
	ds_read_b64_tr_b16 v[126:127], v171 offset:0x3800
	s_nop 0
	s_waitcnt lgkmcnt(6)
	v_mfma_f32_32x32x16_bf16 v[0:15], v[64:67], v[112:115], v[0:15]
	ds_read_b64_tr_b16 v[112:113], v171 offset:0x200
	ds_read_b64_tr_b16 v[114:115], v171 offset:0xa00
	s_waitcnt lgkmcnt(6)
	v_mfma_f32_32x32x16_bf16 v[0:15], v[68:71], v[116:119], v[0:15]
	ds_read_b64_tr_b16 v[116:117], v171 offset:0x1200
	ds_read_b64_tr_b16 v[118:119], v171 offset:0x1a00
	s_waitcnt lgkmcnt(6)
	v_mfma_f32_32x32x16_bf16 v[0:15], v[72:75], v[120:123], v[0:15]
	ds_read_b64_tr_b16 v[120:121], v171 offset:0x2200
	ds_read_b64_tr_b16 v[122:123], v171 offset:0x2a00
	s_waitcnt lgkmcnt(6)
	v_mfma_f32_32x32x16_bf16 v[0:15], v[76:79], v[124:127], v[0:15]
	ds_read_b64_tr_b16 v[124:125], v171 offset:0x3200
	ds_read_b64_tr_b16 v[126:127], v171 offset:0x3a00
	s_waitcnt lgkmcnt(6)
	v_mfma_f32_32x32x16_bf16 v[48:63], v[64:67], v[112:115], v[48:63]
	ds_read_b64_tr_b16 v[112:113], v171 offset:0x400
	ds_read_b64_tr_b16 v[114:115], v171 offset:0xc00
	s_waitcnt lgkmcnt(6)
	v_mfma_f32_32x32x16_bf16 v[48:63], v[68:71], v[116:119], v[48:63]
	ds_read_b64_tr_b16 v[116:117], v171 offset:0x1400
	ds_read_b64_tr_b16 v[118:119], v171 offset:0x1c00
	s_waitcnt lgkmcnt(6)
; #define WAIT_L0() asm volatile("s_waitcnt lgkmcnt(0)" ::: "memory")
; #define SBAR() __builtin_amdgcn_sched_barrier(0)
; __device__ __forceinline__ int crow(int r, int hi) { return (r & 3) + 8 * (r >> 2) + 4 * hi; }
; template <bool GM>
; __device__ __forceinline__ void partialSM(f32x16& p0, f32x16& p1, bool mask, int kbase, int L, int qpos, int hi) {
;   if (mask) {
; #pragma unroll
;     for (int r = 0; r < 16; ++r) {
;       int k = kbase + crow(r, hi);
;       asm volatile("" : "+v"(k) : "v"(p0[r]));
;       bool ok = k < L;
;       if (GM) ok = ok && (k < 16 || abs(qpos - k) <= 128);
;       p0[r] = ok ? p0[r] : -1e30f;
;       int k2 = k + 32;
;       asm volatile("" : "+v"(k2) : "v"(p1[r]));
;       bool ok2 = k2 < L;
;       if (GM) ok2 = ok2 && (k2 < 16 || abs(qpos - k2) <= 128);
;       p1[r] = ok2 ? p1[r] : -1e30f;
;     }
;   }
; template <int NCB, int D0> __device__ __forceinline__ void pv_one(f32x16& od, int vb, bf16x8 pa0, bf16x8 pa1, bf16x8 pa2, bf16x8 pa3) {
;   constexpr int KSTEP = NCB * 1024, HALF = NCB * 512, B0 = D0 * 512;
;   const s16x4 l0 = tr_read<B0>(vb), h0 = tr_read<B0 + HALF>(vb), l1 = tr_read<B0 + KSTEP>(vb), h1 = tr_read<B0 + KSTEP + HALF>(vb);
;   const s16x4 l2 = tr_read<B0 + 2 * KSTEP>(vb), h2 = tr_read<B0 + 2 * KSTEP + HALF>(vb), l3 = tr_read<B0 + 3 * KSTEP>(vb), h3 = tr_read<B0 + 3 * KSTEP + HALF>(vb);
;   WAIT_L0(); SBAR();
;     ...
;   od = __builtin_amdgcn_mfma_f32_32x32x16_bf16(pa0, PK(l0, h0), od, 0, 0, 0);
;   od = __builtin_amdgcn_mfma_f32_32x32x16_bf16(pa1, PK(l1, h1), od, 0, 0, 0);
;   od = __builtin_amdgcn_mfma_f32_32x32x16_bf16(pa2, PK(l2, h2), od, 0, 0, 0);
;   od = __builtin_amdgcn_mfma_f32_32x32x16_bf16(pa3, PK(l3, h3), od, 0, 0, 0);
;     ...
; }
; template <int NCB> __device__ __forceinline__ void pv_all(f32x16 (&o)[NCB], int vb, bf16x8 pa0, bf16x8 pa1, bf16x8 pa2, bf16x8 pa3) {
;   pv_one<NCB, 0>(o[0], vb, pa0, pa1, pa2, pa3); pv_one<NCB, 1>(o[1], vb, pa0, pa1, pa2, pa3);
;   if constexpr (NCB == 4) { pv_one<NCB, 2>(o[2], vb, pa0, pa1, pa2, pa3); pv_one<NCB, 3>(o[3], vb, pa0, pa1, pa2, pa3); }
; }
	v_mfma_f32_32x32x16_bf16 v[48:63], v[72:75], v[120:123], v[48:63]
	ds_read_b64_tr_b16 v[120:121], v171 offset:0x2400
	ds_read_b64_tr_b16 v[122:123], v171 offset:0x2c00
	s_waitcnt lgkmcnt(6)
	v_mfma_f32_32x32x16_bf16 v[48:63], v[76:79], v[124:127], v[48:63]
	ds_read_b64_tr_b16 v[124:125], v171 offset:0x3400
	ds_read_b64_tr_b16 v[126:127], v171 offset:0x3c00
	s_waitcnt lgkmcnt(6)
	v_mfma_f32_32x32x16_bf16 v[32:47], v[64:67], v[112:115], v[32:47]
	ds_read_b64_tr_b16 v[112:113], v171 offset:0x600
	ds_read_b64_tr_b16 v[114:115], v171 offset:0xe00
	s_waitcnt lgkmcnt(6)
	v_mfma_f32_32x32x16_bf16 v[32:47], v[68:71], v[116:119], v[32:47]
	ds_read_b64_tr_b16 v[116:117], v171 offset:0x1600
	ds_read_b64_tr_b16 v[118:119], v171 offset:0x1e00
	s_waitcnt lgkmcnt(6)
	v_mfma_f32_32x32x16_bf16 v[32:47], v[72:75], v[120:123], v[32:47]
	ds_read_b64_tr_b16 v[120:121], v171 offset:0x2600
	ds_read_b64_tr_b16 v[122:123], v171 offset:0x2e00
	s_waitcnt lgkmcnt(6)
	v_mfma_f32_32x32x16_bf16 v[32:47], v[76:79], v[124:127], v[32:47]
	ds_read_b64_tr_b16 v[124:125], v171 offset:0x3600
	ds_read_b64_tr_b16 v[126:127], v171 offset:0x3e00
	s_waitcnt lgkmcnt(6)
	v_mfma_f32_32x32x16_bf16 v[16:31], v[64:67], v[112:115], v[16:31]
	s_add_i32 s20, s69, 64
	s_cmp_le_i32 s20, s59
	v_add_u32_e32 v178, s69, v175
	s_waitcnt lgkmcnt(4)
	v_mfma_f32_32x32x16_bf16 v[16:31], v[68:71], v[116:119], v[16:31]
	s_waitcnt lgkmcnt(2)
	v_mfma_f32_32x32x16_bf16 v[16:31], v[72:75], v[120:123], v[16:31]
	s_waitcnt lgkmcnt(0)
	v_mfma_f32_32x32x16_bf16 v[16:31], v[76:79], v[124:127], v[16:31]
	s_cbranch_scc1 .LBB0_400
	v_add_u32_e32 v64, 64, v178
	s_nop 0
	v_cmp_gt_i32_e32 vcc, s94, v64
	v_add_u32_e32 v64, 32, v64
	s_nop 0
	v_cndmask_b32_e32 v80, v233, v80, vcc
	v_cmp_gt_i32_e32 vcc, s94, v64
	v_add_u32_e32 v64, 0x41, v178
	s_nop 0
	v_cndmask_b32_e32 v96, v233, v96, vcc
	v_cmp_gt_i32_e32 vcc, s94, v64
	v_add_u32_e32 v64, 32, v64
	s_nop 0
	v_cndmask_b32_e32 v81, v233, v81, vcc
	v_cmp_gt_i32_e32 vcc, s94, v64
	v_add_u32_e32 v64, 0x42, v178
	s_nop 0
	v_cndmask_b32_e32 v97, v233, v97, vcc
	v_cmp_gt_i32_e32 vcc, s94, v64
	v_add_u32_e32 v64, 32, v64
	s_nop 0
	v_cndmask_b32_e32 v82, v233, v82, vcc
	v_cmp_gt_i32_e32 vcc, s94, v64
	v_add_u32_e32 v64, 0x43, v178
	s_nop 0
	v_cndmask_b32_e32 v98, v233, v98, vcc
	v_cmp_gt_i32_e32 vcc, s94, v64
	v_add_u32_e32 v64, 32, v64
	s_nop 0
	v_cndmask_b32_e32 v83, v233, v83, vcc
	v_cmp_gt_i32_e32 vcc, s94, v64
	v_add_u32_e32 v64, 0x48, v178
	s_nop 0
	v_cndmask_b32_e32 v99, v233, v99, vcc
	v_cmp_gt_i32_e32 vcc, s94, v64
	v_add_u32_e32 v64, 32, v64
	s_nop 0
	v_cndmask_b32_e32 v84, v233, v84, vcc
	v_cmp_gt_i32_e32 vcc, s94, v64
	v_add_u32_e32 v64, 0x49, v178
	s_nop 0
	v_cndmask_b32_e32 v100, v233, v100, vcc
	v_cmp_gt_i32_e32 vcc, s94, v64
	v_add_u32_e32 v64, 32, v64
	s_nop 0
	v_cndmask_b32_e32 v85, v233, v85, vcc
	v_cmp_gt_i32_e32 vcc, s94, v64
	v_add_u32_e32 v64, 0x4a, v178
	s_nop 0
	v_cndmask_b32_e32 v101, v233, v101, vcc
	v_cmp_gt_i32_e32 vcc, s94, v64
	v_add_u32_e32 v64, 32, v64
	s_nop 0
	v_cndmask_b32_e32 v86, v233, v86, vcc
	v_cmp_gt_i32_e32 vcc, s94, v64
	v_add_u32_e32 v64, 0x4b, v178
	s_nop 0
	v_cndmask_b32_e32 v102, v233, v102, vcc
	v_cmp_gt_i32_e32 vcc, s94, v64
	v_add_u32_e32 v64, 32, v64
	s_nop 0
	v_cndmask_b32_e32 v87, v233, v87, vcc
	v_cmp_gt_i32_e32 vcc, s94, v64
	v_add_u32_e32 v64, 0x50, v178
	s_nop 0
	v_cndmask_b32_e32 v103, v233, v103, vcc
	v_cmp_gt_i32_e32 vcc, s94, v64
	v_add_u32_e32 v64, 32, v64
	s_nop 0
	v_cndmask_b32_e32 v88, v233, v88, vcc
	v_cmp_gt_i32_e32 vcc, s94, v64
	v_add_u32_e32 v64, 0x51, v178
	s_nop 0
	v_cndmask_b32_e32 v104, v233, v104, vcc
	v_cmp_gt_i32_e32 vcc, s94, v64
	v_add_u32_e32 v64, 32, v64
	s_nop 0
	v_cndmask_b32_e32 v89, v233, v89, vcc
	v_cmp_gt_i32_e32 vcc, s94, v64
	v_add_u32_e32 v64, 0x52, v178
	s_nop 0
	v_cndmask_b32_e32 v105, v233, v105, vcc
	v_cmp_gt_i32_e32 vcc, s94, v64
	v_add_u32_e32 v64, 32, v64
	s_nop 0
	v_cndmask_b32_e32 v90, v233, v90, vcc
	v_cmp_gt_i32_e32 vcc, s94, v64
	v_add_u32_e32 v64, 0x53, v178
	s_nop 0
	v_cndmask_b32_e32 v106, v233, v106, vcc
	v_cmp_gt_i32_e32 vcc, s94, v64
	v_add_u32_e32 v64, 32, v64
	s_nop 0
	v_cndmask_b32_e32 v91, v233, v91, vcc
	v_cmp_gt_i32_e32 vcc, s94, v64
	v_add_u32_e32 v64, 0x58, v178
	s_nop 0
	v_cndmask_b32_e32 v107, v233, v107, vcc
	v_cmp_gt_i32_e32 vcc, s94, v64
	v_add_u32_e32 v64, 32, v64
	s_nop 0
	v_cndmask_b32_e32 v92, v233, v92, vcc
	v_cmp_gt_i32_e32 vcc, s94, v64
	v_add_u32_e32 v64, 0x59, v178
	s_nop 0
	v_cndmask_b32_e32 v108, v233, v108, vcc
	v_cmp_gt_i32_e32 vcc, s94, v64
	v_add_u32_e32 v64, 32, v64
	s_nop 0
	v_cndmask_b32_e32 v93, v233, v93, vcc
	v_cmp_gt_i32_e32 vcc, s94, v64
	v_add_u32_e32 v64, 0x5a, v178
	s_nop 0
	v_cndmask_b32_e32 v109, v233, v109, vcc
	v_cmp_gt_i32_e32 vcc, s94, v64
	v_add_u32_e32 v64, 32, v64
	s_nop 0
	v_cndmask_b32_e32 v94, v233, v94, vcc
	v_cmp_gt_i32_e32 vcc, s94, v64
	v_add_u32_e32 v64, 0x5b, v178
	s_nop 0
	v_cndmask_b32_e32 v110, v233, v110, vcc
	v_cmp_gt_i32_e32 vcc, s94, v64
	v_add_u32_e32 v64, 32, v64
	s_nop 0
	v_cndmask_b32_e32 v95, v233, v95, vcc
	v_cmp_gt_i32_e32 vcc, s94, v64
	s_nop 1
	v_cndmask_b32_e32 v111, v233, v111, vcc
; #define WAIT_V0() asm volatile("s_waitcnt vmcnt(0)" ::: "memory")
; #define SBAR() __builtin_amdgcn_sched_barrier(0)
; #define SWRITE(b) do { FRESH_COORDS(); \
;     if constexpr (!KDMA) { _Pragma("unroll") for (int i = 0; i < KC; ++i) *reinterpret_cast<bf16x8*>(shm + (b) * SHM_K + klo[i]) = ks[i]; } \
;     _Pragma("unroll") for (int i = 0; i < VC; ++i) *reinterpret_cast<bf16x8*>(shm + (b) * SHM_V + vlo[i]) = vs[i]; } while (0)
; #define QKT(P0, P1, BUF) qkt<DQK, QL>(P0, P1, shm + K_OFF + (BUF) * SHM_K, qr, qlds, kofs, negM)
; __device__ __forceinline__ void finishSM(f32x16& p0, f32x16& p1, float& l_reg, bf16x8& pa0, bf16x8& pa1, bf16x8& pa2, bf16x8& pa3) {
; #pragma unroll
;   for (int r = 0; r < 16; ++r) p1[r] = __builtin_amdgcn_exp2f(p1[r]);
;   float ps = 0;
; #pragma unroll
;   for (int r = 0; r < 16; ++r) ps += p0[r];
; #pragma unroll
;   for (int r = 0; r < 16; ++r) ps += p1[r];
;   { auto rr = __builtin_amdgcn_permlane32_swap(__float_as_uint(ps), __float_as_uint(ps), false, false);
;     ps = __uint_as_float(rr[0]) + __uint_as_float(rr[1]); }
;   l_reg += ps;
;     ...
;   PK4(p0, 0, pa0); PK4(p0, 8, pa1); PK4(p1, 0, pa2); PK4(p1, 8, pa3);
;     ...
; }
;     ...
;     __syncthreads(); WAIT_V0(); SWRITE(0);
;     __syncthreads();
;     SBAR();
;     if constexpr (ONEP) { finishSM(pB0, pB1, l_reg, pa0, pa1, pa2, pa3); SBAR(); QKT(pA0, pA1, 0); }
;     else { QKT(pA0, pA1, 0); finishSM(pB0, pB1, l_reg, pa0, pa1, pa2, pa3); }
;     SBAR();
;     if (j + 2 < NT) SLOAD(TKEY(j + 2), 1);
.LBB0_400:
	s_barrier
	s_waitcnt vmcnt(0)
	s_waitcnt vmcnt(2)
	ds_write_b128 v174, v[146:149] offset:32768
	s_waitcnt vmcnt(1)
	ds_write_b128 v172, v[150:153]
	s_waitcnt vmcnt(0)
	ds_write_b128 v173, v[154:157]
	v_exp_f32_e32 v179, v80
	v_exp_f32_e32 v184, v81
	v_exp_f32_e32 v185, v82
	v_exp_f32_e32 v186, v83
	v_exp_f32_e32 v187, v84
	v_exp_f32_e32 v188, v85
	v_exp_f32_e32 v189, v86
	v_exp_f32_e32 v190, v87
	v_exp_f32_e32 v191, v88
	v_exp_f32_e32 v192, v89
	v_exp_f32_e32 v193, v90
	v_exp_f32_e32 v194, v91
	v_exp_f32_e32 v195, v92
	v_exp_f32_e32 v196, v93
	v_exp_f32_e32 v197, v94
	v_exp_f32_e32 v198, v95
	s_waitcnt lgkmcnt(0)
	s_barrier
	ds_read_b128 v[64:67], v169 offset:32768
	ds_read_b128 v[180:183], v169 offset:36864
	v_mov_b64_e32 v[126:127], s[18:19]
	v_mov_b64_e32 v[124:125], s[16:17]
	v_mov_b64_e32 v[122:123], s[14:15]
	v_mov_b64_e32 v[120:121], s[12:13]
	v_mov_b64_e32 v[118:119], s[10:11]
	v_mov_b64_e32 v[116:117], s[8:9]
	v_mov_b64_e32 v[114:115], s[6:7]
	v_mov_b64_e32 v[112:113], s[4:5]
	v_exp_f32_e32 v111, v111
	s_waitcnt lgkmcnt(1)
	v_mfma_f32_32x32x16_bf16 v[80:95], v[64:67], v[142:145], v[112:127]
	s_waitcnt lgkmcnt(0)
	v_mfma_f32_32x32x16_bf16 v[64:79], v[180:183], v[142:145], v[112:127]
	s_nop 6
	ds_read_b128 v[112:115], v168 offset:32768
	ds_read_b128 v[116:119], v168 offset:36864
	v_exp_f32_e32 v120, v102
	v_exp_f32_e32 v121, v103
	v_exp_f32_e32 v122, v104
	v_exp_f32_e32 v123, v105
	v_exp_f32_e32 v124, v106
	v_exp_f32_e32 v125, v107
	s_waitcnt lgkmcnt(1)
	v_mfma_f32_32x32x16_bf16 v[80:95], v[112:115], v[138:141], v[80:95]
	v_exp_f32_e32 v126, v108
	v_exp_f32_e32 v127, v109
	v_exp_f32_e32 v180, v110
	s_waitcnt lgkmcnt(0)
	v_mfma_f32_32x32x16_bf16 v[64:79], v[116:119], v[138:141], v[64:79]
	ds_read_b128 v[112:115], v167 offset:32768
	ds_read_b128 v[116:119], v167 offset:36864
	s_waitcnt lgkmcnt(1)
	v_mfma_f32_32x32x16_bf16 v[80:95], v[112:115], v[134:137], v[80:95]
	s_waitcnt lgkmcnt(0)
	v_mfma_f32_32x32x16_bf16 v[64:79], v[116:119], v[134:137], v[64:79]
	ds_read_b128 v[112:115], v166 offset:32768
	ds_read_b128 v[116:119], v166 offset:36864
	s_waitcnt lgkmcnt(1)
	v_mfma_f32_32x32x16_bf16 v[80:95], v[112:115], v[130:133], v[80:95]
	v_exp_f32_e32 v114, v96
	v_add_f32_e32 v96, 0, v179
	v_add_f32_e32 v96, v186, v96
	v_add_f32_e32 v112, v184, v187
	v_add_f32_e32 v113, v185, v188
	v_add_f32_e32 v96, v189, v96
	v_add_f32_e32 v112, v190, v112
	v_add_f32_e32 v113, v191, v113
	v_add_f32_e32 v96, v192, v96
	v_add_f32_e32 v112, v193, v112
	v_add_f32_e32 v113, v194, v113
	v_add_f32_e32 v96, v195, v96
	v_exp_f32_e32 v115, v97
	v_add_f32_e32 v112, v196, v112
	s_waitcnt lgkmcnt(0)
	v_mfma_f32_32x32x16_bf16 v[64:79], v[116:119], v[130:133], v[64:79]
	v_exp_f32_e32 v116, v98
	v_add_f32_e32 v113, v197, v113
	v_exp_f32_e32 v117, v99
	v_add_f32_e32 v96, v198, v96
	v_exp_f32_e32 v118, v100
	v_add_f32_e32 v112, v114, v112
	v_exp_f32_e32 v119, v101
	v_add_f32_e32 v113, v115, v113
	v_add_f32_e32 v96, v116, v96
	v_add_f32_e32 v112, v117, v112
	v_add_f32_e32 v113, v118, v113
	v_add_f32_e32 v96, v119, v96
	v_add_f32_e32 v112, v120, v112
	v_add_f32_e32 v113, v121, v113
	v_add_f32_e32 v96, v122, v96
	v_add_f32_e32 v112, v123, v112
	v_add_f32_e32 v113, v124, v113
	v_add_f32_e32 v96, v125, v96
	v_add_f32_e32 v112, v126, v112
	v_add_f32_e32 v113, v127, v113
	v_add_f32_e32 v96, v180, v96
	v_add_f32_e32 v112, v111, v112
	v_add_f32_e32 v112, v96, v112
	v_add_f32_e32 v112, v113, v112
	v_mov_b32_e32 v113, v112
	v_cvt_pk_bf16_f32 v96, v179, v184
	v_cvt_pk_bf16_f32 v97, v185, v186
	v_cvt_pk_bf16_f32 v98, v187, v188
	v_cvt_pk_bf16_f32 v99, v189, v190
	v_cvt_pk_bf16_f32 v100, v191, v192
	v_cvt_pk_bf16_f32 v101, v193, v194
	v_cvt_pk_bf16_f32 v102, v195, v196
	v_cvt_pk_bf16_f32 v103, v197, v198
	v_cvt_pk_bf16_f32 v104, v114, v115
	v_cvt_pk_bf16_f32 v105, v116, v117
	v_cvt_pk_bf16_f32 v106, v118, v119
	v_cvt_pk_bf16_f32 v107, v120, v121
	v_cvt_pk_bf16_f32 v108, v122, v123
	v_cvt_pk_bf16_f32 v109, v124, v125
	v_cvt_pk_bf16_f32 v110, v126, v127
	v_cvt_pk_bf16_f32 v111, v180, v111
	s_nop 1
	v_permlane32_swap_b32_e32 v112, v113
	v_permlane32_swap_b32_e32 v96, v98
	v_permlane32_swap_b32_e32 v97, v99
	v_permlane32_swap_b32_e32 v100, v102
	v_permlane32_swap_b32_e32 v101, v103
	v_permlane32_swap_b32_e32 v104, v106
	v_permlane32_swap_b32_e32 v105, v107
	v_permlane32_swap_b32_e32 v108, v110
	v_permlane32_swap_b32_e32 v109, v111
	s_cmp_lt_i32 s54, s55
	s_cselect_b64 s[20:21], -1, 0
	s_cmp_ge_i32 s54, s55
	s_cbranch_scc1 .LBB0_402
	s_add_i32 s38, s69, 0xc0
	s_mul_i32 s69, s38, 0xc00
	v_mad_i64_i32 v[114:115], s[80:81], s38, v236, v[162:163]
	s_mul_hi_i32 s39, s38, 0xc00
	s_add_u32 s80, s3, s69
	s_addc_u32 s81, s36, s39
	v_lshl_add_u64 v[116:117], v[158:159], 1, s[80:81]
	global_load_dwordx4 v[146:149], v[114:115], off offset:1024
	global_load_dwordx4 v[150:153], v[116:117], off offset:2048
	v_lshl_add_u64 v[114:115], v[160:161], 1, s[80:81]
	global_load_dwordx4 v[154:157], v[114:115], off offset:2048

; __device__ __forceinline__ void finishSM(f32x16& p0, f32x16& p1, float& l_reg, bf16x8& pa0, bf16x8& pa1, bf16x8& pa2, bf16x8& pa3) {
; #pragma unroll
;   for (int r = 0; r < 16; ++r) p1[r] = __builtin_amdgcn_exp2f(p1[r]);
;   float ps = 0;
; #pragma unroll
;   for (int r = 0; r < 16; ++r) ps += p0[r];
; #pragma unroll
;   for (int r = 0; r < 16; ++r) ps += p1[r];
;   { auto rr = __builtin_amdgcn_permlane32_swap(__float_as_uint(ps), __float_as_uint(ps), false, false);
;     ps = __uint_as_float(rr[0]) + __uint_as_float(rr[1]); }
;   l_reg += ps;
;     ...
;   PK4(p0, 0, pa0); PK4(p0, 8, pa1); PK4(p1, 0, pa2); PK4(p1, 8, pa3);
;     ...
; }
; template <int DQK, int QL>
; __device__ __forceinline__ void qkt(f32x16& p0, f32x16& p1, const char* Ks, const bf16x8 (&qr)[DQK / 16 - QL], const char* qlds, const int (&kofs)[4], float negM) {
;   constexpr int QR = DQK / 16 - QL;
; #pragma unroll
;   for (int r = 0; r < 16; ++r) { p0[r] = negM; p1[r] = negM; }
; #pragma unroll
;   for (int d0 = 0; d0 < DQK / 16; ++d0) {
;     const char* kp = Ks + kofs[d0 & 3] + (d0 >> 2) * 128;
;     bf16x8 b0 = *reinterpret_cast<const bf16x8*>(kp);
;     bf16x8 b1 = *reinterpret_cast<const bf16x8*>(kp + 32 * DQK * 2);
;     bf16x8 qf;
;     if constexpr (QL > 0) { if (d0 < QR) qf = qr[d0 < QR ? d0 : 0]; else qf = *reinterpret_cast<const bf16x8*>(qlds + (d0 - QR) * 1024); }
;     else qf = qr[d0];
;     p0 = __builtin_amdgcn_mfma_f32_32x32x16_bf16(b0, qf, p0, 0, 0, 0);
;     p1 = __builtin_amdgcn_mfma_f32_32x32x16_bf16(b1, qf, p1, 0, 0, 0);
;   }
; }
.LBB0_430:
	v_add_f32_e32 v80, 0, v132
	v_add_f32_e32 v80, v131, v80
	v_add_f32_e32 v168, v133, v126
	v_add_f32_e32 v169, v130, v127
	v_add_f32_e32 v80, v124, v80
	v_add_f32_e32 v168, v125, v168
	v_add_f32_e32 v169, v110, v169
	v_add_f32_e32 v80, v111, v80
	v_add_f32_e32 v168, v108, v168
	v_add_f32_e32 v169, v109, v169
	v_exp_f32_e32 v64, v64
	v_add_f32_e32 v80, v106, v80
	v_exp_f32_e32 v65, v65
	v_add_f32_e32 v168, v107, v168
	v_exp_f32_e32 v66, v66
	v_add_f32_e32 v169, v104, v169
	v_exp_f32_e32 v67, v67
	v_add_f32_e32 v80, v105, v80
	v_exp_f32_e32 v68, v68
	v_add_f32_e32 v168, v64, v168
	v_exp_f32_e32 v69, v69
	v_add_f32_e32 v169, v65, v169
	v_exp_f32_e32 v70, v70
	v_add_f32_e32 v80, v66, v80
	v_exp_f32_e32 v71, v71
	v_add_f32_e32 v168, v67, v168
	v_exp_f32_e32 v72, v72
	v_add_f32_e32 v169, v68, v169
	v_exp_f32_e32 v73, v73
	v_add_f32_e32 v80, v69, v80
	v_exp_f32_e32 v74, v74
	v_add_f32_e32 v168, v70, v168
	v_exp_f32_e32 v75, v75
	v_add_f32_e32 v169, v71, v169
	v_exp_f32_e32 v76, v76
	v_add_f32_e32 v80, v72, v80
	v_exp_f32_e32 v77, v77
	v_add_f32_e32 v168, v73, v168
	v_exp_f32_e32 v78, v78
	v_add_f32_e32 v169, v74, v169
	v_exp_f32_e32 v79, v79
	v_add_f32_e32 v80, v75, v80
	v_add_f32_e32 v168, v76, v168
	v_add_f32_e32 v169, v77, v169
	v_add_f32_e32 v80, v78, v80
	v_add_f32_e32 v168, v79, v168
	v_add_f32_e32 v168, v80, v168
	v_add_f32_e32 v168, v169, v168
	v_mov_b32_e32 v169, v168
	s_nop 1
	v_permlane32_swap_b32_e32 v168, v169
	v_cvt_pk_bf16_f32 v134, v132, v133
	v_cvt_pk_bf16_f32 v135, v130, v131
	v_cvt_pk_bf16_f32 v136, v126, v127
	v_cvt_pk_bf16_f32 v137, v124, v125
	v_cvt_pk_bf16_f32 v138, v110, v111
	v_cvt_pk_bf16_f32 v139, v108, v109
	v_cvt_pk_bf16_f32 v140, v106, v107
	v_cvt_pk_bf16_f32 v141, v104, v105
	v_cvt_pk_bf16_f32 v146, v64, v65
	v_cvt_pk_bf16_f32 v147, v66, v67
	v_cvt_pk_bf16_f32 v148, v68, v69
	v_cvt_pk_bf16_f32 v149, v70, v71
	v_cvt_pk_bf16_f32 v142, v72, v73
	v_cvt_pk_bf16_f32 v143, v74, v75
	v_cvt_pk_bf16_f32 v144, v76, v77
	v_cvt_pk_bf16_f32 v145, v78, v79
	s_nop 0
	v_permlane32_swap_b32_e32 v134, v136
	v_permlane32_swap_b32_e32 v135, v137
	v_permlane32_swap_b32_e32 v138, v140
	v_permlane32_swap_b32_e32 v139, v141
	v_permlane32_swap_b32_e32 v146, v148
	v_permlane32_swap_b32_e32 v147, v149
	v_permlane32_swap_b32_e32 v142, v144
	v_permlane32_swap_b32_e32 v143, v145
	ds_read_b128 v[80:83], v153 offset:57344
	ds_read_b128 v[84:87], v153 offset:57472
	v_mov_b64_e32 v[110:111], s[18:19]
	v_mov_b64_e32 v[108:109], s[16:17]
	v_mov_b64_e32 v[106:107], s[14:15]
	v_mov_b64_e32 v[104:105], s[12:13]
	v_mov_b64_e32 v[102:103], s[10:11]
	v_mov_b64_e32 v[100:101], s[8:9]
	v_mov_b64_e32 v[98:99], s[6:7]
	v_mov_b64_e32 v[96:97], s[4:5]
	v_add_u32_e32 v171, v155, v154
	s_waitcnt lgkmcnt(1)
	v_mfma_f32_32x32x16_bf16 v[64:79], v[80:83], v[120:123], v[96:111]
	ds_read_b128 v[80:83], v152 offset:57344
	ds_read_b128 v[88:91], v153 offset:57600
	s_waitcnt lgkmcnt(1)
	v_mfma_f32_32x32x16_bf16 v[64:79], v[80:83], v[116:119], v[64:79]
	ds_read_b128 v[80:83], v151 offset:57344
	ds_read_b128 v[92:95], v151 offset:57472
	s_waitcnt lgkmcnt(1)
	v_mfma_f32_32x32x16_bf16 v[64:79], v[80:83], v[112:115], v[64:79]
	ds_read_b128 v[80:83], v150 offset:57344
	ds_read_b128 v[124:127], v171
	ds_read_b128 v[130:133], v151 offset:57600
	ds_read_b128 v[172:175], v171 offset:1024
	s_waitcnt lgkmcnt(2)
	v_mfma_f32_32x32x16_bf16 v[64:79], v[80:83], v[124:127], v[64:79]
	s_waitcnt lgkmcnt(0)
	v_mfma_f32_32x32x16_bf16 v[64:79], v[84:87], v[172:175], v[64:79]
	ds_read_b128 v[80:83], v152 offset:57472
	ds_read_b128 v[176:179], v171 offset:2048
	ds_read_b128 v[84:87], v152 offset:57600
	ds_read_b128 v[180:183], v171 offset:3072
	s_waitcnt lgkmcnt(2)
	v_mfma_f32_32x32x16_bf16 v[64:79], v[80:83], v[176:179], v[64:79]
	s_waitcnt lgkmcnt(0)
	v_mfma_f32_32x32x16_bf16 v[64:79], v[92:95], v[180:183], v[64:79]
	ds_read_b128 v[80:83], v150 offset:57472
	ds_read_b128 v[184:187], v171 offset:4096
	ds_read_b128 v[188:191], v171 offset:5120
	ds_read_b128 v[92:95], v150 offset:57600
	ds_read_b128 v[192:195], v171 offset:6144
	ds_read_b128 v[196:199], v171 offset:7168
	ds_read_b128 v[200:203], v165 offset:12288
	ds_read_b128 v[204:207], v165 offset:12416
	ds_read_b128 v[208:211], v163 offset:12288
	ds_read_b128 v[212:215], v163 offset:12416
	ds_read_b128 v[216:219], v166 offset:12416
	ds_read_b128 v[220:223], v166 offset:12544
	s_waitcnt lgkmcnt(10)
	v_mfma_f32_32x32x16_bf16 v[64:79], v[80:83], v[184:187], v[64:79]
	s_waitcnt lgkmcnt(9)
	v_mfma_f32_32x32x16_bf16 v[64:79], v[88:91], v[188:191], v[64:79]
	s_waitcnt lgkmcnt(7)
	v_mfma_f32_32x32x16_bf16 v[64:79], v[84:87], v[192:195], v[64:79]
	s_waitcnt lgkmcnt(6)
	v_mfma_f32_32x32x16_bf16 v[64:79], v[130:133], v[196:199], v[64:79]
	ds_read_b128 v[130:133], v166 offset:12288
	ds_read_b128 v[224:227], v171 offset:8192
	ds_read_b128 v[228:231], v164 offset:12288
	ds_read_b128 v[238:241], v165 offset:12544
	ds_read_b128 v[242:245], v164 offset:12416
	ds_read_b128 v[246:249], v164 offset:12544
	ds_read_b128 v[250:253], v163 offset:12544
	s_waitcnt lgkmcnt(5)
; #define WAIT_L0() asm volatile("s_waitcnt lgkmcnt(0)" ::: "memory")
; #define SBAR() __builtin_amdgcn_sched_barrier(0)
; __device__ __forceinline__ int v_rd_base(int lane) { return ((lane & 3) << 3) | (((lane >> 2) & 3) << 6) | (((lane >> 4) & 1) << 5) | (((lane >> 5) & 1) << 8); }
; #define V_COORDS(T) do { if constexpr (VC == 2) { const int sr = (T) >> 4, sc = ((T) & 15) * 8; vgo[0] = sr * LDV + sc; vgo[VC - 1] = (32 + sr) * LDV + sc; vlo[0] = v_st<NCB>(sr, sc); vlo[VC - 1] = v_st<NCB>(32 + sr, sc); } \
;     else { const int sr = (T) >> 3, sc = ((T) & 7) * 8; vgo[0] = sr * LDV + sc; vlo[0] = v_st<NCB>(sr, sc); } } while (0)
; template <int NCB, int D0> __device__ __forceinline__ void pv_one(f32x16& od, int vb, bf16x8 pa0, bf16x8 pa1, bf16x8 pa2, bf16x8 pa3) {
;   constexpr int KSTEP = NCB * 1024, HALF = NCB * 512, B0 = D0 * 512;
;   const s16x4 l0 = tr_read<B0>(vb), h0 = tr_read<B0 + HALF>(vb), l1 = tr_read<B0 + KSTEP>(vb), h1 = tr_read<B0 + KSTEP + HALF>(vb);
;   const s16x4 l2 = tr_read<B0 + 2 * KSTEP>(vb), h2 = tr_read<B0 + 2 * KSTEP + HALF>(vb), l3 = tr_read<B0 + 3 * KSTEP>(vb), h3 = tr_read<B0 + 3 * KSTEP + HALF>(vb);
;   WAIT_L0(); SBAR();
;     ...
;   od = __builtin_amdgcn_mfma_f32_32x32x16_bf16(pa0, PK(l0, h0), od, 0, 0, 0);
;   od = __builtin_amdgcn_mfma_f32_32x32x16_bf16(pa1, PK(l1, h1), od, 0, 0, 0);
;   od = __builtin_amdgcn_mfma_f32_32x32x16_bf16(pa2, PK(l2, h2), od, 0, 0, 0);
;   od = __builtin_amdgcn_mfma_f32_32x32x16_bf16(pa3, PK(l3, h3), od, 0, 0, 0);
;     ...
; }
; template <int NCB> __device__ __forceinline__ void pv_all(f32x16 (&o)[NCB], int vb, bf16x8 pa0, bf16x8 pa1, bf16x8 pa2, bf16x8 pa3) {
;   pv_one<NCB, 0>(o[0], vb, pa0, pa1, pa2, pa3); pv_one<NCB, 1>(o[1], vb, pa0, pa1, pa2, pa3);
;   if constexpr (NCB == 4) { pv_one<NCB, 2>(o[2], vb, pa0, pa1, pa2, pa3); pv_one<NCB, 3>(o[3], vb, pa0, pa1, pa2, pa3); }
; }
;     ...
;   if constexpr (KDMA) {
;   } else {
; #pragma unroll
;     for (int i = 0; i < KC; ++i) { const int c = tid + i * 512, row = c / CPR, cc = c % CPR; kgo[i] = row * LDK + cc * 8; klo[i] = K_OFF + KSWZ(KRS, row, cc * 16); }
;     V_COORDS(tid);
;   }
;   const int vb0 = (int)(uintptr_t)shm + v_rd_base(lane);
;   int kofs[4];
; #pragma unroll
;   for (int b = 0; b < 4; ++b) kofs[b] = (r32 ^ ((r32 >> 3) & 1)) * KRS + ((b * 32 + hi * 16) ^ ((r32 & 7) << 4));
;   bf16x8 ks[KC], vs[VC];
	v_mfma_f32_32x32x16_bf16 v[64:79], v[92:95], v[224:227], v[64:79]
	v_mfma_f32_32x32x16_bf16 v[80:95], v[130:133], v[120:123], v[96:111]
	s_add_i32 s68, s23, 0x80
	s_ashr_i32 s69, s68, 31
	s_mul_i32 s20, s68, 0x600
	s_mul_hi_i32 s21, s68, 0x600
	s_add_u32 s20, s3, s20
	s_nop 1
	v_mov_b32_e32 v97, v157
	v_mfma_f32_32x32x16_bf16 v[80:95], v[200:203], v[116:119], v[80:95]
	v_mul_hi_i32 v99, v97, s82
	v_lshrrev_b32_e32 v100, 31, v99
	v_ashrrev_i32_e32 v99, 2, v99
	v_add_u32_e32 v99, v99, v100
	v_lshrrev_b32_e32 v101, 3, v99
	v_mul_lo_u32 v100, v99, 24
	v_bitop3_b32 v99, v101, v99, 1 bitop3:0x6c
	v_add_u32_e32 v101, 0x200, v97
	v_mul_hi_i32 v102, v101, s82
	v_sub_u32_e32 v100, v97, v100
	v_lshrrev_b32_e32 v103, 31, v102
	v_ashrrev_i32_e32 v102, 2, v102
	v_bitop3_b32 v100, v99, v100, 7 bitop3:0x6c
	v_mul_lo_u32 v99, v99, s85
	v_add_u32_e32 v102, v102, v103
	v_lshl_add_u32 v100, v100, 3, v99
	v_mul_lo_u32 v99, v102, 24
	v_lshlrev_b32_e32 v96, 3, v97
	v_lshlrev_b32_e32 v98, 5, v97
	v_sub_u32_e32 v99, v101, v99
	v_lshrrev_b32_e32 v101, 3, v102
	v_add_u32_e32 v97, 0x400, v97
	v_bitop3_b32 v101, v101, v102, 1 bitop3:0x6c
	v_mul_hi_i32 v102, v97, s82
	v_lshrrev_b32_e32 v103, 31, v102
	v_ashrrev_i32_e32 v102, 2, v102
	v_add_u32_e32 v103, v102, v103
	v_bitop3_b32 v99, v101, v99, 7 bitop3:0x6c
	v_mul_lo_u32 v101, v101, s85
	v_mul_lo_u32 v102, v103, 24
	v_sub_u32_e32 v97, v97, v102
	v_lshl_add_u32 v102, v99, 3, v101
	v_lshrrev_b32_e32 v99, 3, v103
	s_waitcnt lgkmcnt(4)
	v_mfma_f32_32x32x16_bf16 v[80:95], v[228:231], v[112:115], v[80:95]
	v_bitop3_b32 v99, v99, v103, 1 bitop3:0x6c
	v_bitop3_b32 v97, v99, v97, 7 bitop3:0x6c
	v_mul_lo_u32 v99, v99, s85
	s_addc_u32 s21, s36, s21
	v_ashrrev_i32_e32 v101, 31, v100
	v_readfirstlane_b32 s38, v160
	v_lshl_add_u32 v104, v97, 3, v99
	v_lshl_add_u64 v[100:101], v[100:101], 1, s[20:21]
	s_mov_b32 m0, s38
	v_ashrrev_i32_e32 v103, 31, v102
	v_readfirstlane_b32 s38, v161
	global_load_lds_dwordx4 v[100:101], off
	v_lshl_add_u64 v[100:101], v[102:103], 1, s[20:21]
	s_mov_b32 m0, s38
	v_ashrrev_i32_e32 v105, 31, v104
	v_and_b32_e32 v96, 0x78, v96
	global_load_lds_dwordx4 v[100:101], off
	v_lshl_add_u64 v[100:101], v[104:105], 1, s[20:21]
	s_lshl_b64 s[20:21], s[68:69], 10
	v_and_or_b32 v96, v98, s24, v96
	v_readfirstlane_b32 s38, v162
	s_add_u32 s20, s83, s20
	v_add_u32_e32 v98, 0x4000, v96
	s_mov_b32 m0, s38
	s_addc_u32 s21, s93, s21
	v_ashrrev_i32_e32 v97, 31, v96
	global_load_lds_dwordx4 v[100:101], off
	v_lshl_add_u64 v[96:97], v[96:97], 1, s[20:21]
	v_ashrrev_i32_e32 v99, 31, v98
	v_mfma_f32_32x32x16_bf16 v[80:95], v[208:211], v[124:127], v[80:95]
	v_lshl_add_u64 v[98:99], v[98:99], 1, s[20:21]
	global_load_dwordx4 v[130:133], v[96:97], off
	global_load_dwordx4 v[124:127], v[98:99], off
	v_mfma_f32_32x32x16_bf16 v[80:95], v[216:219], v[172:175], v[80:95]
	v_mfma_f32_32x32x16_bf16 v[80:95], v[204:207], v[176:179], v[80:95]
	s_waitcnt lgkmcnt(0)
	v_mfma_f32_32x32x16_bf16 v[80:95], v[242:245], v[180:183], v[80:95]
	v_mfma_f32_32x32x16_bf16 v[80:95], v[212:215], v[184:187], v[80:95]
	v_mfma_f32_32x32x16_bf16 v[80:95], v[220:223], v[188:191], v[80:95]
	v_mfma_f32_32x32x16_bf16 v[80:95], v[238:241], v[192:195], v[80:95]
	v_mfma_f32_32x32x16_bf16 v[80:95], v[246:249], v[196:199], v[80:95]
	v_mfma_f32_32x32x16_bf16 v[80:95], v[250:253], v[224:227], v[80:95]
	ds_read_b64_tr_b16 v[96:97], v159 offset:0
	ds_read_b64_tr_b16 v[98:99], v159 offset:0x800
	ds_read_b64_tr_b16 v[100:101], v159 offset:0x1000
	ds_read_b64_tr_b16 v[102:103], v159 offset:0x1800
	ds_read_b64_tr_b16 v[104:105], v159 offset:0x2000
	ds_read_b64_tr_b16 v[106:107], v159 offset:0x2800
	ds_read_b64_tr_b16 v[108:109], v159 offset:0x3000
	ds_read_b64_tr_b16 v[110:111], v159 offset:0x3800
	s_nop 0
	s_waitcnt lgkmcnt(6)
	v_mfma_f32_32x32x16_bf16 v[0:15], v[134:137], v[96:99], v[0:15]
	ds_read_b64_tr_b16 v[96:97], v159 offset:0x200
	ds_read_b64_tr_b16 v[98:99], v159 offset:0xa00
	s_waitcnt lgkmcnt(6)
	v_mfma_f32_32x32x16_bf16 v[0:15], v[138:141], v[100:103], v[0:15]
	ds_read_b64_tr_b16 v[100:101], v159 offset:0x1200
	ds_read_b64_tr_b16 v[102:103], v159 offset:0x1a00
	s_waitcnt lgkmcnt(6)
	v_mfma_f32_32x32x16_bf16 v[0:15], v[146:149], v[104:107], v[0:15]
	ds_read_b64_tr_b16 v[104:105], v159 offset:0x2200
	ds_read_b64_tr_b16 v[106:107], v159 offset:0x2a00
	s_waitcnt lgkmcnt(6)
	v_mfma_f32_32x32x16_bf16 v[0:15], v[142:145], v[108:111], v[0:15]
	ds_read_b64_tr_b16 v[108:109], v159 offset:0x3200
	ds_read_b64_tr_b16 v[110:111], v159 offset:0x3a00
	s_waitcnt lgkmcnt(6)
	v_mfma_f32_32x32x16_bf16 v[48:63], v[134:137], v[96:99], v[48:63]
	ds_read_b64_tr_b16 v[96:97], v159 offset:0x400
	ds_read_b64_tr_b16 v[98:99], v159 offset:0xc00
	s_waitcnt lgkmcnt(6)
	v_mfma_f32_32x32x16_bf16 v[48:63], v[138:141], v[100:103], v[48:63]
	ds_read_b64_tr_b16 v[100:101], v159 offset:0x1400
	ds_read_b64_tr_b16 v[102:103], v159 offset:0x1c00
	s_waitcnt lgkmcnt(6)
	v_mfma_f32_32x32x16_bf16 v[48:63], v[146:149], v[104:107], v[48:63]
	ds_read_b64_tr_b16 v[104:105], v159 offset:0x2400
	ds_read_b64_tr_b16 v[106:107], v159 offset:0x2c00
	s_waitcnt lgkmcnt(6)
	v_mfma_f32_32x32x16_bf16 v[48:63], v[142:145], v[108:111], v[48:63]
	ds_read_b64_tr_b16 v[108:109], v159 offset:0x3400
	ds_read_b64_tr_b16 v[110:111], v159 offset:0x3c00
	s_waitcnt lgkmcnt(6)
	v_mfma_f32_32x32x16_bf16 v[32:47], v[134:137], v[96:99], v[32:47]
	ds_read_b64_tr_b16 v[96:97], v159 offset:0x600
	ds_read_b64_tr_b16 v[98:99], v159 offset:0xe00
	s_waitcnt lgkmcnt(6)
	v_mfma_f32_32x32x16_bf16 v[32:47], v[138:141], v[100:103], v[32:47]
	ds_read_b64_tr_b16 v[100:101], v159 offset:0x1600
	ds_read_b64_tr_b16 v[102:103], v159 offset:0x1e00
	s_waitcnt lgkmcnt(6)
	v_mfma_f32_32x32x16_bf16 v[32:47], v[146:149], v[104:107], v[32:47]
	ds_read_b64_tr_b16 v[104:105], v159 offset:0x2600
	ds_read_b64_tr_b16 v[106:107], v159 offset:0x2e00
	s_waitcnt lgkmcnt(6)
	v_mfma_f32_32x32x16_bf16 v[32:47], v[142:145], v[108:111], v[32:47]
	ds_read_b64_tr_b16 v[108:109], v159 offset:0x3600
	ds_read_b64_tr_b16 v[110:111], v159 offset:0x3e00
	s_waitcnt lgkmcnt(6)
	v_mfma_f32_32x32x16_bf16 v[16:31], v[134:137], v[96:99], v[16:31]
	s_add_i32 s20, s23, 64
	v_lshlrev_b32_e32 v96, 2, v128
	s_cmp_le_i32 s20, s59
	v_add_u32_e32 v170, s23, v96
	s_waitcnt lgkmcnt(4)
	v_mfma_f32_32x32x16_bf16 v[16:31], v[138:141], v[100:103], v[16:31]
	s_waitcnt lgkmcnt(2)
	v_mfma_f32_32x32x16_bf16 v[16:31], v[146:149], v[104:107], v[16:31]
	s_waitcnt lgkmcnt(0)
	v_mfma_f32_32x32x16_bf16 v[16:31], v[142:145], v[108:111], v[16:31]
	s_cbranch_scc1 .LBB0_432
; __device__ __forceinline__ int crow(int r, int hi) { return (r & 3) + 8 * (r >> 2) + 4 * hi; }
; template <bool GM>
; __device__ __forceinline__ void partialSM(f32x16& p0, f32x16& p1, bool mask, int kbase, int L, int qpos, int hi) {
;   if (mask) {
; #pragma unroll
;     for (int r = 0; r < 16; ++r) {
;       int k = kbase + crow(r, hi);
;       asm volatile("" : "+v"(k) : "v"(p0[r]));
;       bool ok = k < L;
;       if (GM) ok = ok && (k < 16 || abs(qpos - k) <= 128);
;       p0[r] = ok ? p0[r] : -1e30f;
;       int k2 = k + 32;
;       asm volatile("" : "+v"(k2) : "v"(p1[r]));
;       bool ok2 = k2 < L;
;       if (GM) ok2 = ok2 && (k2 < 16 || abs(qpos - k2) <= 128);
;       p1[r] = ok2 ? p1[r] : -1e30f;
;     }
;   }
; #pragma unroll
;   for (int r = 0; r < 16; ++r) p0[r] = __builtin_amdgcn_exp2f(p0[r]);
	v_add_u32_e32 v96, 64, v170
	s_nop 0
	v_cmp_gt_i32_e32 vcc, s94, v96
	v_add_u32_e32 v96, 32, v96
	s_nop 0
	v_cndmask_b32_e32 v64, v233, v64, vcc
	v_cmp_gt_i32_e32 vcc, s94, v96
	v_add_u32_e32 v96, 0x41, v170
	s_nop 0
	v_cndmask_b32_e32 v80, v233, v80, vcc
	v_cmp_gt_i32_e32 vcc, s94, v96
	v_add_u32_e32 v96, 32, v96
	s_nop 0
	v_cndmask_b32_e32 v65, v233, v65, vcc
	v_cmp_gt_i32_e32 vcc, s94, v96
	v_add_u32_e32 v96, 0x42, v170
	s_nop 0
	v_cndmask_b32_e32 v81, v233, v81, vcc
	v_cmp_gt_i32_e32 vcc, s94, v96
	v_add_u32_e32 v96, 32, v96
	s_nop 0
	v_cndmask_b32_e32 v66, v233, v66, vcc
	v_cmp_gt_i32_e32 vcc, s94, v96
	v_add_u32_e32 v96, 0x43, v170
	s_nop 0
	v_cndmask_b32_e32 v82, v233, v82, vcc
	v_cmp_gt_i32_e32 vcc, s94, v96
	v_add_u32_e32 v96, 32, v96
	s_nop 0
	v_cndmask_b32_e32 v67, v233, v67, vcc
	v_cmp_gt_i32_e32 vcc, s94, v96
	v_add_u32_e32 v96, 0x48, v170
	s_nop 0
	v_cndmask_b32_e32 v83, v233, v83, vcc
	v_cmp_gt_i32_e32 vcc, s94, v96
	v_add_u32_e32 v96, 32, v96
	s_nop 0
	v_cndmask_b32_e32 v68, v233, v68, vcc
	v_cmp_gt_i32_e32 vcc, s94, v96
	v_add_u32_e32 v96, 0x49, v170
	s_nop 0
	v_cndmask_b32_e32 v84, v233, v84, vcc
	v_cmp_gt_i32_e32 vcc, s94, v96
	v_add_u32_e32 v96, 32, v96
	s_nop 0
	v_cndmask_b32_e32 v69, v233, v69, vcc
	v_cmp_gt_i32_e32 vcc, s94, v96
	v_add_u32_e32 v96, 0x4a, v170
	s_nop 0
	v_cndmask_b32_e32 v85, v233, v85, vcc
	v_cmp_gt_i32_e32 vcc, s94, v96
	v_add_u32_e32 v96, 32, v96
	s_nop 0
	v_cndmask_b32_e32 v70, v233, v70, vcc
	v_cmp_gt_i32_e32 vcc, s94, v96
	v_add_u32_e32 v96, 0x4b, v170
	s_nop 0
	v_cndmask_b32_e32 v86, v233, v86, vcc
	v_cmp_gt_i32_e32 vcc, s94, v96
	v_add_u32_e32 v96, 32, v96
	s_nop 0
	v_cndmask_b32_e32 v71, v233, v71, vcc
	v_cmp_gt_i32_e32 vcc, s94, v96
	v_add_u32_e32 v96, 0x50, v170
	s_nop 0
	v_cndmask_b32_e32 v87, v233, v87, vcc
	v_cmp_gt_i32_e32 vcc, s94, v96
	v_add_u32_e32 v96, 32, v96
	s_nop 0
	v_cndmask_b32_e32 v72, v233, v72, vcc
	v_cmp_gt_i32_e32 vcc, s94, v96
	v_add_u32_e32 v96, 0x51, v170
	s_nop 0
	v_cndmask_b32_e32 v88, v233, v88, vcc
	v_cmp_gt_i32_e32 vcc, s94, v96
	v_add_u32_e32 v96, 32, v96
	s_nop 0
	v_cndmask_b32_e32 v73, v233, v73, vcc
	v_cmp_gt_i32_e32 vcc, s94, v96
	v_add_u32_e32 v96, 0x52, v170
	s_nop 0
	v_cndmask_b32_e32 v89, v233, v89, vcc
	v_cmp_gt_i32_e32 vcc, s94, v96
	v_add_u32_e32 v96, 32, v96
	s_nop 0
	v_cndmask_b32_e32 v74, v233, v74, vcc
	v_cmp_gt_i32_e32 vcc, s94, v96
	v_add_u32_e32 v96, 0x53, v170
	s_nop 0
	v_cndmask_b32_e32 v90, v233, v90, vcc
	v_cmp_gt_i32_e32 vcc, s94, v96
	v_add_u32_e32 v96, 32, v96
	s_nop 0
	v_cndmask_b32_e32 v75, v233, v75, vcc
	v_cmp_gt_i32_e32 vcc, s94, v96
	v_add_u32_e32 v96, 0x58, v170
	s_nop 0
	v_cndmask_b32_e32 v91, v233, v91, vcc
	v_cmp_gt_i32_e32 vcc, s94, v96
	v_add_u32_e32 v96, 32, v96
	s_nop 0
	v_cndmask_b32_e32 v76, v233, v76, vcc
	v_cmp_gt_i32_e32 vcc, s94, v96
	v_add_u32_e32 v96, 0x59, v170
	s_nop 0
	v_cndmask_b32_e32 v92, v233, v92, vcc
	v_cmp_gt_i32_e32 vcc, s94, v96
	v_add_u32_e32 v96, 32, v96
	s_nop 0
	v_cndmask_b32_e32 v77, v233, v77, vcc
	v_cmp_gt_i32_e32 vcc, s94, v96
	v_add_u32_e32 v96, 0x5a, v170
	s_nop 0
	v_cndmask_b32_e32 v93, v233, v93, vcc
	v_cmp_gt_i32_e32 vcc, s94, v96
	v_add_u32_e32 v96, 32, v96
	s_nop 0
	v_cndmask_b32_e32 v78, v233, v78, vcc
	v_cmp_gt_i32_e32 vcc, s94, v96
	v_add_u32_e32 v96, 0x5b, v170
	s_nop 0
	v_cndmask_b32_e32 v94, v233, v94, vcc
	v_cmp_gt_i32_e32 vcc, s94, v96
	v_add_u32_e32 v96, 32, v96
	s_nop 0
	v_cndmask_b32_e32 v79, v233, v79, vcc
	v_cmp_gt_i32_e32 vcc, s94, v96
	s_nop 1
	v_cndmask_b32_e32 v95, v233, v95, vcc
.LBB0_432:
	v_mov_b32_e32 v96, v157
	v_ashrrev_i32_e32 v97, 4, v96
	v_and_b32_e32 v99, 0xfffff0, v97
	v_lshlrev_b32_e32 v100, 1, v97
	v_add_u32_e32 v98, 32, v97
	v_and_or_b32 v99, v100, 8, v99
	v_lshrrev_b32_e32 v100, 1, v97
	v_and_b32_e32 v97, 3, v97
	v_and_or_b32 v97, v100, 4, v97
	v_and_b32_e32 v100, 0xfffff0, v98
	v_lshlrev_b32_e32 v98, 1, v98
	v_and_or_b32 v98, v98, 8, v100
	v_lshrrev_b32_e32 v99, 1, v99
	v_bfe_u32 v101, v96, 2, 2
	v_lshrrev_b32_e32 v98, 1, v98
	v_or_b32_e32 v99, v99, v101
	v_lshlrev_b32_e32 v96, 4, v96
	v_or_b32_e32 v98, v98, v101
	v_lshlrev_b32_e32 v99, 9, v99
	v_lshlrev_b32_e32 v97, 6, v97
	v_and_b32_e32 v96, 48, v96
	v_lshlrev_b32_e32 v98, 9, v98
	v_or3_b32 v99, v99, v97, v96
	v_or3_b32 v96, v98, v97, v96
	s_waitcnt vmcnt(0)
	s_barrier
	s_waitcnt vmcnt(0)
	ds_write_b128 v99, v[130:133]
	ds_write_b128 v96, v[124:127]
	v_exp_f32_e32 v64, v64
	v_exp_f32_e32 v66, v66
	v_exp_f32_e32 v68, v68
	v_exp_f32_e32 v70, v70
	v_exp_f32_e32 v72, v72
	v_exp_f32_e32 v74, v74
	v_exp_f32_e32 v76, v76
	v_exp_f32_e32 v78, v78
	v_exp_f32_e32 v65, v65
	v_exp_f32_e32 v67, v67
	v_exp_f32_e32 v69, v69
	v_exp_f32_e32 v71, v71
	v_exp_f32_e32 v73, v73
	v_exp_f32_e32 v75, v75
	v_exp_f32_e32 v77, v77
	v_exp_f32_e32 v79, v79
	s_waitcnt lgkmcnt(0)
	s_barrier
; __device__ __forceinline__ void finishSM(f32x16& p0, f32x16& p1, float& l_reg, bf16x8& pa0, bf16x8& pa1, bf16x8& pa2, bf16x8& pa3) {
; #pragma unroll
;   for (int r = 0; r < 16; ++r) p1[r] = __builtin_amdgcn_exp2f(p1[r]);
;   float ps = 0;
; #pragma unroll
;   for (int r = 0; r < 16; ++r) ps += p0[r];
; #pragma unroll
;   for (int r = 0; r < 16; ++r) ps += p1[r];
;   { auto rr = __builtin_amdgcn_permlane32_swap(__float_as_uint(ps), __float_as_uint(ps), false, false);
;     ps = __uint_as_float(rr[0]) + __uint_as_float(rr[1]); }
;   l_reg += ps;
;     ...
;   PK4(p0, 0, pa0); PK4(p0, 8, pa1); PK4(p1, 0, pa2); PK4(p1, 8, pa3);
;     ...
; }
; template <int DQK, int QL>
; __device__ __forceinline__ void qkt(f32x16& p0, f32x16& p1, const char* Ks, const bf16x8 (&qr)[DQK / 16 - QL], const char* qlds, const int (&kofs)[4], float negM) {
;   constexpr int QR = DQK / 16 - QL;
; #pragma unroll
;   for (int r = 0; r < 16; ++r) { p0[r] = negM; p1[r] = negM; }
; #pragma unroll
;   for (int d0 = 0; d0 < DQK / 16; ++d0) {
;     const char* kp = Ks + kofs[d0 & 3] + (d0 >> 2) * 128;
;     bf16x8 b0 = *reinterpret_cast<const bf16x8*>(kp);
;     bf16x8 b1 = *reinterpret_cast<const bf16x8*>(kp + 32 * DQK * 2);
;     bf16x8 qf;
;     if constexpr (QL > 0) { if (d0 < QR) qf = qr[d0 < QR ? d0 : 0]; else qf = *reinterpret_cast<const bf16x8*>(qlds + (d0 - QR) * 1024); }
;     else qf = qr[d0];
;     p0 = __builtin_amdgcn_mfma_f32_32x32x16_bf16(b0, qf, p0, 0, 0, 0);
;     p1 = __builtin_amdgcn_mfma_f32_32x32x16_bf16(b1, qf, p1, 0, 0, 0);
;   }
; }
	v_add_f32_e32 v96, 0, v64
	v_add_f32_e32 v96, v67, v96
	v_add_f32_e32 v172, v65, v68
	v_add_f32_e32 v173, v66, v69
	v_add_f32_e32 v96, v70, v96
	v_add_f32_e32 v172, v71, v172
	v_add_f32_e32 v173, v72, v173
	v_add_f32_e32 v96, v73, v96
	v_add_f32_e32 v172, v74, v172
	v_add_f32_e32 v173, v75, v173
	v_exp_f32_e32 v80, v80
	v_add_f32_e32 v96, v76, v96
	v_exp_f32_e32 v81, v81
	v_add_f32_e32 v172, v77, v172
	v_exp_f32_e32 v82, v82
	v_add_f32_e32 v173, v78, v173
	v_exp_f32_e32 v83, v83
	v_add_f32_e32 v96, v79, v96
	v_exp_f32_e32 v84, v84
	v_add_f32_e32 v172, v80, v172
	v_exp_f32_e32 v85, v85
	v_add_f32_e32 v173, v81, v173
	v_exp_f32_e32 v86, v86
	v_add_f32_e32 v96, v82, v96
	v_exp_f32_e32 v87, v87
	v_add_f32_e32 v172, v83, v172
	v_exp_f32_e32 v88, v88
	v_add_f32_e32 v173, v84, v173
	v_exp_f32_e32 v89, v89
	v_add_f32_e32 v96, v85, v96
	v_exp_f32_e32 v90, v90
	v_add_f32_e32 v172, v86, v172
	v_exp_f32_e32 v91, v91
	v_add_f32_e32 v173, v87, v173
	v_exp_f32_e32 v92, v92
	v_add_f32_e32 v96, v88, v96
	v_exp_f32_e32 v93, v93
	v_add_f32_e32 v172, v89, v172
	v_exp_f32_e32 v94, v94
	v_add_f32_e32 v173, v90, v173
	v_exp_f32_e32 v95, v95
	v_add_f32_e32 v96, v91, v96
	v_add_f32_e32 v172, v92, v172
	v_add_f32_e32 v173, v93, v173
	v_add_f32_e32 v96, v94, v96
	v_add_f32_e32 v172, v95, v172
	v_add_f32_e32 v172, v96, v172
	v_add_f32_e32 v172, v173, v172
	v_mov_b32_e32 v173, v172
	v_cvt_pk_bf16_f32 v134, v64, v65
	v_cvt_pk_bf16_f32 v135, v66, v67
	v_cvt_pk_bf16_f32 v136, v68, v69
	v_cvt_pk_bf16_f32 v137, v70, v71
	v_cvt_pk_bf16_f32 v138, v72, v73
	v_cvt_pk_bf16_f32 v139, v74, v75
	v_cvt_pk_bf16_f32 v140, v76, v77
	v_cvt_pk_bf16_f32 v141, v78, v79
	v_cvt_pk_bf16_f32 v142, v80, v81
	v_cvt_pk_bf16_f32 v143, v82, v83
	v_cvt_pk_bf16_f32 v144, v84, v85
	v_cvt_pk_bf16_f32 v145, v86, v87
	v_cvt_pk_bf16_f32 v146, v88, v89
	v_cvt_pk_bf16_f32 v147, v90, v91
	v_cvt_pk_bf16_f32 v148, v92, v93
	v_cvt_pk_bf16_f32 v149, v94, v95
	s_nop 1
	v_permlane32_swap_b32_e32 v172, v173
	v_permlane32_swap_b32_e32 v134, v136
	v_permlane32_swap_b32_e32 v135, v137
	v_permlane32_swap_b32_e32 v138, v140
	v_permlane32_swap_b32_e32 v139, v141
	v_permlane32_swap_b32_e32 v142, v144
	v_permlane32_swap_b32_e32 v143, v145
	v_permlane32_swap_b32_e32 v146, v148
	v_permlane32_swap_b32_e32 v147, v149
	ds_read_b128 v[64:67], v153 offset:32768
	ds_read_b128 v[174:177], v153 offset:45056
	v_mov_b64_e32 v[110:111], s[18:19]
	v_mov_b64_e32 v[108:109], s[16:17]
	v_mov_b64_e32 v[106:107], s[14:15]
	v_mov_b64_e32 v[104:105], s[12:13]
	v_mov_b64_e32 v[102:103], s[10:11]
	v_mov_b64_e32 v[100:101], s[8:9]
	v_mov_b64_e32 v[98:99], s[6:7]
	v_mov_b64_e32 v[96:97], s[4:5]
	s_waitcnt lgkmcnt(1)
	s_nop 0
	v_mfma_f32_32x32x16_bf16 v[80:95], v[64:67], v[120:123], v[96:111]
	s_waitcnt lgkmcnt(0)
	v_mfma_f32_32x32x16_bf16 v[64:79], v[174:177], v[120:123], v[96:111]
	s_nop 6
	ds_read_b128 v[96:99], v152 offset:32768
	ds_read_b128 v[100:103], v152 offset:45056
	s_waitcnt lgkmcnt(1)
	v_mfma_f32_32x32x16_bf16 v[80:95], v[96:99], v[116:119], v[80:95]
	s_waitcnt lgkmcnt(0)
	v_mfma_f32_32x32x16_bf16 v[64:79], v[100:103], v[116:119], v[64:79]
	ds_read_b128 v[96:99], v151 offset:32768
	ds_read_b128 v[100:103], v151 offset:45056
	s_waitcnt lgkmcnt(1)
	v_mfma_f32_32x32x16_bf16 v[80:95], v[96:99], v[112:115], v[80:95]
	s_waitcnt lgkmcnt(0)
	v_mfma_f32_32x32x16_bf16 v[64:79], v[100:103], v[112:115], v[64:79]
	ds_read_b128 v[96:99], v150 offset:32768
	ds_read_b128 v[100:103], v150 offset:45056
	ds_read_b128 v[104:107], v171
	s_waitcnt lgkmcnt(0)
	v_mfma_f32_32x32x16_bf16 v[80:95], v[96:99], v[104:107], v[80:95]
	v_mfma_f32_32x32x16_bf16 v[64:79], v[100:103], v[104:107], v[64:79]
	ds_read_b128 v[96:99], v153 offset:32896
	ds_read_b128 v[100:103], v153 offset:45184
	ds_read_b128 v[104:107], v171 offset:1024
	s_waitcnt lgkmcnt(0)
	v_mfma_f32_32x32x16_bf16 v[80:95], v[96:99], v[104:107], v[80:95]
	v_mfma_f32_32x32x16_bf16 v[64:79], v[100:103], v[104:107], v[64:79]
	ds_read_b128 v[96:99], v152 offset:32896
	ds_read_b128 v[100:103], v152 offset:45184
	ds_read_b128 v[104:107], v171 offset:2048
	s_waitcnt lgkmcnt(0)
	v_mfma_f32_32x32x16_bf16 v[80:95], v[96:99], v[104:107], v[80:95]
	v_mfma_f32_32x32x16_bf16 v[64:79], v[100:103], v[104:107], v[64:79]
	ds_read_b128 v[96:99], v151 offset:32896
	ds_read_b128 v[100:103], v151 offset:45184
	ds_read_b128 v[104:107], v171 offset:3072
	s_waitcnt lgkmcnt(0)
	v_mfma_f32_32x32x16_bf16 v[80:95], v[96:99], v[104:107], v[80:95]
	v_mfma_f32_32x32x16_bf16 v[64:79], v[100:103], v[104:107], v[64:79]
	ds_read_b128 v[96:99], v150 offset:32896
	ds_read_b128 v[100:103], v150 offset:45184
	ds_read_b128 v[104:107], v171 offset:4096
	s_waitcnt lgkmcnt(0)
	v_mfma_f32_32x32x16_bf16 v[80:95], v[96:99], v[104:107], v[80:95]
	v_mfma_f32_32x32x16_bf16 v[64:79], v[100:103], v[104:107], v[64:79]
	ds_read_b128 v[96:99], v153 offset:33024
	ds_read_b128 v[100:103], v153 offset:45312
	ds_read_b128 v[104:107], v171 offset:5120
	s_waitcnt lgkmcnt(0)
	v_mfma_f32_32x32x16_bf16 v[80:95], v[96:99], v[104:107], v[80:95]
	v_mfma_f32_32x32x16_bf16 v[64:79], v[100:103], v[104:107], v[64:79]
	ds_read_b128 v[96:99], v152 offset:33024
	ds_read_b128 v[100:103], v152 offset:45312
	ds_read_b128 v[104:107], v171 offset:6144
	s_waitcnt lgkmcnt(0)
	v_mfma_f32_32x32x16_bf16 v[80:95], v[96:99], v[104:107], v[80:95]
	v_mfma_f32_32x32x16_bf16 v[64:79], v[100:103], v[104:107], v[64:79]
	ds_read_b128 v[96:99], v151 offset:33024
	ds_read_b128 v[100:103], v151 offset:45312
	ds_read_b128 v[104:107], v171 offset:7168
	s_waitcnt lgkmcnt(0)
	v_mfma_f32_32x32x16_bf16 v[80:95], v[96:99], v[104:107], v[80:95]
	v_mfma_f32_32x32x16_bf16 v[64:79], v[100:103], v[104:107], v[64:79]
	ds_read_b128 v[96:99], v150 offset:33024
	ds_read_b128 v[100:103], v150 offset:45312
	ds_read_b128 v[104:107], v171 offset:8192
	s_waitcnt lgkmcnt(0)
	v_mfma_f32_32x32x16_bf16 v[80:95], v[96:99], v[104:107], v[80:95]
	v_mfma_f32_32x32x16_bf16 v[64:79], v[100:103], v[104:107], v[64:79]
	s_cmp_lt_i32 s22, s54
	s_cselect_b64 s[20:21], -1, 0
	s_cmp_ge_i32 s22, s54
	s_cbranch_scc1 .LBB0_434
; __device__ __forceinline__ int v_rd_base(int lane) { return ((lane & 3) << 3) | (((lane >> 2) & 3) << 6) | (((lane >> 4) & 1) << 5) | (((lane >> 5) & 1) << 8); }
; #define V_COORDS(T) do { if constexpr (VC == 2) { const int sr = (T) >> 4, sc = ((T) & 15) * 8; vgo[0] = sr * LDV + sc; vgo[VC - 1] = (32 + sr) * LDV + sc; vlo[0] = v_st<NCB>(sr, sc); vlo[VC - 1] = v_st<NCB>(32 + sr, sc); } \
;     else { const int sr = (T) >> 3, sc = ((T) & 7) * 8; vgo[0] = sr * LDV + sc; vlo[0] = v_st<NCB>(sr, sc); } } while (0)
;     ...
;   if constexpr (KDMA) {
;   } else {
; #pragma unroll
;     for (int i = 0; i < KC; ++i) { const int c = tid + i * 512, row = c / CPR, cc = c % CPR; kgo[i] = row * LDK + cc * 8; klo[i] = K_OFF + KSWZ(KRS, row, cc * 16); }
;     V_COORDS(tid);
;   }
;   const int vb0 = (int)(uintptr_t)shm + v_rd_base(lane);
;   int kofs[4];
; #pragma unroll
;   for (int b = 0; b < 4; ++b) kofs[b] = (r32 ^ ((r32 >> 3) & 1)) * KRS + ((b * 32 + hi * 16) ^ ((r32 & 7) << 4));
;   bf16x8 ks[KC], vs[VC];
	v_mov_b32_e32 v97, v157
	s_add_i32 vcc_lo, s23, 0xc0
	v_mul_hi_i32 v99, v97, s82
	v_lshrrev_b32_e32 v100, 31, v99
	v_ashrrev_i32_e32 v99, 2, v99
	v_add_u32_e32 v99, v99, v100
	v_mul_lo_u32 v100, v99, 24
	v_lshrrev_b32_e32 v101, 3, v99
	v_sub_u32_e32 v100, v97, v100
	v_bitop3_b32 v99, v101, v99, 1 bitop3:0x6c
	v_bitop3_b32 v100, v99, v100, 7 bitop3:0x6c
	v_mul_lo_u32 v99, v99, s85
	v_lshl_add_u32 v100, v100, 3, v99
	v_add_u32_e32 v99, 0x200, v97
	v_mul_hi_i32 v101, v99, s82
	v_lshrrev_b32_e32 v102, 31, v101
	v_ashrrev_i32_e32 v101, 2, v101
	v_add_u32_e32 v101, v101, v102
	v_mul_lo_u32 v102, v101, 24
	v_sub_u32_e32 v99, v99, v102
	v_lshrrev_b32_e32 v102, 3, v101
	v_bitop3_b32 v101, v102, v101, 1 bitop3:0x6c
	v_lshlrev_b32_e32 v96, 3, v97
	v_lshlrev_b32_e32 v98, 5, v97
	v_bitop3_b32 v99, v101, v99, 7 bitop3:0x6c
	v_mul_lo_u32 v101, v101, s85
	v_add_u32_e32 v97, 0x400, v97
	v_lshl_add_u32 v102, v99, 3, v101
	v_mul_hi_i32 v99, v97, s82
	v_lshrrev_b32_e32 v101, 31, v99
	v_ashrrev_i32_e32 v99, 2, v99
	v_add_u32_e32 v99, v99, v101
	v_mul_lo_u32 v101, v99, 24
	v_sub_u32_e32 v97, v97, v101
	v_lshrrev_b32_e32 v101, 3, v99
	v_bitop3_b32 v99, v101, v99, 1 bitop3:0x6c
	s_ashr_i32 vcc_hi, vcc_lo, 31
	s_mul_i32 s38, vcc_lo, 0x600
	v_bitop3_b32 v97, v99, v97, 7 bitop3:0x6c
	v_mul_lo_u32 v99, v99, s85
	s_mul_hi_i32 s23, vcc_lo, 0x600
	s_add_u32 s38, s3, s38
	v_lshl_add_u32 v104, v97, 3, v99
	s_addc_u32 s39, s36, s23
	v_ashrrev_i32_e32 v101, 31, v100
	v_readfirstlane_b32 s23, v167
	v_add_u32_e32 v97, 0x2000, v167
	v_lshl_add_u64 v[100:101], v[100:101], 1, s[38:39]
	s_mov_b32 m0, s23
	v_ashrrev_i32_e32 v103, 31, v102
	v_readfirstlane_b32 s23, v97
	global_load_lds_dwordx4 v[100:101], off
	v_lshl_add_u64 v[100:101], v[102:103], 1, s[38:39]
	s_mov_b32 m0, s23
	v_ashrrev_i32_e32 v105, 31, v104
	v_and_b32_e32 v96, 0x78, v96
	global_load_lds_dwordx4 v[100:101], off
	v_lshl_add_u64 v[100:101], v[104:105], 1, s[38:39]
	v_add_u32_e32 v97, 0x4000, v167
	s_lshl_b64 s[38:39], vcc, 10
	v_and_or_b32 v96, v98, s24, v96
	v_readfirstlane_b32 s23, v97
	s_add_u32 s38, s83, s38
	v_add_u32_e32 v98, 0x4000, v96
	s_mov_b32 m0, s23
	s_addc_u32 s39, s93, s39
	v_ashrrev_i32_e32 v97, 31, v96
	global_load_lds_dwordx4 v[100:101], off
	v_lshl_add_u64 v[96:97], v[96:97], 1, s[38:39]
	v_ashrrev_i32_e32 v99, 31, v98
	v_lshl_add_u64 v[98:99], v[98:99], 1, s[38:39]
	global_load_dwordx4 v[130:133], v[96:97], off
	global_load_dwordx4 v[124:127], v[98:99], off

; __device__ __forceinline__ void finishSM(f32x16& p0, f32x16& p1, float& l_reg, bf16x8& pa0, bf16x8& pa1, bf16x8& pa2, bf16x8& pa3) {
; #pragma unroll
;   for (int r = 0; r < 16; ++r) p1[r] = __builtin_amdgcn_exp2f(p1[r]);
;   float ps = 0;
; #pragma unroll
;   for (int r = 0; r < 16; ++r) ps += p0[r];
; #pragma unroll
;   for (int r = 0; r < 16; ++r) ps += p1[r];
;   { auto rr = __builtin_amdgcn_permlane32_swap(__float_as_uint(ps), __float_as_uint(ps), false, false);
;     ps = __uint_as_float(rr[0]) + __uint_as_float(rr[1]); }
;   l_reg += ps;
;     ...
;   PK4(p0, 0, pa0); PK4(p0, 8, pa1); PK4(p1, 0, pa2); PK4(p1, 8, pa3);
;     ...
; }
; template <int DQK, int QL>
; __device__ __forceinline__ void qkt(f32x16& p0, f32x16& p1, const char* Ks, const bf16x8 (&qr)[DQK / 16 - QL], const char* qlds, const int (&kofs)[4], float negM) {
;   constexpr int QR = DQK / 16 - QL;
; #pragma unroll
;   for (int r = 0; r < 16; ++r) { p0[r] = negM; p1[r] = negM; }
; #pragma unroll
;   for (int d0 = 0; d0 < DQK / 16; ++d0) {
;     const char* kp = Ks + kofs[d0 & 3] + (d0 >> 2) * 128;
;     bf16x8 b0 = *reinterpret_cast<const bf16x8*>(kp);
;     bf16x8 b1 = *reinterpret_cast<const bf16x8*>(kp + 32 * DQK * 2);
;     bf16x8 qf;
;     if constexpr (QL > 0) { if (d0 < QR) qf = qr[d0 < QR ? d0 : 0]; else qf = *reinterpret_cast<const bf16x8*>(qlds + (d0 - QR) * 1024); }
;     else qf = qr[d0];
;     p0 = __builtin_amdgcn_mfma_f32_32x32x16_bf16(b0, qf, p0, 0, 0, 0);
;     p1 = __builtin_amdgcn_mfma_f32_32x32x16_bf16(b1, qf, p1, 0, 0, 0);
;   }
; }
; template <int NCB> __device__ __forceinline__ int v_st(int k, int c) {
;   const int kk = (k & ~0xC) | ((k & 4) << 1) | ((k & 8) >> 1);
;   return ((kk >> 3) * NCB + (c >> 5)) * 512 + ((kk & 7) * 32 + (c & 31)) * 2;
; }
; __device__ __forceinline__ int v_rd_base(int lane) { return ((lane & 3) << 3) | (((lane >> 2) & 3) << 6) | (((lane >> 4) & 1) << 5) | (((lane >> 5) & 1) << 8); }
; template <int OFF> __device__ __forceinline__ s16x4 tr_read(int vb) {
;   s16x4 r; asm volatile("ds_read_b64_tr_b16 %0, %1 offset:%2" : "=&v"(r) : "v"(vb), "i"(OFF) : "memory"); return r;
; }
; template <int NCB, int D0> __device__ __forceinline__ void pv_one(f32x16& od, int vb, bf16x8 pa0, bf16x8 pa1, bf16x8 pa2, bf16x8 pa3) {
;   constexpr int KSTEP = NCB * 1024, HALF = NCB * 512, B0 = D0 * 512;
.LBB0_650:
	ds_read_b128 v[40:43], v150 offset:40960
	ds_read_b128 v[158:161], v150 offset:45056
	s_waitcnt vmcnt(0)
	v_mov_b64_e32 v[110:111], s[18:19]
	v_mov_b64_e32 v[108:109], s[16:17]
	v_mov_b64_e32 v[106:107], s[14:15]
	v_mov_b64_e32 v[104:105], s[12:13]
	v_mov_b64_e32 v[102:103], s[10:11]
	v_mov_b64_e32 v[100:101], s[8:9]
	v_mov_b64_e32 v[98:99], s[6:7]
	v_mov_b64_e32 v[96:97], s[4:5]
	s_waitcnt lgkmcnt(1)
	s_nop 0
	v_mfma_f32_32x32x16_bf16 v[56:71], v[40:43], v[124:127], v[96:111]
	s_waitcnt lgkmcnt(0)
	v_mfma_f32_32x32x16_bf16 v[40:55], v[158:161], v[124:127], v[96:111]
	s_nop 6
	ds_read_b128 v[96:99], v148 offset:40960
	ds_read_b128 v[100:103], v148 offset:45056
	s_waitcnt lgkmcnt(1)
	v_mfma_f32_32x32x16_bf16 v[56:71], v[96:99], v[120:123], v[56:71]
	s_waitcnt lgkmcnt(0)
	v_mfma_f32_32x32x16_bf16 v[40:55], v[100:103], v[120:123], v[40:55]
	ds_read_b128 v[96:99], v147 offset:40960
	ds_read_b128 v[100:103], v147 offset:45056
	s_waitcnt lgkmcnt(1)
	v_mfma_f32_32x32x16_bf16 v[56:71], v[96:99], v[116:119], v[56:71]
	s_waitcnt lgkmcnt(0)
	v_mfma_f32_32x32x16_bf16 v[40:55], v[100:103], v[116:119], v[40:55]
	ds_read_b128 v[96:99], v146 offset:40960
	ds_read_b128 v[100:103], v146 offset:45056
	s_waitcnt lgkmcnt(1)
	v_mfma_f32_32x32x16_bf16 v[56:71], v[96:99], v[112:115], v[56:71]
	v_exp_f32_e32 v96, v32
	v_add_f32_e32 v32, 0, v90
	v_add_f32_e32 v32, v87, v32
	v_add_f32_e32 v104, v91, v86
	v_add_f32_e32 v105, v88, v85
	v_add_f32_e32 v32, v82, v32
	v_add_f32_e32 v104, v81, v104
	v_add_f32_e32 v105, v74, v105
	v_add_f32_e32 v32, v75, v32
	v_add_f32_e32 v104, v76, v104
	v_add_f32_e32 v105, v77, v105
	v_add_f32_e32 v32, v78, v32
	v_exp_f32_e32 v97, v33
	v_add_f32_e32 v104, v79, v104
	v_exp_f32_e32 v98, v34
	v_add_f32_e32 v105, v80, v105
	v_exp_f32_e32 v99, v35
	v_add_f32_e32 v32, v83, v32
	s_waitcnt lgkmcnt(0)
	v_mfma_f32_32x32x16_bf16 v[40:55], v[100:103], v[112:115], v[40:55]
	v_exp_f32_e32 v100, v36
	v_add_f32_e32 v104, v96, v104
	v_exp_f32_e32 v101, v37
	v_add_f32_e32 v105, v97, v105
	v_exp_f32_e32 v102, v38
	v_add_f32_e32 v32, v98, v32
	v_exp_f32_e32 v103, v39
	v_add_f32_e32 v104, v99, v104
	v_exp_f32_e32 v36, v72
	v_add_f32_e32 v105, v100, v105
	v_exp_f32_e32 v37, v73
	v_add_f32_e32 v32, v101, v32
	v_exp_f32_e32 v38, v84
	v_add_f32_e32 v104, v102, v104
	v_exp_f32_e32 v39, v89
	v_add_f32_e32 v105, v103, v105
	v_exp_f32_e32 v72, v92
	v_add_f32_e32 v32, v36, v32
	v_exp_f32_e32 v73, v93
	v_add_f32_e32 v104, v37, v104
	v_exp_f32_e32 v84, v94
	v_add_f32_e32 v105, v38, v105
	v_exp_f32_e32 v89, v95
	v_add_f32_e32 v32, v39, v32
	v_add_f32_e32 v104, v72, v104
	v_add_f32_e32 v105, v73, v105
	v_add_f32_e32 v32, v84, v32
	v_add_f32_e32 v104, v89, v104
	v_add_f32_e32 v104, v32, v104
	v_add_f32_e32 v104, v105, v104
	v_mov_b32_e32 v105, v104
	v_cvt_pk_bf16_f32 v32, v90, v91
	v_cvt_pk_bf16_f32 v33, v88, v87
	v_cvt_pk_bf16_f32 v34, v86, v85
	v_cvt_pk_bf16_f32 v35, v82, v81
	s_nop 1
	v_permlane32_swap_b32_e32 v104, v105
	v_permlane32_swap_b32_e32 v32, v34
	v_permlane32_swap_b32_e32 v33, v35
	v_cvt_pk_bf16_f32 v74, v74, v75
	v_cvt_pk_bf16_f32 v75, v76, v77
	v_cvt_pk_bf16_f32 v76, v78, v79
	v_cvt_pk_bf16_f32 v77, v80, v83
	v_cvt_pk_bf16_f32 v78, v96, v97
	v_cvt_pk_bf16_f32 v79, v98, v99
	v_cvt_pk_bf16_f32 v80, v100, v101
	v_cvt_pk_bf16_f32 v81, v102, v103
	v_cvt_pk_bf16_f32 v36, v36, v37
	v_cvt_pk_bf16_f32 v37, v38, v39
	v_cvt_pk_bf16_f32 v38, v72, v73
	v_cvt_pk_bf16_f32 v39, v84, v89
	s_nop 0
	v_permlane32_swap_b32_e32 v74, v76
	v_permlane32_swap_b32_e32 v75, v77
	v_permlane32_swap_b32_e32 v78, v80
	v_permlane32_swap_b32_e32 v79, v81
	v_permlane32_swap_b32_e32 v36, v38
	v_permlane32_swap_b32_e32 v37, v39
	v_mad_i64_i32 v[72:73], s[20:21], s97, v237, v[134:135]
	v_mad_i64_i32 v[82:83], s[20:21], s97, v237, v[136:137]
	global_load_dwordx4 v[96:99], v[72:73], off offset:1024
	global_load_dwordx4 v[100:103], v[82:83], off offset:1280
	ds_read_b64_tr_b16 v[82:83], v156 offset:0
	ds_read_b64_tr_b16 v[84:85], v156 offset:0x400
	ds_read_b64_tr_b16 v[86:87], v156 offset:0x800
	ds_read_b64_tr_b16 v[88:89], v156 offset:0xc00
	ds_read_b64_tr_b16 v[90:91], v156 offset:0x1000
	ds_read_b64_tr_b16 v[92:93], v156 offset:0x1400
	ds_read_b64_tr_b16 v[106:107], v156 offset:0x1800
	ds_read_b64_tr_b16 v[108:109], v156 offset:0x1c00
	s_nop 0
	s_waitcnt lgkmcnt(6)
	v_mfma_f32_32x32x16_bf16 v[0:15], v[32:35], v[82:85], v[0:15]
	ds_read_b64_tr_b16 v[82:83], v156 offset:0x200
	ds_read_b64_tr_b16 v[84:85], v156 offset:0x600
	s_waitcnt lgkmcnt(6)
	v_mfma_f32_32x32x16_bf16 v[0:15], v[74:77], v[86:89], v[0:15]
	ds_read_b64_tr_b16 v[86:87], v156 offset:0xa00
	ds_read_b64_tr_b16 v[88:89], v156 offset:0xe00
	s_waitcnt lgkmcnt(6)
	v_mfma_f32_32x32x16_bf16 v[0:15], v[78:81], v[90:93], v[0:15]
	ds_read_b64_tr_b16 v[90:91], v156 offset:0x1200
	ds_read_b64_tr_b16 v[92:93], v156 offset:0x1600
	s_waitcnt lgkmcnt(6)
	v_mfma_f32_32x32x16_bf16 v[0:15], v[36:39], v[106:109], v[0:15]
	ds_read_b64_tr_b16 v[106:107], v156 offset:0x1a00
	ds_read_b64_tr_b16 v[108:109], v156 offset:0x1e00
	s_waitcnt lgkmcnt(6)
	v_mfma_f32_32x32x16_bf16 v[16:31], v[32:35], v[82:85], v[16:31]
	v_add_u32_e32 v82, s97, v151
	v_subrev_u32_e32 v34, 64, v82
	v_mov_b32_e32 v32, 0xf149f2ca
	v_cmp_gt_i32_e32 vcc, s94, v34
	v_mov_b32_e32 v33, 0xf149f2ca
	s_waitcnt lgkmcnt(4)
	v_mfma_f32_32x32x16_bf16 v[16:31], v[74:77], v[86:89], v[16:31]
	s_waitcnt lgkmcnt(2)
	v_mfma_f32_32x32x16_bf16 v[16:31], v[78:81], v[90:93], v[16:31]
	s_waitcnt lgkmcnt(0)
	v_mfma_f32_32x32x16_bf16 v[16:31], v[36:39], v[106:109], v[16:31]
	v_readfirstlane_b32 s100, v34
	v_readfirstlane_b32 s101, v145
	s_nop 0
	s_add_i32 s98, s100, 0x61
	s_cmp_ge_i32 s98, s101
	s_cbranch_scc0 .Lgq_slow_1
	s_add_i32 s98, s101, 0x41
	s_cmp_le_i32 s100, s98
	s_cbranch_scc0 .Lgq_slow_1
	s_add_i32 s98, s100, 64
	s_cmp_le_i32 s98, s94
	s_cbranch_scc0 .Lgq_slow_1
	v_mov_b32_e32 v33, v56
	v_mov_b32_e32 v32, v40
	v_mov_b32_e32 v34, v57
	v_mov_b32_e32 v83, v41
	v_mov_b32_e32 v35, v58
	v_mov_b32_e32 v84, v42
	v_mov_b32_e32 v36, v59
	v_mov_b32_e32 v85, v43
	v_mov_b32_e32 v37, v60
	v_mov_b32_e32 v86, v44
	v_mov_b32_e32 v38, v61
	v_mov_b32_e32 v87, v45
	v_mov_b32_e32 v39, v62
	v_mov_b32_e32 v88, v46
	v_mov_b32_e32 v40, v63
	v_mov_b32_e32 v89, v47
	v_mov_b32_e32 v41, v64
	v_mov_b32_e32 v90, v48
	v_mov_b32_e32 v42, v65
	v_mov_b32_e32 v91, v49
	v_mov_b32_e32 v43, v66
	v_mov_b32_e32 v92, v50
	v_mov_b32_e32 v44, v67
	v_mov_b32_e32 v93, v51
	v_mov_b32_e32 v45, v68
	v_mov_b32_e32 v94, v52
	v_mov_b32_e32 v46, v69
	v_mov_b32_e32 v95, v53
	v_mov_b32_e32 v47, v70
	v_mov_b32_e32 v106, v54
	v_mov_b32_e32 v48, v71
	v_mov_b32_e32 v107, v55
	s_branch .Lgq_end_1

; #define WAIT_V0() asm volatile("s_waitcnt vmcnt(0)" ::: "memory")
; #define SBAR() __builtin_amdgcn_sched_barrier(0)
; #define SWRITE(b) do { FRESH_COORDS(); \
;     if constexpr (!KDMA) { _Pragma("unroll") for (int i = 0; i < KC; ++i) *reinterpret_cast<bf16x8*>(shm + (b) * SHM_K + klo[i]) = ks[i]; } \
;     _Pragma("unroll") for (int i = 0; i < VC; ++i) *reinterpret_cast<bf16x8*>(shm + (b) * SHM_V + vlo[i]) = vs[i]; } while (0)
; #define QKT(P0, P1, BUF) qkt<DQK, QL>(P0, P1, shm + K_OFF + (BUF) * SHM_K, qr, qlds, kofs, negM)
; __device__ __forceinline__ void finishSM(f32x16& p0, f32x16& p1, float& l_reg, bf16x8& pa0, bf16x8& pa1, bf16x8& pa2, bf16x8& pa3) {
; #pragma unroll
;   for (int r = 0; r < 16; ++r) p1[r] = __builtin_amdgcn_exp2f(p1[r]);
;   float ps = 0;
; #pragma unroll
;   for (int r = 0; r < 16; ++r) ps += p0[r];
; #pragma unroll
;   for (int r = 0; r < 16; ++r) ps += p1[r];
;   { auto rr = __builtin_amdgcn_permlane32_swap(__float_as_uint(ps), __float_as_uint(ps), false, false);
;     ps = __uint_as_float(rr[0]) + __uint_as_float(rr[1]); }
;   l_reg += ps;
;     ...
;   PK4(p0, 0, pa0); PK4(p0, 8, pa1); PK4(p1, 0, pa2); PK4(p1, 8, pa3);
;     ...
; }
;     ...
;     __syncthreads(); WAIT_V0(); SWRITE(0);
;     __syncthreads();
;     SBAR();
;     if constexpr (ONEP) { finishSM(pB0, pB1, l_reg, pa0, pa1, pa2, pa3); SBAR(); QKT(pA0, pA1, 0); }
;     else { QKT(pA0, pA1, 0); finishSM(pB0, pB1, l_reg, pa0, pa1, pa2, pa3); }
;     SBAR();
;     if (j + 2 < NT) SLOAD(TKEY(j + 2), 1);
.Lgq_end_1:
	s_barrier
	s_waitcnt vmcnt(0)
	ds_write_b128 v154, v[96:99] offset:32768
	ds_write_b128 v153, v[100:103]
	v_exp_f32_e32 v33, v33
	v_exp_f32_e32 v157, v34
	v_exp_f32_e32 v158, v35
	v_exp_f32_e32 v159, v36
	v_exp_f32_e32 v160, v37
	v_exp_f32_e32 v161, v38
	v_exp_f32_e32 v162, v39
	v_exp_f32_e32 v163, v40
	v_exp_f32_e32 v164, v41
	v_exp_f32_e32 v165, v42
	v_exp_f32_e32 v166, v43
	v_exp_f32_e32 v167, v44
	v_exp_f32_e32 v168, v45
	v_exp_f32_e32 v169, v46
	v_exp_f32_e32 v170, v47
	v_exp_f32_e32 v171, v48
	s_waitcnt lgkmcnt(0)
	s_barrier
	ds_read_b128 v[34:37], v150 offset:32768
	ds_read_b128 v[108:111], v150 offset:36864
	v_mov_b64_e32 v[80:81], s[18:19]
	v_mov_b64_e32 v[78:79], s[16:17]
	v_mov_b64_e32 v[76:77], s[14:15]
	v_mov_b64_e32 v[74:75], s[12:13]
	v_mov_b64_e32 v[72:73], s[10:11]
	v_mov_b64_e32 v[70:71], s[8:9]
	v_mov_b64_e32 v[68:69], s[6:7]
	v_mov_b64_e32 v[66:67], s[4:5]
	v_exp_f32_e32 v32, v32
	s_waitcnt lgkmcnt(1)
	v_mfma_f32_32x32x16_bf16 v[50:65], v[34:37], v[124:127], v[66:81]
	s_waitcnt lgkmcnt(0)
	v_mfma_f32_32x32x16_bf16 v[34:49], v[108:111], v[124:127], v[66:81]
	s_nop 6
	ds_read_b128 v[66:69], v148 offset:32768
	ds_read_b128 v[70:73], v148 offset:36864
	v_exp_f32_e32 v80, v87
	v_exp_f32_e32 v81, v88
	v_exp_f32_e32 v87, v92
	v_exp_f32_e32 v88, v93
	v_exp_f32_e32 v92, v107
	s_waitcnt lgkmcnt(1)
	v_mfma_f32_32x32x16_bf16 v[50:65], v[66:69], v[120:123], v[50:65]
	s_waitcnt lgkmcnt(0)
	v_mfma_f32_32x32x16_bf16 v[34:49], v[70:73], v[120:123], v[34:49]
	ds_read_b128 v[66:69], v147 offset:32768
	ds_read_b128 v[70:73], v147 offset:36864
	s_waitcnt lgkmcnt(1)
	v_mfma_f32_32x32x16_bf16 v[50:65], v[66:69], v[116:119], v[50:65]
	s_waitcnt lgkmcnt(0)
	v_mfma_f32_32x32x16_bf16 v[34:49], v[70:73], v[116:119], v[34:49]
	ds_read_b128 v[66:69], v146 offset:32768
	ds_read_b128 v[70:73], v146 offset:36864
	s_waitcnt lgkmcnt(1)
	v_mfma_f32_32x32x16_bf16 v[50:65], v[66:69], v[112:115], v[50:65]
	v_add_f32_e32 v66, 0, v33
	v_add_f32_e32 v66, v66, v157
	v_add_f32_e32 v66, v66, v158
	v_add_f32_e32 v66, v66, v159
	v_add_f32_e32 v66, v66, v160
	v_add_f32_e32 v66, v66, v161
	v_add_f32_e32 v66, v66, v162
	v_add_f32_e32 v66, v66, v163
	v_add_f32_e32 v66, v66, v164
	v_add_f32_e32 v66, v66, v165
	v_add_f32_e32 v66, v66, v166
	v_add_f32_e32 v66, v66, v167
	v_add_f32_e32 v66, v66, v168
	s_waitcnt lgkmcnt(0)
	v_mfma_f32_32x32x16_bf16 v[34:49], v[70:73], v[112:115], v[34:49]
	v_exp_f32_e32 v70, v83
	v_exp_f32_e32 v71, v84
	v_add_f32_e32 v66, v66, v170
	v_exp_f32_e32 v72, v85
	v_add_f32_e32 v83, v169, v171
	v_exp_f32_e32 v73, v86
	v_add_f32_e32 v66, v32, v66
	v_add_f32_e32 v83, v70, v83
	v_add_f32_e32 v66, v71, v66
	v_exp_f32_e32 v84, v89
	v_add_f32_e32 v83, v72, v83
	v_exp_f32_e32 v85, v90
	v_add_f32_e32 v66, v73, v66
	v_exp_f32_e32 v86, v91
	v_add_f32_e32 v83, v80, v83
	v_add_f32_e32 v66, v81, v66
	v_add_f32_e32 v83, v84, v83
	v_exp_f32_e32 v89, v94
	v_add_f32_e32 v66, v85, v66
	v_exp_f32_e32 v90, v95
	v_add_f32_e32 v83, v86, v83
	v_exp_f32_e32 v91, v106
	v_add_f32_e32 v66, v87, v66
	v_add_f32_e32 v83, v88, v83
	v_add_f32_e32 v66, v89, v66
	v_add_f32_e32 v83, v90, v83
	v_add_f32_e32 v66, v91, v66
	v_add_f32_e32 v83, v92, v83
	v_add_f32_e32 v83, v66, v83
	v_mov_b32_e32 v106, v83
	v_cvt_pk_bf16_f32 v66, v33, v157
	v_cvt_pk_bf16_f32 v67, v158, v159
	v_cvt_pk_bf16_f32 v68, v160, v161
	v_cvt_pk_bf16_f32 v69, v162, v163
	v_cvt_pk_bf16_f32 v74, v164, v165
	v_cvt_pk_bf16_f32 v75, v166, v167
	v_cvt_pk_bf16_f32 v76, v168, v169
	v_cvt_pk_bf16_f32 v77, v170, v171
	v_cvt_pk_bf16_f32 v78, v32, v70
	v_cvt_pk_bf16_f32 v79, v71, v72
	v_cvt_pk_bf16_f32 v80, v73, v80
	v_cvt_pk_bf16_f32 v81, v81, v84
	v_cvt_pk_bf16_f32 v70, v85, v86
	v_cvt_pk_bf16_f32 v71, v87, v88
	v_cvt_pk_bf16_f32 v72, v89, v90
	v_cvt_pk_bf16_f32 v73, v91, v92
	s_nop 1
	v_permlane32_swap_b32_e32 v83, v106
	v_permlane32_swap_b32_e32 v66, v68
	v_permlane32_swap_b32_e32 v67, v69
	v_permlane32_swap_b32_e32 v74, v76
	v_permlane32_swap_b32_e32 v75, v77
	v_permlane32_swap_b32_e32 v78, v80
	v_permlane32_swap_b32_e32 v79, v81
	v_permlane32_swap_b32_e32 v70, v72
	v_permlane32_swap_b32_e32 v71, v73
	s_cmp_lt_i32 s87, s89
	s_cselect_b64 s[72:73], -1, 0
	s_cmp_ge_i32 s87, s89
	s_cbranch_scc1 .LBB0_844
	s_add_i32 s3, s97, 64
	v_mad_i64_i32 v[32:33], s[20:21], s3, v237, v[134:135]
	v_mad_i64_i32 v[84:85], s[20:21], s3, v237, v[136:137]
	global_load_dwordx4 v[96:99], v[32:33], off offset:1024
	global_load_dwordx4 v[100:103], v[84:85], off offset:1280
